# v23 with the redundant second s_waitcnt lgkmcnt(0) deleted at each K-loop stage head (60 sites)
# speedup vs baseline: 1.0049x; 1.0049x over previous
.LBB0_285:
	ds_read_b128 v[154:157], v151
	ds_read_b128 v[158:161], v151 offset:1024
	ds_read_b128 v[164:167], v151 offset:2048
	ds_read_b128 v[168:171], v151 offset:3072
	ds_read_b128 v[172:175], v152
	ds_read_b128 v[176:179], v152 offset:1024
	ds_read_b128 v[180:183], v152 offset:2048
	ds_read_b128 v[184:187], v152 offset:3072
	s_add_u32 s36, s34, 0xfff80080
	s_addc_u32 s37, s35, -1
	s_cmp_eq_u32 s53, 28
	s_cselect_b32 s39, s16, s37
	s_cselect_b32 s38, s17, s36
	s_cselect_b32 s37, s18, s25
	s_cselect_b32 s36, s19, s23
	v_lshl_add_u64 v[146:147], s[34:35], 0, v[138:139]
	s_add_i32 m0, s31, 0xc000
	ds_read_b128 v[188:191], v153
	ds_read_b128 v[192:195], v153 offset:1024
	ds_read_b128 v[196:199], v153 offset:2048
	ds_read_b128 v[200:203], v153 offset:3072
	ds_read_b128 v[204:207], v153 offset:4096
	ds_read_b128 v[208:211], v153 offset:5120
	ds_read_b128 v[212:215], v153 offset:6144
	ds_read_b128 v[216:219], v153 offset:7168
	global_load_lds_dwordx4 v[146:147], off
	v_lshl_add_u64 v[146:147], s[34:35], 0, v[140:141]
	s_add_i32 m0, s31, 0xe000
	s_nop 0
	global_load_lds_dwordx4 v[146:147], off
	s_waitcnt vmcnt(8)
	s_waitcnt lgkmcnt(0)
	v_mfma_f32_16x16x32_bf16 v[126:129], v[154:157], v[188:191], v[126:129]
	v_mfma_f32_16x16x32_bf16 v[122:125], v[164:167], v[188:191], v[122:125]
	v_mfma_f32_16x16x32_bf16 v[110:113], v[154:157], v[196:199], v[110:113]
	v_mfma_f32_16x16x32_bf16 v[106:109], v[164:167], v[196:199], v[106:109]
	s_barrier
	s_setprio 1
	v_mfma_f32_16x16x32_bf16 v[94:97], v[154:157], v[204:207], v[94:97]
	v_mfma_f32_16x16x32_bf16 v[90:93], v[164:167], v[204:207], v[90:93]
	v_mfma_f32_16x16x32_bf16 v[78:81], v[154:157], v[212:215], v[78:81]
	v_mfma_f32_16x16x32_bf16 v[74:77], v[164:167], v[212:215], v[74:77]
	v_mfma_f32_16x16x32_bf16 v[126:129], v[158:161], v[192:195], v[126:129]
	v_mfma_f32_16x16x32_bf16 v[122:125], v[168:171], v[192:195], v[122:125]
	v_mfma_f32_16x16x32_bf16 v[110:113], v[158:161], v[200:203], v[110:113]
	v_mfma_f32_16x16x32_bf16 v[106:109], v[168:171], v[200:203], v[106:109]
	v_mfma_f32_16x16x32_bf16 v[94:97], v[158:161], v[208:211], v[94:97]
	v_mfma_f32_16x16x32_bf16 v[90:93], v[168:171], v[208:211], v[90:93]
	v_mfma_f32_16x16x32_bf16 v[78:81], v[158:161], v[216:219], v[78:81]
	v_mfma_f32_16x16x32_bf16 v[74:77], v[168:171], v[216:219], v[74:77]
	v_mfma_f32_16x16x32_bf16 v[118:121], v[172:175], v[188:191], v[118:121]
	v_mfma_f32_16x16x32_bf16 v[114:117], v[180:183], v[188:191], v[114:117]
	v_mfma_f32_16x16x32_bf16 v[102:105], v[172:175], v[196:199], v[102:105]
	v_mfma_f32_16x16x32_bf16 v[98:101], v[180:183], v[196:199], v[98:101]
	v_mfma_f32_16x16x32_bf16 v[86:89], v[172:175], v[204:207], v[86:89]
	v_mfma_f32_16x16x32_bf16 v[82:85], v[180:183], v[204:207], v[82:85]
	v_mfma_f32_16x16x32_bf16 v[70:73], v[172:175], v[212:215], v[70:73]
	v_mfma_f32_16x16x32_bf16 v[66:69], v[180:183], v[212:215], v[66:69]
	v_mfma_f32_16x16x32_bf16 v[118:121], v[176:179], v[192:195], v[118:121]
	v_mfma_f32_16x16x32_bf16 v[114:117], v[184:187], v[192:195], v[114:117]
	v_mfma_f32_16x16x32_bf16 v[102:105], v[176:179], v[200:203], v[102:105]
	v_mfma_f32_16x16x32_bf16 v[98:101], v[184:187], v[200:203], v[98:101]
	v_mfma_f32_16x16x32_bf16 v[86:89], v[176:179], v[208:211], v[86:89]
	v_mfma_f32_16x16x32_bf16 v[82:85], v[184:187], v[208:211], v[82:85]
	v_mfma_f32_16x16x32_bf16 v[70:73], v[176:179], v[216:219], v[70:73]
	v_mfma_f32_16x16x32_bf16 v[66:69], v[184:187], v[216:219], v[66:69]
	s_setprio 0
	s_barrier
	s_add_i32 s54, s15, s44
	v_lshl_add_u64 v[146:147], s[36:37], 0, v[134:135]
	s_mov_b32 m0, s54
	ds_read_b128 v[188:191], v153 offset:16384
	ds_read_b128 v[192:195], v153 offset:17408
	ds_read_b128 v[196:199], v153 offset:18432
	ds_read_b128 v[200:203], v153 offset:19456
	ds_read_b128 v[204:207], v153 offset:20480
	ds_read_b128 v[208:211], v153 offset:21504
	ds_read_b128 v[212:215], v153 offset:22528
	ds_read_b128 v[216:219], v153 offset:23552
	global_load_lds_dwordx4 v[146:147], off
	s_add_i32 m0, s54, 0x2000
	s_add_u32 s54, s36, 0x80000
	v_lshl_add_u64 v[220:221], s[36:37], 0, v[130:131]
	s_addc_u32 s55, s37, 0
	s_add_i32 s56, s51, s44
	global_load_lds_dwordx4 v[220:221], off
	v_lshl_add_u64 v[222:223], s[54:55], 0, v[134:135]
	s_mov_b32 m0, s56
	v_lshl_add_u64 v[224:225], s[38:39], 0, v[132:133]
	global_load_lds_dwordx4 v[222:223], off
	v_lshl_add_u64 v[222:223], s[54:55], 0, v[130:131]
	s_add_i32 m0, s56, 0x2000
	s_nop 0
	global_load_lds_dwordx4 v[222:223], off
	v_lshl_add_u64 v[222:223], s[38:39], 0, v[136:137]
	s_mov_b32 m0, s31
	s_nop 0
	global_load_lds_dwordx4 v[222:223], off
	s_mov_b32 m0, s47
	s_nop 0
	global_load_lds_dwordx4 v[224:225], off
	s_waitcnt vmcnt(8)
	s_waitcnt lgkmcnt(0)
	v_mfma_f32_16x16x32_bf16 v[62:65], v[154:157], v[188:191], v[62:65]
	v_mfma_f32_16x16x32_bf16 v[58:61], v[164:167], v[188:191], v[58:61]
	v_mfma_f32_16x16x32_bf16 v[46:49], v[154:157], v[196:199], v[46:49]
	v_mfma_f32_16x16x32_bf16 v[42:45], v[164:167], v[196:199], v[42:45]
	s_barrier
	s_setprio 1
	v_mfma_f32_16x16x32_bf16 v[30:33], v[154:157], v[204:207], v[30:33]
	v_mfma_f32_16x16x32_bf16 v[26:29], v[164:167], v[204:207], v[26:29]
	v_mfma_f32_16x16x32_bf16 v[14:17], v[154:157], v[212:215], v[14:17]
	v_mfma_f32_16x16x32_bf16 v[10:13], v[164:167], v[212:215], v[10:13]
	v_mfma_f32_16x16x32_bf16 v[62:65], v[158:161], v[192:195], v[62:65]
	v_mfma_f32_16x16x32_bf16 v[58:61], v[168:171], v[192:195], v[58:61]
	v_mfma_f32_16x16x32_bf16 v[46:49], v[158:161], v[200:203], v[46:49]
	v_mfma_f32_16x16x32_bf16 v[42:45], v[168:171], v[200:203], v[42:45]
	v_mfma_f32_16x16x32_bf16 v[30:33], v[158:161], v[208:211], v[30:33]
	v_mfma_f32_16x16x32_bf16 v[26:29], v[168:171], v[208:211], v[26:29]
	v_mfma_f32_16x16x32_bf16 v[14:17], v[158:161], v[216:219], v[14:17]
	v_mfma_f32_16x16x32_bf16 v[10:13], v[168:171], v[216:219], v[10:13]
	v_mfma_f32_16x16x32_bf16 v[54:57], v[172:175], v[188:191], v[54:57]
	v_mfma_f32_16x16x32_bf16 v[50:53], v[180:183], v[188:191], v[50:53]
	v_mfma_f32_16x16x32_bf16 v[38:41], v[172:175], v[196:199], v[38:41]
	v_mfma_f32_16x16x32_bf16 v[34:37], v[180:183], v[196:199], v[34:37]
	v_mfma_f32_16x16x32_bf16 v[22:25], v[172:175], v[204:207], v[22:25]
	v_mfma_f32_16x16x32_bf16 v[18:21], v[180:183], v[204:207], v[18:21]
	v_mfma_f32_16x16x32_bf16 v[6:9], v[172:175], v[212:215], v[6:9]
	v_mfma_f32_16x16x32_bf16 v[2:5], v[180:183], v[212:215], v[2:5]
	v_mfma_f32_16x16x32_bf16 v[54:57], v[176:179], v[192:195], v[54:57]
	v_mfma_f32_16x16x32_bf16 v[50:53], v[184:187], v[192:195], v[50:53]
	v_mfma_f32_16x16x32_bf16 v[38:41], v[176:179], v[200:203], v[38:41]
	v_mfma_f32_16x16x32_bf16 v[34:37], v[184:187], v[200:203], v[34:37]
	v_mfma_f32_16x16x32_bf16 v[22:25], v[176:179], v[208:211], v[22:25]
	v_mfma_f32_16x16x32_bf16 v[18:21], v[184:187], v[208:211], v[18:21]
	v_mfma_f32_16x16x32_bf16 v[6:9], v[176:179], v[216:219], v[6:9]
	v_mfma_f32_16x16x32_bf16 v[2:5], v[184:187], v[216:219], v[2:5]
	s_setprio 0
	s_barrier
	s_add_i32 s54, 0, 0x18000
	v_add_u32_e32 v163, s54, v149
	s_add_i32 s55, 0, 0x1c000
	ds_read_b128 v[154:157], v163
	ds_read_b128 v[158:161], v163 offset:1024
	ds_read_b128 v[164:167], v163 offset:2048
	ds_read_b128 v[168:171], v163 offset:3072
	v_add_u32_e32 v163, s55, v149
	ds_read_b128 v[172:175], v163
	ds_read_b128 v[176:179], v163 offset:1024
	ds_read_b128 v[180:183], v163 offset:2048
	ds_read_b128 v[184:187], v163 offset:3072
	s_add_u32 s38, s38, 0x80000
	s_addc_u32 s39, s39, 0
	s_mov_b32 m0, s48
	v_lshl_add_u64 v[226:227], s[38:39], 0, v[136:137]
	ds_read_b128 v[188:191], v153 offset:32768
	ds_read_b128 v[192:195], v153 offset:33792
	ds_read_b128 v[196:199], v153 offset:34816
	ds_read_b128 v[200:203], v153 offset:35840
	ds_read_b128 v[204:207], v153 offset:36864
	ds_read_b128 v[208:211], v153 offset:37888
	ds_read_b128 v[212:215], v153 offset:38912
	ds_read_b128 v[216:219], v153 offset:39936
	global_load_lds_dwordx4 v[226:227], off
	v_lshl_add_u64 v[226:227], s[38:39], 0, v[132:133]
	s_mov_b32 m0, s49
	s_nop 0
	global_load_lds_dwordx4 v[226:227], off
	s_waitcnt vmcnt(8)
	s_waitcnt lgkmcnt(0)
	v_mfma_f32_16x16x32_bf16 v[126:129], v[154:157], v[188:191], v[126:129]
	v_mfma_f32_16x16x32_bf16 v[122:125], v[164:167], v[188:191], v[122:125]
	v_mfma_f32_16x16x32_bf16 v[110:113], v[154:157], v[196:199], v[110:113]
	v_mfma_f32_16x16x32_bf16 v[106:109], v[164:167], v[196:199], v[106:109]
	s_barrier
	s_setprio 1
	v_mfma_f32_16x16x32_bf16 v[94:97], v[154:157], v[204:207], v[94:97]
	v_mfma_f32_16x16x32_bf16 v[90:93], v[164:167], v[204:207], v[90:93]
	v_mfma_f32_16x16x32_bf16 v[78:81], v[154:157], v[212:215], v[78:81]
	v_mfma_f32_16x16x32_bf16 v[74:77], v[164:167], v[212:215], v[74:77]
	v_mfma_f32_16x16x32_bf16 v[126:129], v[158:161], v[192:195], v[126:129]
	v_mfma_f32_16x16x32_bf16 v[122:125], v[168:171], v[192:195], v[122:125]
	v_mfma_f32_16x16x32_bf16 v[110:113], v[158:161], v[200:203], v[110:113]
	v_mfma_f32_16x16x32_bf16 v[106:109], v[168:171], v[200:203], v[106:109]
	v_mfma_f32_16x16x32_bf16 v[94:97], v[158:161], v[208:211], v[94:97]
	v_mfma_f32_16x16x32_bf16 v[90:93], v[168:171], v[208:211], v[90:93]
	v_mfma_f32_16x16x32_bf16 v[78:81], v[158:161], v[216:219], v[78:81]
	v_mfma_f32_16x16x32_bf16 v[74:77], v[168:171], v[216:219], v[74:77]
	v_mfma_f32_16x16x32_bf16 v[118:121], v[172:175], v[188:191], v[118:121]
	v_mfma_f32_16x16x32_bf16 v[114:117], v[180:183], v[188:191], v[114:117]
	v_mfma_f32_16x16x32_bf16 v[102:105], v[172:175], v[196:199], v[102:105]
	v_mfma_f32_16x16x32_bf16 v[98:101], v[180:183], v[196:199], v[98:101]
	v_mfma_f32_16x16x32_bf16 v[86:89], v[172:175], v[204:207], v[86:89]
	v_mfma_f32_16x16x32_bf16 v[82:85], v[180:183], v[204:207], v[82:85]
	v_mfma_f32_16x16x32_bf16 v[70:73], v[172:175], v[212:215], v[70:73]
	v_mfma_f32_16x16x32_bf16 v[66:69], v[180:183], v[212:215], v[66:69]
	v_mfma_f32_16x16x32_bf16 v[118:121], v[176:179], v[192:195], v[118:121]
	v_mfma_f32_16x16x32_bf16 v[114:117], v[184:187], v[192:195], v[114:117]
	v_mfma_f32_16x16x32_bf16 v[102:105], v[176:179], v[200:203], v[102:105]
	v_mfma_f32_16x16x32_bf16 v[98:101], v[184:187], v[200:203], v[98:101]
	v_mfma_f32_16x16x32_bf16 v[86:89], v[176:179], v[208:211], v[86:89]
	v_mfma_f32_16x16x32_bf16 v[82:85], v[184:187], v[208:211], v[82:85]
	v_mfma_f32_16x16x32_bf16 v[70:73], v[176:179], v[216:219], v[70:73]
	v_mfma_f32_16x16x32_bf16 v[66:69], v[184:187], v[216:219], v[66:69]
	s_setprio 0
	s_barrier
	s_add_i32 s38, s54, s44
	v_lshl_add_u64 v[146:147], v[146:147], 0, s[10:11]
	s_mov_b32 m0, s38
	ds_read_b128 v[188:191], v153 offset:49152
	ds_read_b128 v[192:195], v153 offset:50176
	ds_read_b128 v[196:199], v153 offset:51200
	ds_read_b128 v[200:203], v153 offset:52224
	ds_read_b128 v[204:207], v153 offset:53248
	ds_read_b128 v[208:211], v153 offset:54272
	ds_read_b128 v[212:215], v153 offset:55296
	ds_read_b128 v[216:219], v153 offset:56320
	global_load_lds_dwordx4 v[146:147], off
	s_add_i32 m0, s38, 0x2000
	s_add_u32 s36, s36, 0x80080
	v_lshl_add_u64 v[146:147], v[220:221], 0, s[10:11]
	s_addc_u32 s37, s37, 0
	s_add_i32 s38, s55, s44
	global_load_lds_dwordx4 v[146:147], off
	v_lshl_add_u64 v[146:147], s[36:37], 0, v[134:135]
	s_mov_b32 m0, s38
	s_nop 0
	global_load_lds_dwordx4 v[146:147], off
	v_lshl_add_u64 v[146:147], s[36:37], 0, v[130:131]
	s_add_i32 m0, s38, 0x2000
	s_nop 0
	global_load_lds_dwordx4 v[146:147], off
	v_lshl_add_u64 v[146:147], v[222:223], 0, s[10:11]
	s_mov_b32 m0, s20
	s_nop 0
	global_load_lds_dwordx4 v[146:147], off
	v_lshl_add_u64 v[146:147], v[224:225], 0, s[10:11]
	s_mov_b32 m0, s21
	s_nop 0
	global_load_lds_dwordx4 v[146:147], off
	s_waitcnt vmcnt(8)
	s_waitcnt lgkmcnt(0)
	v_mfma_f32_16x16x32_bf16 v[62:65], v[154:157], v[188:191], v[62:65]
	v_mfma_f32_16x16x32_bf16 v[58:61], v[164:167], v[188:191], v[58:61]
	v_mfma_f32_16x16x32_bf16 v[46:49], v[154:157], v[196:199], v[46:49]
	v_mfma_f32_16x16x32_bf16 v[42:45], v[164:167], v[196:199], v[42:45]
	s_barrier
	s_setprio 1
	v_mfma_f32_16x16x32_bf16 v[30:33], v[154:157], v[204:207], v[30:33]
	v_mfma_f32_16x16x32_bf16 v[26:29], v[164:167], v[204:207], v[26:29]
	v_mfma_f32_16x16x32_bf16 v[14:17], v[154:157], v[212:215], v[14:17]
	v_mfma_f32_16x16x32_bf16 v[10:13], v[164:167], v[212:215], v[10:13]
	v_mfma_f32_16x16x32_bf16 v[62:65], v[158:161], v[192:195], v[62:65]
	v_mfma_f32_16x16x32_bf16 v[58:61], v[168:171], v[192:195], v[58:61]
	v_mfma_f32_16x16x32_bf16 v[46:49], v[158:161], v[200:203], v[46:49]
	v_mfma_f32_16x16x32_bf16 v[42:45], v[168:171], v[200:203], v[42:45]
	v_mfma_f32_16x16x32_bf16 v[30:33], v[158:161], v[208:211], v[30:33]
	v_mfma_f32_16x16x32_bf16 v[26:29], v[168:171], v[208:211], v[26:29]
	v_mfma_f32_16x16x32_bf16 v[14:17], v[158:161], v[216:219], v[14:17]
	v_mfma_f32_16x16x32_bf16 v[10:13], v[168:171], v[216:219], v[10:13]
	v_mfma_f32_16x16x32_bf16 v[54:57], v[172:175], v[188:191], v[54:57]
	v_mfma_f32_16x16x32_bf16 v[50:53], v[180:183], v[188:191], v[50:53]
	v_mfma_f32_16x16x32_bf16 v[38:41], v[172:175], v[196:199], v[38:41]
	v_mfma_f32_16x16x32_bf16 v[34:37], v[180:183], v[196:199], v[34:37]
	v_mfma_f32_16x16x32_bf16 v[22:25], v[172:175], v[204:207], v[22:25]
	v_mfma_f32_16x16x32_bf16 v[18:21], v[180:183], v[204:207], v[18:21]
	v_mfma_f32_16x16x32_bf16 v[6:9], v[172:175], v[212:215], v[6:9]
	v_mfma_f32_16x16x32_bf16 v[2:5], v[180:183], v[212:215], v[2:5]
	v_mfma_f32_16x16x32_bf16 v[54:57], v[176:179], v[192:195], v[54:57]
	v_mfma_f32_16x16x32_bf16 v[50:53], v[184:187], v[192:195], v[50:53]
	v_mfma_f32_16x16x32_bf16 v[38:41], v[176:179], v[200:203], v[38:41]
	v_mfma_f32_16x16x32_bf16 v[34:37], v[184:187], v[200:203], v[34:37]
	v_mfma_f32_16x16x32_bf16 v[22:25], v[176:179], v[208:211], v[22:25]
	v_mfma_f32_16x16x32_bf16 v[18:21], v[184:187], v[208:211], v[18:21]
	v_mfma_f32_16x16x32_bf16 v[6:9], v[176:179], v[216:219], v[6:9]
	v_mfma_f32_16x16x32_bf16 v[2:5], v[184:187], v[216:219], v[2:5]
	s_setprio 0
	s_barrier
	s_add_i32 s53, s53, 2
	s_add_u32 s34, s34, 0x100
	s_addc_u32 s35, s35, 0
	s_add_u32 s23, s23, 0x100
	s_addc_u32 s25, s25, 0
	s_cmp_gt_u32 s53, 29
	s_cbranch_scc0 .LBB0_285
	s_and_b64 vcc, exec, s[12:13]
	s_cbranch_vccz .LBB0_288
	s_barrier

.LBB0_356:
	ds_read_b128 v[134:137], v213
	ds_read_b128 v[138:141], v213 offset:1024
	ds_read_b128 v[142:145], v213 offset:2048
	ds_read_b128 v[178:181], v213 offset:3072
	ds_read_b128 v[182:185], v214
	ds_read_b128 v[186:189], v214 offset:1024
	ds_read_b128 v[190:193], v214 offset:2048
	ds_read_b128 v[194:197], v214 offset:3072
	s_add_u32 s36, s34, 0x100
	s_addc_u32 s37, s35, 0
	s_add_u32 s16, s3, s34
	s_addc_u32 s17, s14, s35
	s_cmpk_eq_i32 s15, 0x54
	s_cselect_b32 s41, s27, s17
	s_cselect_b32 s17, 0, s36
	s_cselect_b32 s40, s26, s16
	s_cselect_b32 s16, 0, s37
	s_add_u32 s38, s8, s17
	s_addc_u32 s39, s9, s16
	s_mov_b32 m0, s63
	v_lshl_add_u64 v[244:245], v[130:131], 0, s[34:35]
	ds_read_b128 v[198:201], v215
	ds_read_b128 v[202:205], v215 offset:1024
	ds_read_b128 v[206:209], v215 offset:2048
	ds_read_b128 v[224:227], v215 offset:3072
	ds_read_b128 v[228:231], v215 offset:4096
	ds_read_b128 v[232:235], v215 offset:5120
	ds_read_b128 v[236:239], v215 offset:6144
	ds_read_b128 v[240:243], v215 offset:7168
	global_load_lds_dwordx4 v[244:245], off
	v_lshl_add_u64 v[244:245], v[132:133], 0, s[34:35]
	s_mov_b32 m0, s64
	s_nop 0
	global_load_lds_dwordx4 v[244:245], off
	s_waitcnt vmcnt(8)
	s_waitcnt lgkmcnt(0)
	v_mfma_f32_16x16x32_bf16 v[86:89], v[134:137], v[198:201], v[86:89]
	v_mfma_f32_16x16x32_bf16 v[82:85], v[142:145], v[198:201], v[82:85]
	v_mfma_f32_16x16x32_bf16 v[110:113], v[134:137], v[206:209], v[110:113]
	v_mfma_f32_16x16x32_bf16 v[106:109], v[142:145], v[206:209], v[106:109]
	s_barrier
	s_setprio 1
	v_mfma_f32_16x16x32_bf16 v[118:121], v[134:137], v[228:231], v[118:121]
	v_mfma_f32_16x16x32_bf16 v[114:117], v[142:145], v[228:231], v[114:117]
	v_mfma_f32_16x16x32_bf16 v[126:129], v[134:137], v[236:239], v[126:129]
	v_mfma_f32_16x16x32_bf16 v[122:125], v[142:145], v[236:239], v[122:125]
	v_mfma_f32_16x16x32_bf16 v[86:89], v[138:141], v[202:205], v[86:89]
	v_mfma_f32_16x16x32_bf16 v[82:85], v[178:181], v[202:205], v[82:85]
	v_mfma_f32_16x16x32_bf16 v[110:113], v[138:141], v[224:227], v[110:113]
	v_mfma_f32_16x16x32_bf16 v[106:109], v[178:181], v[224:227], v[106:109]
	v_mfma_f32_16x16x32_bf16 v[118:121], v[138:141], v[232:235], v[118:121]
	v_mfma_f32_16x16x32_bf16 v[114:117], v[178:181], v[232:235], v[114:117]
	v_mfma_f32_16x16x32_bf16 v[126:129], v[138:141], v[240:243], v[126:129]
	v_mfma_f32_16x16x32_bf16 v[122:125], v[178:181], v[240:243], v[122:125]
	v_mfma_f32_16x16x32_bf16 v[26:29], v[182:185], v[198:201], v[26:29]
	v_mfma_f32_16x16x32_bf16 v[30:33], v[190:193], v[198:201], v[30:33]
	v_mfma_f32_16x16x32_bf16 v[42:45], v[182:185], v[206:209], v[42:45]
	v_mfma_f32_16x16x32_bf16 v[50:53], v[190:193], v[206:209], v[50:53]
	v_mfma_f32_16x16x32_bf16 v[66:69], v[182:185], v[228:231], v[66:69]
	v_mfma_f32_16x16x32_bf16 v[70:73], v[190:193], v[228:231], v[70:73]
	v_mfma_f32_16x16x32_bf16 v[90:93], v[182:185], v[236:239], v[90:93]
	v_mfma_f32_16x16x32_bf16 v[94:97], v[190:193], v[236:239], v[94:97]
	v_mfma_f32_16x16x32_bf16 v[26:29], v[186:189], v[202:205], v[26:29]
	v_mfma_f32_16x16x32_bf16 v[30:33], v[194:197], v[202:205], v[30:33]
	v_mfma_f32_16x16x32_bf16 v[42:45], v[186:189], v[224:227], v[42:45]
	v_mfma_f32_16x16x32_bf16 v[50:53], v[194:197], v[224:227], v[50:53]
	v_mfma_f32_16x16x32_bf16 v[66:69], v[186:189], v[232:235], v[66:69]
	v_mfma_f32_16x16x32_bf16 v[70:73], v[194:197], v[232:235], v[70:73]
	v_mfma_f32_16x16x32_bf16 v[90:93], v[186:189], v[240:243], v[90:93]
	v_mfma_f32_16x16x32_bf16 v[94:97], v[194:197], v[240:243], v[94:97]
	s_setprio 0
	s_barrier
	s_mov_b32 m0, s65
	v_lshl_add_u64 v[244:245], s[38:39], 0, v[150:151]
	s_add_u32 s16, s38, 0x160000
	ds_read_b128 v[198:201], v215 offset:16384
	ds_read_b128 v[202:205], v215 offset:17408
	ds_read_b128 v[206:209], v215 offset:18432
	ds_read_b128 v[224:227], v215 offset:19456
	ds_read_b128 v[228:231], v215 offset:20480
	ds_read_b128 v[232:235], v215 offset:21504
	ds_read_b128 v[236:239], v215 offset:22528
	ds_read_b128 v[240:243], v215 offset:23552
	global_load_lds_dwordx4 v[244:245], off
	v_lshl_add_u64 v[246:247], s[38:39], 0, v[146:147]
	s_mov_b32 m0, s66
	s_addc_u32 s17, s39, 0
	global_load_lds_dwordx4 v[246:247], off
	v_lshl_add_u64 v[248:249], s[16:17], 0, v[150:151]
	s_mov_b32 m0, s67
	v_lshl_add_u64 v[250:251], s[40:41], 0, v[148:149]
	global_load_lds_dwordx4 v[248:249], off
	v_lshl_add_u64 v[248:249], s[16:17], 0, v[146:147]
	s_mov_b32 m0, s68
	s_nop 0
	global_load_lds_dwordx4 v[248:249], off
	v_lshl_add_u64 v[248:249], s[40:41], 0, v[152:153]
	s_mov_b32 m0, s51
	s_nop 0
	global_load_lds_dwordx4 v[248:249], off
	s_mov_b32 m0, s52
	s_nop 0
	global_load_lds_dwordx4 v[250:251], off
	s_waitcnt vmcnt(8)
	s_waitcnt lgkmcnt(0)
	v_mfma_f32_16x16x32_bf16 v[102:105], v[134:137], v[198:201], v[102:105]
	v_mfma_f32_16x16x32_bf16 v[98:101], v[142:145], v[198:201], v[98:101]
	v_mfma_f32_16x16x32_bf16 v[62:65], v[134:137], v[206:209], v[62:65]
	v_mfma_f32_16x16x32_bf16 v[58:61], v[142:145], v[206:209], v[58:61]
	s_barrier
	s_setprio 1
	v_mfma_f32_16x16x32_bf16 v[38:41], v[134:137], v[228:231], v[38:41]
	v_mfma_f32_16x16x32_bf16 v[34:37], v[142:145], v[228:231], v[34:37]
	v_mfma_f32_16x16x32_bf16 v[14:17], v[134:137], v[236:239], v[14:17]
	v_mfma_f32_16x16x32_bf16 v[10:13], v[142:145], v[236:239], v[10:13]
	v_mfma_f32_16x16x32_bf16 v[102:105], v[138:141], v[202:205], v[102:105]
	v_mfma_f32_16x16x32_bf16 v[98:101], v[178:181], v[202:205], v[98:101]
	v_mfma_f32_16x16x32_bf16 v[62:65], v[138:141], v[224:227], v[62:65]
	v_mfma_f32_16x16x32_bf16 v[58:61], v[178:181], v[224:227], v[58:61]
	v_mfma_f32_16x16x32_bf16 v[38:41], v[138:141], v[232:235], v[38:41]
	v_mfma_f32_16x16x32_bf16 v[34:37], v[178:181], v[232:235], v[34:37]
	v_mfma_f32_16x16x32_bf16 v[14:17], v[138:141], v[240:243], v[14:17]
	v_mfma_f32_16x16x32_bf16 v[10:13], v[178:181], v[240:243], v[10:13]
	v_mfma_f32_16x16x32_bf16 v[78:81], v[182:185], v[198:201], v[78:81]
	v_mfma_f32_16x16x32_bf16 v[74:77], v[190:193], v[198:201], v[74:77]
	v_mfma_f32_16x16x32_bf16 v[54:57], v[182:185], v[206:209], v[54:57]
	v_mfma_f32_16x16x32_bf16 v[46:49], v[190:193], v[206:209], v[46:49]
	v_mfma_f32_16x16x32_bf16 v[22:25], v[182:185], v[228:231], v[22:25]
	v_mfma_f32_16x16x32_bf16 v[18:21], v[190:193], v[228:231], v[18:21]
	v_mfma_f32_16x16x32_bf16 v[6:9], v[182:185], v[236:239], v[6:9]
	v_mfma_f32_16x16x32_bf16 v[2:5], v[190:193], v[236:239], v[2:5]
	v_mfma_f32_16x16x32_bf16 v[78:81], v[186:189], v[202:205], v[78:81]
	v_mfma_f32_16x16x32_bf16 v[74:77], v[194:197], v[202:205], v[74:77]
	v_mfma_f32_16x16x32_bf16 v[54:57], v[186:189], v[224:227], v[54:57]
	v_mfma_f32_16x16x32_bf16 v[46:49], v[194:197], v[224:227], v[46:49]
	v_mfma_f32_16x16x32_bf16 v[22:25], v[186:189], v[232:235], v[22:25]
	v_mfma_f32_16x16x32_bf16 v[18:21], v[194:197], v[232:235], v[18:21]
	v_mfma_f32_16x16x32_bf16 v[6:9], v[186:189], v[240:243], v[6:9]
	v_mfma_f32_16x16x32_bf16 v[2:5], v[194:197], v[240:243], v[2:5]
	s_setprio 0
	s_barrier
	ds_read_b128 v[134:137], v219
	ds_read_b128 v[138:141], v219 offset:1024
	ds_read_b128 v[142:145], v219 offset:2048
	ds_read_b128 v[178:181], v219 offset:3072
	ds_read_b128 v[182:185], v220
	ds_read_b128 v[186:189], v220 offset:1024
	ds_read_b128 v[190:193], v220 offset:2048
	ds_read_b128 v[194:197], v220 offset:3072
	s_add_u32 s16, s40, 0x160000
	s_addc_u32 s17, s41, 0
	s_mov_b32 m0, s53
	v_lshl_add_u64 v[252:253], s[16:17], 0, v[152:153]
	ds_read_b128 v[198:201], v215 offset:32768
	ds_read_b128 v[202:205], v215 offset:33792
	ds_read_b128 v[206:209], v215 offset:34816
	ds_read_b128 v[224:227], v215 offset:35840
	ds_read_b128 v[228:231], v215 offset:36864
	ds_read_b128 v[232:235], v215 offset:37888
	ds_read_b128 v[236:239], v215 offset:38912
	ds_read_b128 v[240:243], v215 offset:39936
	global_load_lds_dwordx4 v[252:253], off
	v_lshl_add_u64 v[252:253], s[16:17], 0, v[148:149]
	s_mov_b32 m0, s54
	s_nop 0
	global_load_lds_dwordx4 v[252:253], off
	s_waitcnt vmcnt(8)
	s_waitcnt lgkmcnt(0)
	v_mfma_f32_16x16x32_bf16 v[86:89], v[134:137], v[198:201], v[86:89]
	v_mfma_f32_16x16x32_bf16 v[82:85], v[142:145], v[198:201], v[82:85]
	v_mfma_f32_16x16x32_bf16 v[110:113], v[134:137], v[206:209], v[110:113]
	v_mfma_f32_16x16x32_bf16 v[106:109], v[142:145], v[206:209], v[106:109]
	s_barrier
	s_setprio 1
	v_mfma_f32_16x16x32_bf16 v[118:121], v[134:137], v[228:231], v[118:121]
	v_mfma_f32_16x16x32_bf16 v[114:117], v[142:145], v[228:231], v[114:117]
	v_mfma_f32_16x16x32_bf16 v[126:129], v[134:137], v[236:239], v[126:129]
	v_mfma_f32_16x16x32_bf16 v[122:125], v[142:145], v[236:239], v[122:125]
	v_mfma_f32_16x16x32_bf16 v[86:89], v[138:141], v[202:205], v[86:89]
	v_mfma_f32_16x16x32_bf16 v[82:85], v[178:181], v[202:205], v[82:85]
	v_mfma_f32_16x16x32_bf16 v[110:113], v[138:141], v[224:227], v[110:113]
	v_mfma_f32_16x16x32_bf16 v[106:109], v[178:181], v[224:227], v[106:109]
	v_mfma_f32_16x16x32_bf16 v[118:121], v[138:141], v[232:235], v[118:121]
	v_mfma_f32_16x16x32_bf16 v[114:117], v[178:181], v[232:235], v[114:117]
	v_mfma_f32_16x16x32_bf16 v[126:129], v[138:141], v[240:243], v[126:129]
	v_mfma_f32_16x16x32_bf16 v[122:125], v[178:181], v[240:243], v[122:125]
	v_mfma_f32_16x16x32_bf16 v[26:29], v[182:185], v[198:201], v[26:29]
	v_mfma_f32_16x16x32_bf16 v[30:33], v[190:193], v[198:201], v[30:33]
	v_mfma_f32_16x16x32_bf16 v[42:45], v[182:185], v[206:209], v[42:45]
	v_mfma_f32_16x16x32_bf16 v[50:53], v[190:193], v[206:209], v[50:53]
	v_mfma_f32_16x16x32_bf16 v[66:69], v[182:185], v[228:231], v[66:69]
	v_mfma_f32_16x16x32_bf16 v[70:73], v[190:193], v[228:231], v[70:73]
	v_mfma_f32_16x16x32_bf16 v[90:93], v[182:185], v[236:239], v[90:93]
	v_mfma_f32_16x16x32_bf16 v[94:97], v[190:193], v[236:239], v[94:97]
	v_mfma_f32_16x16x32_bf16 v[26:29], v[186:189], v[202:205], v[26:29]
	v_mfma_f32_16x16x32_bf16 v[30:33], v[194:197], v[202:205], v[30:33]
	v_mfma_f32_16x16x32_bf16 v[42:45], v[186:189], v[224:227], v[42:45]
	v_mfma_f32_16x16x32_bf16 v[50:53], v[194:197], v[224:227], v[50:53]
	v_mfma_f32_16x16x32_bf16 v[66:69], v[186:189], v[232:235], v[66:69]
	v_mfma_f32_16x16x32_bf16 v[70:73], v[194:197], v[232:235], v[70:73]
	v_mfma_f32_16x16x32_bf16 v[90:93], v[186:189], v[240:243], v[90:93]
	v_mfma_f32_16x16x32_bf16 v[94:97], v[194:197], v[240:243], v[94:97]
	s_setprio 0
	s_barrier
	s_mov_b32 m0, s69
	v_lshl_add_u64 v[244:245], v[244:245], 0, s[22:23]
	s_add_u32 s16, s38, 0x160080
	ds_read_b128 v[198:201], v215 offset:49152
	ds_read_b128 v[202:205], v215 offset:50176
	ds_read_b128 v[206:209], v215 offset:51200
	ds_read_b128 v[224:227], v215 offset:52224
	ds_read_b128 v[228:231], v215 offset:53248
	ds_read_b128 v[232:235], v215 offset:54272
	ds_read_b128 v[236:239], v215 offset:55296
	ds_read_b128 v[240:243], v215 offset:56320
	global_load_lds_dwordx4 v[244:245], off
	v_lshl_add_u64 v[244:245], v[246:247], 0, s[22:23]
	s_mov_b32 m0, s73
	s_addc_u32 s17, s39, 0
	global_load_lds_dwordx4 v[244:245], off
	v_lshl_add_u64 v[244:245], s[16:17], 0, v[150:151]
	s_mov_b32 m0, s74
	s_nop 0
	global_load_lds_dwordx4 v[244:245], off
	v_lshl_add_u64 v[244:245], s[16:17], 0, v[146:147]
	s_mov_b32 m0, s75
	s_nop 0
	global_load_lds_dwordx4 v[244:245], off
	v_lshl_add_u64 v[244:245], v[248:249], 0, s[22:23]
	s_mov_b32 m0, s60
	s_nop 0
	global_load_lds_dwordx4 v[244:245], off
	v_lshl_add_u64 v[244:245], v[250:251], 0, s[22:23]
	s_mov_b32 m0, s61
	s_nop 0
	global_load_lds_dwordx4 v[244:245], off
	s_waitcnt vmcnt(8)
	s_waitcnt lgkmcnt(0)
	v_mfma_f32_16x16x32_bf16 v[102:105], v[134:137], v[198:201], v[102:105]
	v_mfma_f32_16x16x32_bf16 v[98:101], v[142:145], v[198:201], v[98:101]
	v_mfma_f32_16x16x32_bf16 v[62:65], v[134:137], v[206:209], v[62:65]
	v_mfma_f32_16x16x32_bf16 v[58:61], v[142:145], v[206:209], v[58:61]
	s_barrier
	s_setprio 1
	v_mfma_f32_16x16x32_bf16 v[38:41], v[134:137], v[228:231], v[38:41]
	v_mfma_f32_16x16x32_bf16 v[34:37], v[142:145], v[228:231], v[34:37]
	v_mfma_f32_16x16x32_bf16 v[14:17], v[134:137], v[236:239], v[14:17]
	v_mfma_f32_16x16x32_bf16 v[10:13], v[142:145], v[236:239], v[10:13]
	v_mfma_f32_16x16x32_bf16 v[102:105], v[138:141], v[202:205], v[102:105]
	v_mfma_f32_16x16x32_bf16 v[98:101], v[178:181], v[202:205], v[98:101]
	v_mfma_f32_16x16x32_bf16 v[62:65], v[138:141], v[224:227], v[62:65]
	v_mfma_f32_16x16x32_bf16 v[58:61], v[178:181], v[224:227], v[58:61]
	v_mfma_f32_16x16x32_bf16 v[38:41], v[138:141], v[232:235], v[38:41]
	v_mfma_f32_16x16x32_bf16 v[34:37], v[178:181], v[232:235], v[34:37]
	v_mfma_f32_16x16x32_bf16 v[14:17], v[138:141], v[240:243], v[14:17]
	v_mfma_f32_16x16x32_bf16 v[10:13], v[178:181], v[240:243], v[10:13]
	v_mfma_f32_16x16x32_bf16 v[78:81], v[182:185], v[198:201], v[78:81]
	v_mfma_f32_16x16x32_bf16 v[74:77], v[190:193], v[198:201], v[74:77]
	v_mfma_f32_16x16x32_bf16 v[54:57], v[182:185], v[206:209], v[54:57]
	v_mfma_f32_16x16x32_bf16 v[46:49], v[190:193], v[206:209], v[46:49]
	v_mfma_f32_16x16x32_bf16 v[22:25], v[182:185], v[228:231], v[22:25]
	v_mfma_f32_16x16x32_bf16 v[18:21], v[190:193], v[228:231], v[18:21]
	v_mfma_f32_16x16x32_bf16 v[6:9], v[182:185], v[236:239], v[6:9]
	v_mfma_f32_16x16x32_bf16 v[2:5], v[190:193], v[236:239], v[2:5]
	v_mfma_f32_16x16x32_bf16 v[78:81], v[186:189], v[202:205], v[78:81]
	v_mfma_f32_16x16x32_bf16 v[74:77], v[194:197], v[202:205], v[74:77]
	v_mfma_f32_16x16x32_bf16 v[54:57], v[186:189], v[224:227], v[54:57]
	v_mfma_f32_16x16x32_bf16 v[46:49], v[194:197], v[224:227], v[46:49]
	v_mfma_f32_16x16x32_bf16 v[22:25], v[186:189], v[232:235], v[22:25]
	v_mfma_f32_16x16x32_bf16 v[18:21], v[194:197], v[232:235], v[18:21]
	v_mfma_f32_16x16x32_bf16 v[6:9], v[186:189], v[240:243], v[6:9]
	v_mfma_f32_16x16x32_bf16 v[2:5], v[194:197], v[240:243], v[2:5]
	s_setprio 0
	s_barrier
	s_add_i32 s15, s15, 2
	s_cmpk_gt_u32 s15, 0x55
	s_mov_b64 s[34:35], s[36:37]
	s_cbranch_scc0 .LBB0_356
	s_and_b64 vcc, exec, s[24:25]
	s_cbranch_vccz .LBB0_359
	s_barrier

.LBB0_466:
	ds_read_b128 v[130:133], v170
	ds_read_b128 v[134:137], v170 offset:1024
	ds_read_b128 v[164:167], v170 offset:2048
	ds_read_b128 v[174:177], v170 offset:3072
	ds_read_b128 v[178:181], v171
	ds_read_b128 v[182:185], v171 offset:1024
	ds_read_b128 v[186:189], v171 offset:2048
	ds_read_b128 v[190:193], v171 offset:3072
	s_add_u32 s19, s42, 0xfff80080
	s_addc_u32 s20, s43, -1
	s_cmp_eq_u32 s18, 28
	s_cselect_b32 s47, s3, s20
	s_cselect_b32 s46, s7, s19
	s_cselect_b32 s45, s14, s17
	s_cselect_b32 s44, s15, s16
	v_lshl_add_u64 v[168:169], s[42:43], 0, v[154:155]
	s_add_i32 m0, s41, 0xc000
	ds_read_b128 v[194:197], v172
	ds_read_b128 v[198:201], v172 offset:1024
	ds_read_b128 v[202:205], v172 offset:2048
	ds_read_b128 v[206:209], v172 offset:3072
	ds_read_b128 v[210:213], v172 offset:4096
	ds_read_b128 v[214:217], v172 offset:5120
	ds_read_b128 v[218:221], v172 offset:6144
	ds_read_b128 v[222:225], v172 offset:7168
	global_load_lds_dwordx4 v[168:169], off
	v_lshl_add_u64 v[168:169], s[42:43], 0, v[156:157]
	s_add_i32 m0, s41, 0xe000
	s_nop 0
	global_load_lds_dwordx4 v[168:169], off
	s_waitcnt vmcnt(8)
	s_waitcnt lgkmcnt(0)
	v_mfma_f32_16x16x32_bf16 v[126:129], v[130:133], v[194:197], v[126:129]
	v_mfma_f32_16x16x32_bf16 v[122:125], v[164:167], v[194:197], v[122:125]
	v_mfma_f32_16x16x32_bf16 v[110:113], v[130:133], v[202:205], v[110:113]
	v_mfma_f32_16x16x32_bf16 v[106:109], v[164:167], v[202:205], v[106:109]
	s_barrier
	s_setprio 1
	v_mfma_f32_16x16x32_bf16 v[94:97], v[130:133], v[210:213], v[94:97]
	v_mfma_f32_16x16x32_bf16 v[90:93], v[164:167], v[210:213], v[90:93]
	v_mfma_f32_16x16x32_bf16 v[78:81], v[130:133], v[218:221], v[78:81]
	v_mfma_f32_16x16x32_bf16 v[74:77], v[164:167], v[218:221], v[74:77]
	v_mfma_f32_16x16x32_bf16 v[126:129], v[134:137], v[198:201], v[126:129]
	v_mfma_f32_16x16x32_bf16 v[122:125], v[174:177], v[198:201], v[122:125]
	v_mfma_f32_16x16x32_bf16 v[110:113], v[134:137], v[206:209], v[110:113]
	v_mfma_f32_16x16x32_bf16 v[106:109], v[174:177], v[206:209], v[106:109]
	v_mfma_f32_16x16x32_bf16 v[94:97], v[134:137], v[214:217], v[94:97]
	v_mfma_f32_16x16x32_bf16 v[90:93], v[174:177], v[214:217], v[90:93]
	v_mfma_f32_16x16x32_bf16 v[78:81], v[134:137], v[222:225], v[78:81]
	v_mfma_f32_16x16x32_bf16 v[74:77], v[174:177], v[222:225], v[74:77]
	v_mfma_f32_16x16x32_bf16 v[118:121], v[178:181], v[194:197], v[118:121]
	v_mfma_f32_16x16x32_bf16 v[114:117], v[186:189], v[194:197], v[114:117]
	v_mfma_f32_16x16x32_bf16 v[102:105], v[178:181], v[202:205], v[102:105]
	v_mfma_f32_16x16x32_bf16 v[98:101], v[186:189], v[202:205], v[98:101]
	v_mfma_f32_16x16x32_bf16 v[86:89], v[178:181], v[210:213], v[86:89]
	v_mfma_f32_16x16x32_bf16 v[82:85], v[186:189], v[210:213], v[82:85]
	v_mfma_f32_16x16x32_bf16 v[70:73], v[178:181], v[218:221], v[70:73]
	v_mfma_f32_16x16x32_bf16 v[66:69], v[186:189], v[218:221], v[66:69]
	v_mfma_f32_16x16x32_bf16 v[118:121], v[182:185], v[198:201], v[118:121]
	v_mfma_f32_16x16x32_bf16 v[114:117], v[190:193], v[198:201], v[114:117]
	v_mfma_f32_16x16x32_bf16 v[102:105], v[182:185], v[206:209], v[102:105]
	v_mfma_f32_16x16x32_bf16 v[98:101], v[190:193], v[206:209], v[98:101]
	v_mfma_f32_16x16x32_bf16 v[86:89], v[182:185], v[214:217], v[86:89]
	v_mfma_f32_16x16x32_bf16 v[82:85], v[190:193], v[214:217], v[82:85]
	v_mfma_f32_16x16x32_bf16 v[70:73], v[182:185], v[222:225], v[70:73]
	v_mfma_f32_16x16x32_bf16 v[66:69], v[190:193], v[222:225], v[66:69]
	s_setprio 0
	s_barrier
	s_add_i32 s19, s75, s52
	v_lshl_add_u64 v[168:169], s[44:45], 0, v[140:141]
	s_mov_b32 m0, s19
	ds_read_b128 v[194:197], v172 offset:16384
	ds_read_b128 v[198:201], v172 offset:17408
	ds_read_b128 v[202:205], v172 offset:18432
	ds_read_b128 v[206:209], v172 offset:19456
	ds_read_b128 v[210:213], v172 offset:20480
	ds_read_b128 v[214:217], v172 offset:21504
	ds_read_b128 v[218:221], v172 offset:22528
	ds_read_b128 v[222:225], v172 offset:23552
	global_load_lds_dwordx4 v[168:169], off
	s_add_i32 m0, s19, 0x2000
	s_add_u32 s20, s44, 0x80000
	v_lshl_add_u64 v[226:227], s[44:45], 0, v[144:145]
	s_addc_u32 s21, s45, 0
	s_add_i32 s19, s76, s52
	global_load_lds_dwordx4 v[226:227], off
	v_lshl_add_u64 v[228:229], s[20:21], 0, v[140:141]
	s_mov_b32 m0, s19
	v_lshl_add_u64 v[230:231], s[46:47], 0, v[142:143]
	global_load_lds_dwordx4 v[228:229], off
	v_lshl_add_u64 v[228:229], s[20:21], 0, v[144:145]
	s_add_i32 m0, s19, 0x2000
	s_nop 0
	global_load_lds_dwordx4 v[228:229], off
	v_lshl_add_u64 v[228:229], s[46:47], 0, v[138:139]
	s_mov_b32 m0, s41
	s_nop 0
	global_load_lds_dwordx4 v[228:229], off
	s_mov_b32 m0, s53
	s_nop 0
	global_load_lds_dwordx4 v[230:231], off
	s_waitcnt vmcnt(8)
	s_waitcnt lgkmcnt(0)
	v_mfma_f32_16x16x32_bf16 v[62:65], v[130:133], v[194:197], v[62:65]
	v_mfma_f32_16x16x32_bf16 v[58:61], v[164:167], v[194:197], v[58:61]
	v_mfma_f32_16x16x32_bf16 v[46:49], v[130:133], v[202:205], v[46:49]
	v_mfma_f32_16x16x32_bf16 v[42:45], v[164:167], v[202:205], v[42:45]
	s_barrier
	s_setprio 1
	v_mfma_f32_16x16x32_bf16 v[30:33], v[130:133], v[210:213], v[30:33]
	v_mfma_f32_16x16x32_bf16 v[26:29], v[164:167], v[210:213], v[26:29]
	v_mfma_f32_16x16x32_bf16 v[14:17], v[130:133], v[218:221], v[14:17]
	v_mfma_f32_16x16x32_bf16 v[10:13], v[164:167], v[218:221], v[10:13]
	v_mfma_f32_16x16x32_bf16 v[62:65], v[134:137], v[198:201], v[62:65]
	v_mfma_f32_16x16x32_bf16 v[58:61], v[174:177], v[198:201], v[58:61]
	v_mfma_f32_16x16x32_bf16 v[46:49], v[134:137], v[206:209], v[46:49]
	v_mfma_f32_16x16x32_bf16 v[42:45], v[174:177], v[206:209], v[42:45]
	v_mfma_f32_16x16x32_bf16 v[30:33], v[134:137], v[214:217], v[30:33]
	v_mfma_f32_16x16x32_bf16 v[26:29], v[174:177], v[214:217], v[26:29]
	v_mfma_f32_16x16x32_bf16 v[14:17], v[134:137], v[222:225], v[14:17]
	v_mfma_f32_16x16x32_bf16 v[10:13], v[174:177], v[222:225], v[10:13]
	v_mfma_f32_16x16x32_bf16 v[54:57], v[178:181], v[194:197], v[54:57]
	v_mfma_f32_16x16x32_bf16 v[50:53], v[186:189], v[194:197], v[50:53]
	v_mfma_f32_16x16x32_bf16 v[38:41], v[178:181], v[202:205], v[38:41]
	v_mfma_f32_16x16x32_bf16 v[34:37], v[186:189], v[202:205], v[34:37]
	v_mfma_f32_16x16x32_bf16 v[22:25], v[178:181], v[210:213], v[22:25]
	v_mfma_f32_16x16x32_bf16 v[18:21], v[186:189], v[210:213], v[18:21]
	v_mfma_f32_16x16x32_bf16 v[6:9], v[178:181], v[218:221], v[6:9]
	v_mfma_f32_16x16x32_bf16 v[2:5], v[186:189], v[218:221], v[2:5]
	v_mfma_f32_16x16x32_bf16 v[54:57], v[182:185], v[198:201], v[54:57]
	v_mfma_f32_16x16x32_bf16 v[50:53], v[190:193], v[198:201], v[50:53]
	v_mfma_f32_16x16x32_bf16 v[38:41], v[182:185], v[206:209], v[38:41]
	v_mfma_f32_16x16x32_bf16 v[34:37], v[190:193], v[206:209], v[34:37]
	v_mfma_f32_16x16x32_bf16 v[22:25], v[182:185], v[214:217], v[22:25]
	v_mfma_f32_16x16x32_bf16 v[18:21], v[190:193], v[214:217], v[18:21]
	v_mfma_f32_16x16x32_bf16 v[6:9], v[182:185], v[222:225], v[6:9]
	v_mfma_f32_16x16x32_bf16 v[2:5], v[190:193], v[222:225], v[2:5]
	s_setprio 0
	s_barrier
	s_add_i32 s19, 0, 0x18000
	v_add_u32_e32 v146, s19, v163
	s_add_i32 s31, 0, 0x1c000
	ds_read_b128 v[130:133], v146
	ds_read_b128 v[134:137], v146 offset:1024
	ds_read_b128 v[164:167], v146 offset:2048
	ds_read_b128 v[174:177], v146 offset:3072
	v_add_u32_e32 v146, s31, v163
	ds_read_b128 v[178:181], v146
	ds_read_b128 v[182:185], v146 offset:1024
	ds_read_b128 v[186:189], v146 offset:2048
	ds_read_b128 v[190:193], v146 offset:3072
	s_add_u32 s20, s46, 0x80000
	s_addc_u32 s21, s47, 0
	s_mov_b32 m0, s54
	v_lshl_add_u64 v[232:233], s[20:21], 0, v[138:139]
	ds_read_b128 v[194:197], v172 offset:32768
	ds_read_b128 v[198:201], v172 offset:33792
	ds_read_b128 v[202:205], v172 offset:34816
	ds_read_b128 v[206:209], v172 offset:35840
	ds_read_b128 v[210:213], v172 offset:36864
	ds_read_b128 v[214:217], v172 offset:37888
	ds_read_b128 v[218:221], v172 offset:38912
	ds_read_b128 v[222:225], v172 offset:39936
	global_load_lds_dwordx4 v[232:233], off
	v_lshl_add_u64 v[232:233], s[20:21], 0, v[142:143]
	s_mov_b32 m0, s55
	s_nop 0
	global_load_lds_dwordx4 v[232:233], off
	s_waitcnt vmcnt(8)
	s_waitcnt lgkmcnt(0)
	v_mfma_f32_16x16x32_bf16 v[126:129], v[130:133], v[194:197], v[126:129]
	v_mfma_f32_16x16x32_bf16 v[122:125], v[164:167], v[194:197], v[122:125]
	v_mfma_f32_16x16x32_bf16 v[110:113], v[130:133], v[202:205], v[110:113]
	v_mfma_f32_16x16x32_bf16 v[106:109], v[164:167], v[202:205], v[106:109]
	s_barrier
	s_setprio 1
	v_mfma_f32_16x16x32_bf16 v[94:97], v[130:133], v[210:213], v[94:97]
	v_mfma_f32_16x16x32_bf16 v[90:93], v[164:167], v[210:213], v[90:93]
	v_mfma_f32_16x16x32_bf16 v[78:81], v[130:133], v[218:221], v[78:81]
	v_mfma_f32_16x16x32_bf16 v[74:77], v[164:167], v[218:221], v[74:77]
	v_mfma_f32_16x16x32_bf16 v[126:129], v[134:137], v[198:201], v[126:129]
	v_mfma_f32_16x16x32_bf16 v[122:125], v[174:177], v[198:201], v[122:125]
	v_mfma_f32_16x16x32_bf16 v[110:113], v[134:137], v[206:209], v[110:113]
	v_mfma_f32_16x16x32_bf16 v[106:109], v[174:177], v[206:209], v[106:109]
	v_mfma_f32_16x16x32_bf16 v[94:97], v[134:137], v[214:217], v[94:97]
	v_mfma_f32_16x16x32_bf16 v[90:93], v[174:177], v[214:217], v[90:93]
	v_mfma_f32_16x16x32_bf16 v[78:81], v[134:137], v[222:225], v[78:81]
	v_mfma_f32_16x16x32_bf16 v[74:77], v[174:177], v[222:225], v[74:77]
	v_mfma_f32_16x16x32_bf16 v[118:121], v[178:181], v[194:197], v[118:121]
	v_mfma_f32_16x16x32_bf16 v[114:117], v[186:189], v[194:197], v[114:117]
	v_mfma_f32_16x16x32_bf16 v[102:105], v[178:181], v[202:205], v[102:105]
	v_mfma_f32_16x16x32_bf16 v[98:101], v[186:189], v[202:205], v[98:101]
	v_mfma_f32_16x16x32_bf16 v[86:89], v[178:181], v[210:213], v[86:89]
	v_mfma_f32_16x16x32_bf16 v[82:85], v[186:189], v[210:213], v[82:85]
	v_mfma_f32_16x16x32_bf16 v[70:73], v[178:181], v[218:221], v[70:73]
	v_mfma_f32_16x16x32_bf16 v[66:69], v[186:189], v[218:221], v[66:69]
	v_mfma_f32_16x16x32_bf16 v[118:121], v[182:185], v[198:201], v[118:121]
	v_mfma_f32_16x16x32_bf16 v[114:117], v[190:193], v[198:201], v[114:117]
	v_mfma_f32_16x16x32_bf16 v[102:105], v[182:185], v[206:209], v[102:105]
	v_mfma_f32_16x16x32_bf16 v[98:101], v[190:193], v[206:209], v[98:101]
	v_mfma_f32_16x16x32_bf16 v[86:89], v[182:185], v[214:217], v[86:89]
	v_mfma_f32_16x16x32_bf16 v[82:85], v[190:193], v[214:217], v[82:85]
	v_mfma_f32_16x16x32_bf16 v[70:73], v[182:185], v[222:225], v[70:73]
	v_mfma_f32_16x16x32_bf16 v[66:69], v[190:193], v[222:225], v[66:69]
	s_setprio 0
	s_barrier
	s_add_i32 s19, s19, s52
	v_lshl_add_u64 v[168:169], v[168:169], 0, s[10:11]
	s_mov_b32 m0, s19
	ds_read_b128 v[194:197], v172 offset:49152
	ds_read_b128 v[198:201], v172 offset:50176
	ds_read_b128 v[202:205], v172 offset:51200
	ds_read_b128 v[206:209], v172 offset:52224
	ds_read_b128 v[210:213], v172 offset:53248
	ds_read_b128 v[214:217], v172 offset:54272
	ds_read_b128 v[218:221], v172 offset:55296
	ds_read_b128 v[222:225], v172 offset:56320
	global_load_lds_dwordx4 v[168:169], off
	s_add_i32 m0, s19, 0x2000
	s_add_u32 s20, s44, 0x80080
	v_lshl_add_u64 v[168:169], v[226:227], 0, s[10:11]
	s_addc_u32 s21, s45, 0
	s_add_i32 s19, s31, s52
	global_load_lds_dwordx4 v[168:169], off
	v_lshl_add_u64 v[168:169], s[20:21], 0, v[140:141]
	s_mov_b32 m0, s19
	s_nop 0
	global_load_lds_dwordx4 v[168:169], off
	v_lshl_add_u64 v[168:169], s[20:21], 0, v[144:145]
	s_add_i32 m0, s19, 0x2000
	s_nop 0
	global_load_lds_dwordx4 v[168:169], off
	v_lshl_add_u64 v[168:169], v[228:229], 0, s[10:11]
	s_mov_b32 m0, s67
	s_nop 0
	global_load_lds_dwordx4 v[168:169], off
	v_lshl_add_u64 v[168:169], v[230:231], 0, s[10:11]
	s_mov_b32 m0, s68
	s_nop 0
	global_load_lds_dwordx4 v[168:169], off
	s_waitcnt vmcnt(8)
	s_waitcnt lgkmcnt(0)
	v_mfma_f32_16x16x32_bf16 v[62:65], v[130:133], v[194:197], v[62:65]
	v_mfma_f32_16x16x32_bf16 v[58:61], v[164:167], v[194:197], v[58:61]
	v_mfma_f32_16x16x32_bf16 v[46:49], v[130:133], v[202:205], v[46:49]
	v_mfma_f32_16x16x32_bf16 v[42:45], v[164:167], v[202:205], v[42:45]
	s_barrier
	s_setprio 1
	v_mfma_f32_16x16x32_bf16 v[30:33], v[130:133], v[210:213], v[30:33]
	v_mfma_f32_16x16x32_bf16 v[26:29], v[164:167], v[210:213], v[26:29]
	v_mfma_f32_16x16x32_bf16 v[14:17], v[130:133], v[218:221], v[14:17]
	v_mfma_f32_16x16x32_bf16 v[10:13], v[164:167], v[218:221], v[10:13]
	v_mfma_f32_16x16x32_bf16 v[62:65], v[134:137], v[198:201], v[62:65]
	v_mfma_f32_16x16x32_bf16 v[58:61], v[174:177], v[198:201], v[58:61]
	v_mfma_f32_16x16x32_bf16 v[46:49], v[134:137], v[206:209], v[46:49]
	v_mfma_f32_16x16x32_bf16 v[42:45], v[174:177], v[206:209], v[42:45]
	v_mfma_f32_16x16x32_bf16 v[30:33], v[134:137], v[214:217], v[30:33]
	v_mfma_f32_16x16x32_bf16 v[26:29], v[174:177], v[214:217], v[26:29]
	v_mfma_f32_16x16x32_bf16 v[14:17], v[134:137], v[222:225], v[14:17]
	v_mfma_f32_16x16x32_bf16 v[10:13], v[174:177], v[222:225], v[10:13]
	v_mfma_f32_16x16x32_bf16 v[54:57], v[178:181], v[194:197], v[54:57]
	v_mfma_f32_16x16x32_bf16 v[50:53], v[186:189], v[194:197], v[50:53]
	v_mfma_f32_16x16x32_bf16 v[38:41], v[178:181], v[202:205], v[38:41]
	v_mfma_f32_16x16x32_bf16 v[34:37], v[186:189], v[202:205], v[34:37]
	v_mfma_f32_16x16x32_bf16 v[22:25], v[178:181], v[210:213], v[22:25]
	v_mfma_f32_16x16x32_bf16 v[18:21], v[186:189], v[210:213], v[18:21]
	v_mfma_f32_16x16x32_bf16 v[6:9], v[178:181], v[218:221], v[6:9]
	v_mfma_f32_16x16x32_bf16 v[2:5], v[186:189], v[218:221], v[2:5]
	v_mfma_f32_16x16x32_bf16 v[54:57], v[182:185], v[198:201], v[54:57]
	v_mfma_f32_16x16x32_bf16 v[50:53], v[190:193], v[198:201], v[50:53]
	v_mfma_f32_16x16x32_bf16 v[38:41], v[182:185], v[206:209], v[38:41]
	v_mfma_f32_16x16x32_bf16 v[34:37], v[190:193], v[206:209], v[34:37]
	v_mfma_f32_16x16x32_bf16 v[22:25], v[182:185], v[214:217], v[22:25]
	v_mfma_f32_16x16x32_bf16 v[18:21], v[190:193], v[214:217], v[18:21]
	v_mfma_f32_16x16x32_bf16 v[6:9], v[182:185], v[222:225], v[6:9]
	v_mfma_f32_16x16x32_bf16 v[2:5], v[190:193], v[222:225], v[2:5]
	s_setprio 0
	s_barrier
	s_add_i32 s18, s18, 2
	s_add_u32 s42, s42, 0x100
	s_addc_u32 s43, s43, 0
	s_add_u32 s16, s16, 0x100
	s_addc_u32 s17, s17, 0
	s_cmp_gt_u32 s18, 29
	s_cbranch_scc0 .LBB0_466
	s_and_b64 vcc, exec, s[12:13]
	s_cbranch_vccz .LBB0_469
	s_barrier

.LBB0_699:
	ds_read_b128 v[134:137], v214
	ds_read_b128 v[138:141], v214 offset:1024
	ds_read_b128 v[142:145], v214 offset:2048
	ds_read_b128 v[178:181], v214 offset:3072
	ds_read_b128 v[182:185], v215
	ds_read_b128 v[186:189], v215 offset:1024
	ds_read_b128 v[190:193], v215 offset:2048
	ds_read_b128 v[194:197], v215 offset:3072
	s_add_u32 s40, s38, 0x100
	s_addc_u32 s41, s39, 0
	s_add_u32 s18, s15, s38
	s_addc_u32 s19, s16, s39
	s_cmp_eq_u32 s17, 60
	s_cselect_b32 s45, s3, s19
	s_cselect_b32 s19, 0, s40
	s_cselect_b32 s44, s14, s18
	s_cselect_b32 s18, 0, s41
	s_add_u32 s42, s10, s19
	s_addc_u32 s43, s11, s18
	s_mov_b32 m0, s66
	v_lshl_add_u64 v[244:245], v[130:131], 0, s[38:39]
	ds_read_b128 v[198:201], v216
	ds_read_b128 v[202:205], v216 offset:1024
	ds_read_b128 v[206:209], v216 offset:2048
	ds_read_b128 v[224:227], v216 offset:3072
	ds_read_b128 v[228:231], v216 offset:4096
	ds_read_b128 v[232:235], v216 offset:5120
	ds_read_b128 v[236:239], v216 offset:6144
	ds_read_b128 v[240:243], v216 offset:7168
	global_load_lds_dwordx4 v[244:245], off
	v_lshl_add_u64 v[244:245], v[132:133], 0, s[38:39]
	s_mov_b32 m0, s67
	s_nop 0
	global_load_lds_dwordx4 v[244:245], off
	s_waitcnt vmcnt(8)
	s_waitcnt lgkmcnt(0)
	v_mfma_f32_16x16x32_bf16 v[82:85], v[134:137], v[198:201], v[82:85]
	v_mfma_f32_16x16x32_bf16 v[78:81], v[142:145], v[198:201], v[78:81]
	v_mfma_f32_16x16x32_bf16 v[110:113], v[134:137], v[206:209], v[110:113]
	v_mfma_f32_16x16x32_bf16 v[106:109], v[142:145], v[206:209], v[106:109]
	s_barrier
	s_setprio 1
	v_mfma_f32_16x16x32_bf16 v[118:121], v[134:137], v[228:231], v[118:121]
	v_mfma_f32_16x16x32_bf16 v[114:117], v[142:145], v[228:231], v[114:117]
	v_mfma_f32_16x16x32_bf16 v[126:129], v[134:137], v[236:239], v[126:129]
	v_mfma_f32_16x16x32_bf16 v[122:125], v[142:145], v[236:239], v[122:125]
	v_mfma_f32_16x16x32_bf16 v[82:85], v[138:141], v[202:205], v[82:85]
	v_mfma_f32_16x16x32_bf16 v[78:81], v[178:181], v[202:205], v[78:81]
	v_mfma_f32_16x16x32_bf16 v[110:113], v[138:141], v[224:227], v[110:113]
	v_mfma_f32_16x16x32_bf16 v[106:109], v[178:181], v[224:227], v[106:109]
	v_mfma_f32_16x16x32_bf16 v[118:121], v[138:141], v[232:235], v[118:121]
	v_mfma_f32_16x16x32_bf16 v[114:117], v[178:181], v[232:235], v[114:117]
	v_mfma_f32_16x16x32_bf16 v[126:129], v[138:141], v[240:243], v[126:129]
	v_mfma_f32_16x16x32_bf16 v[122:125], v[178:181], v[240:243], v[122:125]
	v_mfma_f32_16x16x32_bf16 v[22:25], v[182:185], v[198:201], v[22:25]
	v_mfma_f32_16x16x32_bf16 v[26:29], v[190:193], v[198:201], v[26:29]
	v_mfma_f32_16x16x32_bf16 v[42:45], v[182:185], v[206:209], v[42:45]
	v_mfma_f32_16x16x32_bf16 v[46:49], v[190:193], v[206:209], v[46:49]
	v_mfma_f32_16x16x32_bf16 v[62:65], v[182:185], v[228:231], v[62:65]
	v_mfma_f32_16x16x32_bf16 v[70:73], v[190:193], v[228:231], v[70:73]
	v_mfma_f32_16x16x32_bf16 v[90:93], v[182:185], v[236:239], v[90:93]
	v_mfma_f32_16x16x32_bf16 v[94:97], v[190:193], v[236:239], v[94:97]
	v_mfma_f32_16x16x32_bf16 v[22:25], v[186:189], v[202:205], v[22:25]
	v_mfma_f32_16x16x32_bf16 v[26:29], v[194:197], v[202:205], v[26:29]
	v_mfma_f32_16x16x32_bf16 v[42:45], v[186:189], v[224:227], v[42:45]
	v_mfma_f32_16x16x32_bf16 v[46:49], v[194:197], v[224:227], v[46:49]
	v_mfma_f32_16x16x32_bf16 v[62:65], v[186:189], v[232:235], v[62:65]
	v_mfma_f32_16x16x32_bf16 v[70:73], v[194:197], v[232:235], v[70:73]
	v_mfma_f32_16x16x32_bf16 v[90:93], v[186:189], v[240:243], v[90:93]
	v_mfma_f32_16x16x32_bf16 v[94:97], v[194:197], v[240:243], v[94:97]
	s_setprio 0
	s_barrier
	s_mov_b32 m0, s68
	v_lshl_add_u64 v[244:245], s[42:43], 0, v[150:151]
	s_add_u32 s18, s42, 0x100000
	ds_read_b128 v[198:201], v216 offset:16384
	ds_read_b128 v[202:205], v216 offset:17408
	ds_read_b128 v[206:209], v216 offset:18432
	ds_read_b128 v[224:227], v216 offset:19456
	ds_read_b128 v[228:231], v216 offset:20480
	ds_read_b128 v[232:235], v216 offset:21504
	ds_read_b128 v[236:239], v216 offset:22528
	ds_read_b128 v[240:243], v216 offset:23552
	global_load_lds_dwordx4 v[244:245], off
	v_lshl_add_u64 v[246:247], s[42:43], 0, v[146:147]
	s_mov_b32 m0, s69
	s_addc_u32 s19, s43, 0
	global_load_lds_dwordx4 v[246:247], off
	v_lshl_add_u64 v[248:249], s[18:19], 0, v[150:151]
	s_mov_b32 m0, s73
	v_lshl_add_u64 v[250:251], s[44:45], 0, v[148:149]
	global_load_lds_dwordx4 v[248:249], off
	v_lshl_add_u64 v[248:249], s[18:19], 0, v[146:147]
	s_mov_b32 m0, s74
	s_nop 0
	global_load_lds_dwordx4 v[248:249], off
	v_lshl_add_u64 v[248:249], s[44:45], 0, v[152:153]
	s_mov_b32 m0, s9
	s_nop 0
	global_load_lds_dwordx4 v[248:249], off
	s_mov_b32 m0, s55
	s_nop 0
	global_load_lds_dwordx4 v[250:251], off
	s_waitcnt vmcnt(8)
	s_waitcnt lgkmcnt(0)
	v_mfma_f32_16x16x32_bf16 v[102:105], v[134:137], v[198:201], v[102:105]
	v_mfma_f32_16x16x32_bf16 v[98:101], v[142:145], v[198:201], v[98:101]
	v_mfma_f32_16x16x32_bf16 v[66:69], v[134:137], v[206:209], v[66:69]
	v_mfma_f32_16x16x32_bf16 v[58:61], v[142:145], v[206:209], v[58:61]
	s_barrier
	s_setprio 1
	v_mfma_f32_16x16x32_bf16 v[38:41], v[134:137], v[228:231], v[38:41]
	v_mfma_f32_16x16x32_bf16 v[34:37], v[142:145], v[228:231], v[34:37]
	v_mfma_f32_16x16x32_bf16 v[14:17], v[134:137], v[236:239], v[14:17]
	v_mfma_f32_16x16x32_bf16 v[10:13], v[142:145], v[236:239], v[10:13]
	v_mfma_f32_16x16x32_bf16 v[102:105], v[138:141], v[202:205], v[102:105]
	v_mfma_f32_16x16x32_bf16 v[98:101], v[178:181], v[202:205], v[98:101]
	v_mfma_f32_16x16x32_bf16 v[66:69], v[138:141], v[224:227], v[66:69]
	v_mfma_f32_16x16x32_bf16 v[58:61], v[178:181], v[224:227], v[58:61]
	v_mfma_f32_16x16x32_bf16 v[38:41], v[138:141], v[232:235], v[38:41]
	v_mfma_f32_16x16x32_bf16 v[34:37], v[178:181], v[232:235], v[34:37]
	v_mfma_f32_16x16x32_bf16 v[14:17], v[138:141], v[240:243], v[14:17]
	v_mfma_f32_16x16x32_bf16 v[10:13], v[178:181], v[240:243], v[10:13]
	v_mfma_f32_16x16x32_bf16 v[86:89], v[182:185], v[198:201], v[86:89]
	v_mfma_f32_16x16x32_bf16 v[74:77], v[190:193], v[198:201], v[74:77]
	v_mfma_f32_16x16x32_bf16 v[54:57], v[182:185], v[206:209], v[54:57]
	v_mfma_f32_16x16x32_bf16 v[50:53], v[190:193], v[206:209], v[50:53]
	v_mfma_f32_16x16x32_bf16 v[30:33], v[182:185], v[228:231], v[30:33]
	v_mfma_f32_16x16x32_bf16 v[18:21], v[190:193], v[228:231], v[18:21]
	v_mfma_f32_16x16x32_bf16 v[6:9], v[182:185], v[236:239], v[6:9]
	v_mfma_f32_16x16x32_bf16 v[2:5], v[190:193], v[236:239], v[2:5]
	v_mfma_f32_16x16x32_bf16 v[86:89], v[186:189], v[202:205], v[86:89]
	v_mfma_f32_16x16x32_bf16 v[74:77], v[194:197], v[202:205], v[74:77]
	v_mfma_f32_16x16x32_bf16 v[54:57], v[186:189], v[224:227], v[54:57]
	v_mfma_f32_16x16x32_bf16 v[50:53], v[194:197], v[224:227], v[50:53]
	v_mfma_f32_16x16x32_bf16 v[30:33], v[186:189], v[232:235], v[30:33]
	v_mfma_f32_16x16x32_bf16 v[18:21], v[194:197], v[232:235], v[18:21]
	v_mfma_f32_16x16x32_bf16 v[6:9], v[186:189], v[240:243], v[6:9]
	v_mfma_f32_16x16x32_bf16 v[2:5], v[194:197], v[240:243], v[2:5]
	s_setprio 0
	s_barrier
	s_add_i32 s20, 0, 0x1c000
	v_add_u32_e32 v194, s20, v212
	ds_read_b128 v[134:137], v220
	ds_read_b128 v[138:141], v220 offset:1024
	ds_read_b128 v[142:145], v220 offset:2048
	ds_read_b128 v[178:181], v220 offset:3072
	ds_read_b128 v[182:185], v194
	ds_read_b128 v[186:189], v194 offset:1024
	ds_read_b128 v[190:193], v194 offset:2048
	ds_read_b128 v[194:197], v194 offset:3072
	s_add_u32 s18, s44, 0x100000
	s_addc_u32 s19, s45, 0
	s_mov_b32 m0, s56
	v_lshl_add_u64 v[252:253], s[18:19], 0, v[152:153]
	ds_read_b128 v[198:201], v216 offset:32768
	ds_read_b128 v[202:205], v216 offset:33792
	ds_read_b128 v[206:209], v216 offset:34816
	ds_read_b128 v[224:227], v216 offset:35840
	ds_read_b128 v[228:231], v216 offset:36864
	ds_read_b128 v[232:235], v216 offset:37888
	ds_read_b128 v[236:239], v216 offset:38912
	ds_read_b128 v[240:243], v216 offset:39936
	global_load_lds_dwordx4 v[252:253], off
	v_lshl_add_u64 v[252:253], s[18:19], 0, v[148:149]
	s_mov_b32 m0, s57
	s_nop 0
	global_load_lds_dwordx4 v[252:253], off
	s_waitcnt vmcnt(8)
	s_waitcnt lgkmcnt(0)
	v_mfma_f32_16x16x32_bf16 v[82:85], v[134:137], v[198:201], v[82:85]
	v_mfma_f32_16x16x32_bf16 v[78:81], v[142:145], v[198:201], v[78:81]
	v_mfma_f32_16x16x32_bf16 v[110:113], v[134:137], v[206:209], v[110:113]
	v_mfma_f32_16x16x32_bf16 v[106:109], v[142:145], v[206:209], v[106:109]
	s_barrier
	s_setprio 1
	v_mfma_f32_16x16x32_bf16 v[118:121], v[134:137], v[228:231], v[118:121]
	v_mfma_f32_16x16x32_bf16 v[114:117], v[142:145], v[228:231], v[114:117]
	v_mfma_f32_16x16x32_bf16 v[126:129], v[134:137], v[236:239], v[126:129]
	v_mfma_f32_16x16x32_bf16 v[122:125], v[142:145], v[236:239], v[122:125]
	v_mfma_f32_16x16x32_bf16 v[82:85], v[138:141], v[202:205], v[82:85]
	v_mfma_f32_16x16x32_bf16 v[78:81], v[178:181], v[202:205], v[78:81]
	v_mfma_f32_16x16x32_bf16 v[110:113], v[138:141], v[224:227], v[110:113]
	v_mfma_f32_16x16x32_bf16 v[106:109], v[178:181], v[224:227], v[106:109]
	v_mfma_f32_16x16x32_bf16 v[118:121], v[138:141], v[232:235], v[118:121]
	v_mfma_f32_16x16x32_bf16 v[114:117], v[178:181], v[232:235], v[114:117]
	v_mfma_f32_16x16x32_bf16 v[126:129], v[138:141], v[240:243], v[126:129]
	v_mfma_f32_16x16x32_bf16 v[122:125], v[178:181], v[240:243], v[122:125]
	v_mfma_f32_16x16x32_bf16 v[22:25], v[182:185], v[198:201], v[22:25]
	v_mfma_f32_16x16x32_bf16 v[26:29], v[190:193], v[198:201], v[26:29]
	v_mfma_f32_16x16x32_bf16 v[42:45], v[182:185], v[206:209], v[42:45]
	v_mfma_f32_16x16x32_bf16 v[46:49], v[190:193], v[206:209], v[46:49]
	v_mfma_f32_16x16x32_bf16 v[62:65], v[182:185], v[228:231], v[62:65]
	v_mfma_f32_16x16x32_bf16 v[70:73], v[190:193], v[228:231], v[70:73]
	v_mfma_f32_16x16x32_bf16 v[90:93], v[182:185], v[236:239], v[90:93]
	v_mfma_f32_16x16x32_bf16 v[94:97], v[190:193], v[236:239], v[94:97]
	v_mfma_f32_16x16x32_bf16 v[22:25], v[186:189], v[202:205], v[22:25]
	v_mfma_f32_16x16x32_bf16 v[26:29], v[194:197], v[202:205], v[26:29]
	v_mfma_f32_16x16x32_bf16 v[42:45], v[186:189], v[224:227], v[42:45]
	v_mfma_f32_16x16x32_bf16 v[46:49], v[194:197], v[224:227], v[46:49]
	v_mfma_f32_16x16x32_bf16 v[62:65], v[186:189], v[232:235], v[62:65]
	v_mfma_f32_16x16x32_bf16 v[70:73], v[194:197], v[232:235], v[70:73]
	v_mfma_f32_16x16x32_bf16 v[90:93], v[186:189], v[240:243], v[90:93]
	v_mfma_f32_16x16x32_bf16 v[94:97], v[194:197], v[240:243], v[94:97]
	s_setprio 0
	s_barrier
	s_add_i32 s18, s75, s54
	v_lshl_add_u64 v[244:245], v[244:245], 0, s[26:27]
	s_mov_b32 m0, s18
	ds_read_b128 v[198:201], v216 offset:49152
	ds_read_b128 v[202:205], v216 offset:50176
	ds_read_b128 v[206:209], v216 offset:51200
	ds_read_b128 v[224:227], v216 offset:52224
	ds_read_b128 v[228:231], v216 offset:53248
	ds_read_b128 v[232:235], v216 offset:54272
	ds_read_b128 v[236:239], v216 offset:55296
	ds_read_b128 v[240:243], v216 offset:56320
	global_load_lds_dwordx4 v[244:245], off
	s_add_i32 m0, s18, 0x2000
	s_add_u32 s18, s42, 0x100080
	v_lshl_add_u64 v[244:245], v[246:247], 0, s[26:27]
	s_addc_u32 s19, s43, 0
	s_add_i32 s20, s20, s54
	global_load_lds_dwordx4 v[244:245], off
	v_lshl_add_u64 v[244:245], s[18:19], 0, v[150:151]
	s_mov_b32 m0, s20
	s_nop 0
	global_load_lds_dwordx4 v[244:245], off
	v_lshl_add_u64 v[244:245], s[18:19], 0, v[146:147]
	s_add_i32 m0, s20, 0x2000
	s_nop 0
	global_load_lds_dwordx4 v[244:245], off
	v_lshl_add_u64 v[244:245], v[248:249], 0, s[26:27]
	s_mov_b32 m0, s63
	s_nop 0
	global_load_lds_dwordx4 v[244:245], off
	v_lshl_add_u64 v[244:245], v[250:251], 0, s[26:27]
	s_mov_b32 m0, s64
	s_nop 0
	global_load_lds_dwordx4 v[244:245], off
	s_waitcnt vmcnt(8)
	s_waitcnt lgkmcnt(0)
	v_mfma_f32_16x16x32_bf16 v[102:105], v[134:137], v[198:201], v[102:105]
	v_mfma_f32_16x16x32_bf16 v[98:101], v[142:145], v[198:201], v[98:101]
	v_mfma_f32_16x16x32_bf16 v[66:69], v[134:137], v[206:209], v[66:69]
	v_mfma_f32_16x16x32_bf16 v[58:61], v[142:145], v[206:209], v[58:61]
	s_barrier
	s_setprio 1
	v_mfma_f32_16x16x32_bf16 v[38:41], v[134:137], v[228:231], v[38:41]
	v_mfma_f32_16x16x32_bf16 v[34:37], v[142:145], v[228:231], v[34:37]
	v_mfma_f32_16x16x32_bf16 v[14:17], v[134:137], v[236:239], v[14:17]
	v_mfma_f32_16x16x32_bf16 v[10:13], v[142:145], v[236:239], v[10:13]
	v_mfma_f32_16x16x32_bf16 v[102:105], v[138:141], v[202:205], v[102:105]
	v_mfma_f32_16x16x32_bf16 v[98:101], v[178:181], v[202:205], v[98:101]
	v_mfma_f32_16x16x32_bf16 v[66:69], v[138:141], v[224:227], v[66:69]
	v_mfma_f32_16x16x32_bf16 v[58:61], v[178:181], v[224:227], v[58:61]
	v_mfma_f32_16x16x32_bf16 v[38:41], v[138:141], v[232:235], v[38:41]
	v_mfma_f32_16x16x32_bf16 v[34:37], v[178:181], v[232:235], v[34:37]
	v_mfma_f32_16x16x32_bf16 v[14:17], v[138:141], v[240:243], v[14:17]
	v_mfma_f32_16x16x32_bf16 v[10:13], v[178:181], v[240:243], v[10:13]
	v_mfma_f32_16x16x32_bf16 v[86:89], v[182:185], v[198:201], v[86:89]
	v_mfma_f32_16x16x32_bf16 v[74:77], v[190:193], v[198:201], v[74:77]
	v_mfma_f32_16x16x32_bf16 v[54:57], v[182:185], v[206:209], v[54:57]
	v_mfma_f32_16x16x32_bf16 v[50:53], v[190:193], v[206:209], v[50:53]
	v_mfma_f32_16x16x32_bf16 v[30:33], v[182:185], v[228:231], v[30:33]
	v_mfma_f32_16x16x32_bf16 v[18:21], v[190:193], v[228:231], v[18:21]
	v_mfma_f32_16x16x32_bf16 v[6:9], v[182:185], v[236:239], v[6:9]
	v_mfma_f32_16x16x32_bf16 v[2:5], v[190:193], v[236:239], v[2:5]
	v_mfma_f32_16x16x32_bf16 v[86:89], v[186:189], v[202:205], v[86:89]
	v_mfma_f32_16x16x32_bf16 v[74:77], v[194:197], v[202:205], v[74:77]
	v_mfma_f32_16x16x32_bf16 v[54:57], v[186:189], v[224:227], v[54:57]
	v_mfma_f32_16x16x32_bf16 v[50:53], v[194:197], v[224:227], v[50:53]
	v_mfma_f32_16x16x32_bf16 v[30:33], v[186:189], v[232:235], v[30:33]
	v_mfma_f32_16x16x32_bf16 v[18:21], v[194:197], v[232:235], v[18:21]
	v_mfma_f32_16x16x32_bf16 v[6:9], v[186:189], v[240:243], v[6:9]
	v_mfma_f32_16x16x32_bf16 v[2:5], v[194:197], v[240:243], v[2:5]
	s_setprio 0
	s_barrier
	s_add_i32 s17, s17, 2
	s_cmp_gt_u32 s17, 61
	s_mov_b64 s[38:39], s[40:41]
	s_cbranch_scc0 .LBB0_699
	s_and_b64 vcc, exec, s[28:29]
	s_cbranch_vccz .LBB0_702
	s_barrier

.LBB0_877:
	ds_read_b128 v[130:133], v220
	ds_read_b128 v[134:137], v220 offset:1024
	ds_read_b128 v[138:141], v220 offset:2048
	ds_read_b128 v[142:145], v220 offset:3072
	ds_read_b128 v[184:187], v224
	ds_read_b128 v[188:191], v224 offset:1024
	ds_read_b128 v[192:195], v224 offset:2048
	ds_read_b128 v[196:199], v224 offset:3072
	s_add_u32 s14, s36, 0xffea0080
	s_addc_u32 s15, s37, -1
	s_cmpk_eq_i32 s3, 0x54
	s_cselect_b32 s43, s29, s15
	s_cselect_b32 s42, s28, s14
	s_cselect_b32 s41, s9, s39
	s_cselect_b32 s40, s8, s38
	s_mov_b32 m0, s50
	v_lshl_add_u64 v[244:245], s[36:37], 0, v[178:179]
	ds_read_b128 v[200:203], v221
	ds_read_b128 v[204:207], v221 offset:1024
	ds_read_b128 v[208:211], v221 offset:2048
	ds_read_b128 v[212:215], v221 offset:3072
	ds_read_b128 v[228:231], v221 offset:4096
	ds_read_b128 v[232:235], v221 offset:5120
	ds_read_b128 v[236:239], v221 offset:6144
	ds_read_b128 v[240:243], v221 offset:7168
	global_load_lds_dwordx4 v[244:245], off
	v_lshl_add_u64 v[244:245], s[36:37], 0, v[180:181]
	s_mov_b32 m0, s51
	s_nop 0
	global_load_lds_dwordx4 v[244:245], off
	s_waitcnt vmcnt(8)
	s_waitcnt lgkmcnt(0)
	v_mfma_f32_16x16x32_bf16 v[30:33], v[130:133], v[200:203], v[30:33]
	v_mfma_f32_16x16x32_bf16 v[26:29], v[138:141], v[200:203], v[26:29]
	v_mfma_f32_16x16x32_bf16 v[46:49], v[130:133], v[208:211], v[46:49]
	v_mfma_f32_16x16x32_bf16 v[42:45], v[138:141], v[208:211], v[42:45]
	s_barrier
	s_setprio 1
	v_mfma_f32_16x16x32_bf16 v[62:65], v[130:133], v[228:231], v[62:65]
	v_mfma_f32_16x16x32_bf16 v[58:61], v[138:141], v[228:231], v[58:61]
	v_mfma_f32_16x16x32_bf16 v[94:97], v[130:133], v[236:239], v[94:97]
	v_mfma_f32_16x16x32_bf16 v[90:93], v[138:141], v[236:239], v[90:93]
	v_mfma_f32_16x16x32_bf16 v[30:33], v[134:137], v[204:207], v[30:33]
	v_mfma_f32_16x16x32_bf16 v[26:29], v[142:145], v[204:207], v[26:29]
	v_mfma_f32_16x16x32_bf16 v[46:49], v[134:137], v[212:215], v[46:49]
	v_mfma_f32_16x16x32_bf16 v[42:45], v[142:145], v[212:215], v[42:45]
	v_mfma_f32_16x16x32_bf16 v[62:65], v[134:137], v[232:235], v[62:65]
	v_mfma_f32_16x16x32_bf16 v[58:61], v[142:145], v[232:235], v[58:61]
	v_mfma_f32_16x16x32_bf16 v[94:97], v[134:137], v[240:243], v[94:97]
	v_mfma_f32_16x16x32_bf16 v[90:93], v[142:145], v[240:243], v[90:93]
	v_mfma_f32_16x16x32_bf16 v[2:5], v[184:187], v[200:203], v[2:5]
	v_mfma_f32_16x16x32_bf16 v[6:9], v[192:195], v[200:203], v[6:9]
	v_mfma_f32_16x16x32_bf16 v[10:13], v[184:187], v[208:211], v[10:13]
	v_mfma_f32_16x16x32_bf16 v[14:17], v[192:195], v[208:211], v[14:17]
	v_mfma_f32_16x16x32_bf16 v[18:21], v[184:187], v[228:231], v[18:21]
	v_mfma_f32_16x16x32_bf16 v[22:25], v[192:195], v[228:231], v[22:25]
	v_mfma_f32_16x16x32_bf16 v[34:37], v[184:187], v[236:239], v[34:37]
	v_mfma_f32_16x16x32_bf16 v[38:41], v[192:195], v[236:239], v[38:41]
	v_mfma_f32_16x16x32_bf16 v[2:5], v[188:191], v[204:207], v[2:5]
	v_mfma_f32_16x16x32_bf16 v[6:9], v[196:199], v[204:207], v[6:9]
	v_mfma_f32_16x16x32_bf16 v[10:13], v[188:191], v[212:215], v[10:13]
	v_mfma_f32_16x16x32_bf16 v[14:17], v[196:199], v[212:215], v[14:17]
	v_mfma_f32_16x16x32_bf16 v[18:21], v[188:191], v[232:235], v[18:21]
	v_mfma_f32_16x16x32_bf16 v[22:25], v[196:199], v[232:235], v[22:25]
	v_mfma_f32_16x16x32_bf16 v[34:37], v[188:191], v[240:243], v[34:37]
	v_mfma_f32_16x16x32_bf16 v[38:41], v[196:199], v[240:243], v[38:41]
	s_setprio 0
	s_barrier
	s_mov_b32 m0, s52
	v_lshl_add_u64 v[244:245], s[40:41], 0, v[150:151]
	s_add_u32 s14, s40, 0x160000
	ds_read_b128 v[200:203], v221 offset:16384
	ds_read_b128 v[204:207], v221 offset:17408
	ds_read_b128 v[208:211], v221 offset:18432
	ds_read_b128 v[212:215], v221 offset:19456
	ds_read_b128 v[228:231], v221 offset:20480
	ds_read_b128 v[232:235], v221 offset:21504
	ds_read_b128 v[236:239], v221 offset:22528
	ds_read_b128 v[240:243], v221 offset:23552
	global_load_lds_dwordx4 v[244:245], off
	v_lshl_add_u64 v[246:247], s[40:41], 0, v[146:147]
	s_mov_b32 m0, s53
	s_addc_u32 s15, s41, 0
	global_load_lds_dwordx4 v[246:247], off
	v_lshl_add_u64 v[248:249], s[14:15], 0, v[150:151]
	s_mov_b32 m0, s54
	v_lshl_add_u64 v[250:251], s[42:43], 0, v[148:149]
	global_load_lds_dwordx4 v[248:249], off
	v_lshl_add_u64 v[248:249], s[14:15], 0, v[146:147]
	s_mov_b32 m0, s55
	s_nop 0
	global_load_lds_dwordx4 v[248:249], off
	v_lshl_add_u64 v[248:249], s[42:43], 0, v[152:153]
	s_mov_b32 m0, s61
	s_nop 0
	global_load_lds_dwordx4 v[248:249], off
	s_mov_b32 m0, s62
	s_nop 0
	global_load_lds_dwordx4 v[250:251], off
	s_waitcnt vmcnt(8)
	s_waitcnt lgkmcnt(0)
	v_mfma_f32_16x16x32_bf16 v[114:117], v[130:133], v[200:203], v[114:117]
	v_mfma_f32_16x16x32_bf16 v[110:113], v[138:141], v[200:203], v[110:113]
	v_mfma_f32_16x16x32_bf16 v[126:129], v[130:133], v[208:211], v[126:129]
	v_mfma_f32_16x16x32_bf16 v[122:125], v[138:141], v[208:211], v[122:125]
	s_barrier
	s_setprio 1
	v_mfma_f32_16x16x32_bf16 v[118:121], v[130:133], v[228:231], v[118:121]
	v_mfma_f32_16x16x32_bf16 v[106:109], v[138:141], v[228:231], v[106:109]
	v_mfma_f32_16x16x32_bf16 v[78:81], v[130:133], v[236:239], v[78:81]
	v_mfma_f32_16x16x32_bf16 v[74:77], v[138:141], v[236:239], v[74:77]
	v_mfma_f32_16x16x32_bf16 v[114:117], v[134:137], v[204:207], v[114:117]
	v_mfma_f32_16x16x32_bf16 v[110:113], v[142:145], v[204:207], v[110:113]
	v_mfma_f32_16x16x32_bf16 v[126:129], v[134:137], v[212:215], v[126:129]
	v_mfma_f32_16x16x32_bf16 v[122:125], v[142:145], v[212:215], v[122:125]
	v_mfma_f32_16x16x32_bf16 v[118:121], v[134:137], v[232:235], v[118:121]
	v_mfma_f32_16x16x32_bf16 v[106:109], v[142:145], v[232:235], v[106:109]
	v_mfma_f32_16x16x32_bf16 v[78:81], v[134:137], v[240:243], v[78:81]
	v_mfma_f32_16x16x32_bf16 v[74:77], v[142:145], v[240:243], v[74:77]
	v_mfma_f32_16x16x32_bf16 v[50:53], v[184:187], v[200:203], v[50:53]
	v_mfma_f32_16x16x32_bf16 v[54:57], v[192:195], v[200:203], v[54:57]
	v_mfma_f32_16x16x32_bf16 v[82:85], v[184:187], v[208:211], v[82:85]
	v_mfma_f32_16x16x32_bf16 v[86:89], v[192:195], v[208:211], v[86:89]
	v_mfma_f32_16x16x32_bf16 v[102:105], v[184:187], v[228:231], v[102:105]
	v_mfma_f32_16x16x32_bf16 v[98:101], v[192:195], v[228:231], v[98:101]
	v_mfma_f32_16x16x32_bf16 v[70:73], v[184:187], v[236:239], v[70:73]
	v_mfma_f32_16x16x32_bf16 v[66:69], v[192:195], v[236:239], v[66:69]
	v_mfma_f32_16x16x32_bf16 v[50:53], v[188:191], v[204:207], v[50:53]
	v_mfma_f32_16x16x32_bf16 v[54:57], v[196:199], v[204:207], v[54:57]
	v_mfma_f32_16x16x32_bf16 v[82:85], v[188:191], v[212:215], v[82:85]
	v_mfma_f32_16x16x32_bf16 v[86:89], v[196:199], v[212:215], v[86:89]
	v_mfma_f32_16x16x32_bf16 v[102:105], v[188:191], v[232:235], v[102:105]
	v_mfma_f32_16x16x32_bf16 v[98:101], v[196:199], v[232:235], v[98:101]
	v_mfma_f32_16x16x32_bf16 v[70:73], v[188:191], v[240:243], v[70:73]
	v_mfma_f32_16x16x32_bf16 v[66:69], v[196:199], v[240:243], v[66:69]
	s_setprio 0
	s_barrier
	v_add_u32_e32 v196, s74, v218
	ds_read_b128 v[130:133], v225
	ds_read_b128 v[134:137], v225 offset:1024
	ds_read_b128 v[138:141], v225 offset:2048
	ds_read_b128 v[142:145], v225 offset:3072
	ds_read_b128 v[184:187], v196
	ds_read_b128 v[188:191], v196 offset:1024
	ds_read_b128 v[192:195], v196 offset:2048
	ds_read_b128 v[196:199], v196 offset:3072
	s_add_u32 s14, s42, 0x160000
	s_addc_u32 s15, s43, 0
	s_mov_b32 m0, s63
	v_lshl_add_u64 v[252:253], s[14:15], 0, v[152:153]
	ds_read_b128 v[200:203], v221 offset:32768
	ds_read_b128 v[204:207], v221 offset:33792
	ds_read_b128 v[208:211], v221 offset:34816
	ds_read_b128 v[212:215], v221 offset:35840
	ds_read_b128 v[228:231], v221 offset:36864
	ds_read_b128 v[232:235], v221 offset:37888
	ds_read_b128 v[236:239], v221 offset:38912
	ds_read_b128 v[240:243], v221 offset:39936
	global_load_lds_dwordx4 v[252:253], off
	v_lshl_add_u64 v[252:253], s[14:15], 0, v[148:149]
	s_mov_b32 m0, s64
	s_nop 0
	global_load_lds_dwordx4 v[252:253], off
	s_waitcnt vmcnt(8)
	s_waitcnt lgkmcnt(0)
	v_mfma_f32_16x16x32_bf16 v[30:33], v[130:133], v[200:203], v[30:33]
	v_mfma_f32_16x16x32_bf16 v[26:29], v[138:141], v[200:203], v[26:29]
	v_mfma_f32_16x16x32_bf16 v[46:49], v[130:133], v[208:211], v[46:49]
	v_mfma_f32_16x16x32_bf16 v[42:45], v[138:141], v[208:211], v[42:45]
	s_barrier
	s_setprio 1
	v_mfma_f32_16x16x32_bf16 v[62:65], v[130:133], v[228:231], v[62:65]
	v_mfma_f32_16x16x32_bf16 v[58:61], v[138:141], v[228:231], v[58:61]
	v_mfma_f32_16x16x32_bf16 v[94:97], v[130:133], v[236:239], v[94:97]
	v_mfma_f32_16x16x32_bf16 v[90:93], v[138:141], v[236:239], v[90:93]
	v_mfma_f32_16x16x32_bf16 v[30:33], v[134:137], v[204:207], v[30:33]
	v_mfma_f32_16x16x32_bf16 v[26:29], v[142:145], v[204:207], v[26:29]
	v_mfma_f32_16x16x32_bf16 v[46:49], v[134:137], v[212:215], v[46:49]
	v_mfma_f32_16x16x32_bf16 v[42:45], v[142:145], v[212:215], v[42:45]
	v_mfma_f32_16x16x32_bf16 v[62:65], v[134:137], v[232:235], v[62:65]
	v_mfma_f32_16x16x32_bf16 v[58:61], v[142:145], v[232:235], v[58:61]
	v_mfma_f32_16x16x32_bf16 v[94:97], v[134:137], v[240:243], v[94:97]
	v_mfma_f32_16x16x32_bf16 v[90:93], v[142:145], v[240:243], v[90:93]
	v_mfma_f32_16x16x32_bf16 v[2:5], v[184:187], v[200:203], v[2:5]
	v_mfma_f32_16x16x32_bf16 v[6:9], v[192:195], v[200:203], v[6:9]
	v_mfma_f32_16x16x32_bf16 v[10:13], v[184:187], v[208:211], v[10:13]
	v_mfma_f32_16x16x32_bf16 v[14:17], v[192:195], v[208:211], v[14:17]
	v_mfma_f32_16x16x32_bf16 v[18:21], v[184:187], v[228:231], v[18:21]
	v_mfma_f32_16x16x32_bf16 v[22:25], v[192:195], v[228:231], v[22:25]
	v_mfma_f32_16x16x32_bf16 v[34:37], v[184:187], v[236:239], v[34:37]
	v_mfma_f32_16x16x32_bf16 v[38:41], v[192:195], v[236:239], v[38:41]
	v_mfma_f32_16x16x32_bf16 v[2:5], v[188:191], v[204:207], v[2:5]
	v_mfma_f32_16x16x32_bf16 v[6:9], v[196:199], v[204:207], v[6:9]
	v_mfma_f32_16x16x32_bf16 v[10:13], v[188:191], v[212:215], v[10:13]
	v_mfma_f32_16x16x32_bf16 v[14:17], v[196:199], v[212:215], v[14:17]
	v_mfma_f32_16x16x32_bf16 v[18:21], v[188:191], v[232:235], v[18:21]
	v_mfma_f32_16x16x32_bf16 v[22:25], v[196:199], v[232:235], v[22:25]
	v_mfma_f32_16x16x32_bf16 v[34:37], v[188:191], v[240:243], v[34:37]
	v_mfma_f32_16x16x32_bf16 v[38:41], v[196:199], v[240:243], v[38:41]
	s_setprio 0
	s_barrier
	s_mov_b32 m0, s75
	v_lshl_add_u64 v[244:245], v[244:245], 0, s[22:23]
	s_add_u32 s14, s40, 0x160080
	ds_read_b128 v[200:203], v221 offset:49152
	ds_read_b128 v[204:207], v221 offset:50176
	ds_read_b128 v[208:211], v221 offset:51200
	ds_read_b128 v[212:215], v221 offset:52224
	ds_read_b128 v[228:231], v221 offset:53248
	ds_read_b128 v[232:235], v221 offset:54272
	ds_read_b128 v[236:239], v221 offset:55296
	ds_read_b128 v[240:243], v221 offset:56320
	global_load_lds_dwordx4 v[244:245], off
	v_lshl_add_u64 v[244:245], v[246:247], 0, s[22:23]
	s_mov_b32 m0, s76
	s_addc_u32 s15, s41, 0
	global_load_lds_dwordx4 v[244:245], off
	v_lshl_add_u64 v[244:245], s[14:15], 0, v[150:151]
	s_mov_b32 m0, s77
	s_nop 0
	global_load_lds_dwordx4 v[244:245], off
	v_lshl_add_u64 v[244:245], s[14:15], 0, v[146:147]
	s_mov_b32 m0, s78
	s_nop 0
	global_load_lds_dwordx4 v[244:245], off
	v_lshl_add_u64 v[244:245], v[248:249], 0, s[22:23]
	s_mov_b32 m0, s68
	s_nop 0
	global_load_lds_dwordx4 v[244:245], off
	v_lshl_add_u64 v[244:245], v[250:251], 0, s[22:23]
	s_mov_b32 m0, s69
	s_nop 0
	global_load_lds_dwordx4 v[244:245], off
	s_waitcnt vmcnt(8)
	s_waitcnt lgkmcnt(0)
	v_mfma_f32_16x16x32_bf16 v[114:117], v[130:133], v[200:203], v[114:117]
	v_mfma_f32_16x16x32_bf16 v[110:113], v[138:141], v[200:203], v[110:113]
	v_mfma_f32_16x16x32_bf16 v[126:129], v[130:133], v[208:211], v[126:129]
	v_mfma_f32_16x16x32_bf16 v[122:125], v[138:141], v[208:211], v[122:125]
	s_barrier
	s_setprio 1
	v_mfma_f32_16x16x32_bf16 v[118:121], v[130:133], v[228:231], v[118:121]
	v_mfma_f32_16x16x32_bf16 v[106:109], v[138:141], v[228:231], v[106:109]
	v_mfma_f32_16x16x32_bf16 v[78:81], v[130:133], v[236:239], v[78:81]
	v_mfma_f32_16x16x32_bf16 v[74:77], v[138:141], v[236:239], v[74:77]
	v_mfma_f32_16x16x32_bf16 v[114:117], v[134:137], v[204:207], v[114:117]
	v_mfma_f32_16x16x32_bf16 v[110:113], v[142:145], v[204:207], v[110:113]
	v_mfma_f32_16x16x32_bf16 v[126:129], v[134:137], v[212:215], v[126:129]
	v_mfma_f32_16x16x32_bf16 v[122:125], v[142:145], v[212:215], v[122:125]
	v_mfma_f32_16x16x32_bf16 v[118:121], v[134:137], v[232:235], v[118:121]
	v_mfma_f32_16x16x32_bf16 v[106:109], v[142:145], v[232:235], v[106:109]
	v_mfma_f32_16x16x32_bf16 v[78:81], v[134:137], v[240:243], v[78:81]
	v_mfma_f32_16x16x32_bf16 v[74:77], v[142:145], v[240:243], v[74:77]
	v_mfma_f32_16x16x32_bf16 v[50:53], v[184:187], v[200:203], v[50:53]
	v_mfma_f32_16x16x32_bf16 v[54:57], v[192:195], v[200:203], v[54:57]
	v_mfma_f32_16x16x32_bf16 v[82:85], v[184:187], v[208:211], v[82:85]
	v_mfma_f32_16x16x32_bf16 v[86:89], v[192:195], v[208:211], v[86:89]
	v_mfma_f32_16x16x32_bf16 v[102:105], v[184:187], v[228:231], v[102:105]
	v_mfma_f32_16x16x32_bf16 v[98:101], v[192:195], v[228:231], v[98:101]
	v_mfma_f32_16x16x32_bf16 v[70:73], v[184:187], v[236:239], v[70:73]
	v_mfma_f32_16x16x32_bf16 v[66:69], v[192:195], v[236:239], v[66:69]
	v_mfma_f32_16x16x32_bf16 v[50:53], v[188:191], v[204:207], v[50:53]
	v_mfma_f32_16x16x32_bf16 v[54:57], v[196:199], v[204:207], v[54:57]
	v_mfma_f32_16x16x32_bf16 v[82:85], v[188:191], v[212:215], v[82:85]
	v_mfma_f32_16x16x32_bf16 v[86:89], v[196:199], v[212:215], v[86:89]
	v_mfma_f32_16x16x32_bf16 v[102:105], v[188:191], v[232:235], v[102:105]
	v_mfma_f32_16x16x32_bf16 v[98:101], v[196:199], v[232:235], v[98:101]
	v_mfma_f32_16x16x32_bf16 v[70:73], v[188:191], v[240:243], v[70:73]
	v_mfma_f32_16x16x32_bf16 v[66:69], v[196:199], v[240:243], v[66:69]
	s_setprio 0
	s_barrier
	s_add_i32 s3, s3, 2
	s_add_u32 s36, s36, 0x100
	s_addc_u32 s37, s37, 0
	s_add_u32 s38, s38, 0x100
	s_addc_u32 s39, s39, 0
	s_cmpk_gt_u32 s3, 0x55
	s_cbranch_scc0 .LBB0_877
	s_and_b64 vcc, exec, s[24:25]
	s_cbranch_vccz .LBB0_880
	s_barrier

.LBB0_986:
	ds_read_b128 v[130:133], v172
	ds_read_b128 v[134:137], v172 offset:1024
	ds_read_b128 v[138:141], v172 offset:2048
	ds_read_b128 v[142:145], v172 offset:3072
	ds_read_b128 v[166:169], v173
	ds_read_b128 v[176:179], v173 offset:1024
	ds_read_b128 v[180:183], v173 offset:2048
	ds_read_b128 v[184:187], v173 offset:3072
	s_add_u32 s20, s52, 0xfff80080
	s_addc_u32 s21, s53, -1
	s_cmp_eq_u32 s19, 28
	s_cselect_b32 s57, s3, s21
	s_cselect_b32 s56, s14, s20
	s_cselect_b32 s55, s15, s18
	s_cselect_b32 s54, s16, s17
	v_lshl_add_u64 v[220:221], s[52:53], 0, v[156:157]
	s_add_i32 m0, s65, 0xc000
	ds_read_b128 v[188:191], v174
	ds_read_b128 v[192:195], v174 offset:1024
	ds_read_b128 v[196:199], v174 offset:2048
	ds_read_b128 v[200:203], v174 offset:3072
	ds_read_b128 v[204:207], v174 offset:4096
	ds_read_b128 v[208:211], v174 offset:5120
	ds_read_b128 v[212:215], v174 offset:6144
	ds_read_b128 v[216:219], v174 offset:7168
	global_load_lds_dwordx4 v[220:221], off
	v_lshl_add_u64 v[220:221], s[52:53], 0, v[158:159]
	s_add_i32 m0, s65, 0xe000
	s_nop 0
	global_load_lds_dwordx4 v[220:221], off
	s_waitcnt vmcnt(8)
	s_waitcnt lgkmcnt(0)
	v_mfma_f32_16x16x32_bf16 v[126:129], v[130:133], v[188:191], v[126:129]
	v_mfma_f32_16x16x32_bf16 v[122:125], v[138:141], v[188:191], v[122:125]
	v_mfma_f32_16x16x32_bf16 v[110:113], v[130:133], v[196:199], v[110:113]
	v_mfma_f32_16x16x32_bf16 v[106:109], v[138:141], v[196:199], v[106:109]
	s_barrier
	s_setprio 1
	v_mfma_f32_16x16x32_bf16 v[94:97], v[130:133], v[204:207], v[94:97]
	v_mfma_f32_16x16x32_bf16 v[90:93], v[138:141], v[204:207], v[90:93]
	v_mfma_f32_16x16x32_bf16 v[78:81], v[130:133], v[212:215], v[78:81]
	v_mfma_f32_16x16x32_bf16 v[74:77], v[138:141], v[212:215], v[74:77]
	v_mfma_f32_16x16x32_bf16 v[126:129], v[134:137], v[192:195], v[126:129]
	v_mfma_f32_16x16x32_bf16 v[122:125], v[142:145], v[192:195], v[122:125]
	v_mfma_f32_16x16x32_bf16 v[110:113], v[134:137], v[200:203], v[110:113]
	v_mfma_f32_16x16x32_bf16 v[106:109], v[142:145], v[200:203], v[106:109]
	v_mfma_f32_16x16x32_bf16 v[94:97], v[134:137], v[208:211], v[94:97]
	v_mfma_f32_16x16x32_bf16 v[90:93], v[142:145], v[208:211], v[90:93]
	v_mfma_f32_16x16x32_bf16 v[78:81], v[134:137], v[216:219], v[78:81]
	v_mfma_f32_16x16x32_bf16 v[74:77], v[142:145], v[216:219], v[74:77]
	v_mfma_f32_16x16x32_bf16 v[118:121], v[166:169], v[188:191], v[118:121]
	v_mfma_f32_16x16x32_bf16 v[114:117], v[180:183], v[188:191], v[114:117]
	v_mfma_f32_16x16x32_bf16 v[102:105], v[166:169], v[196:199], v[102:105]
	v_mfma_f32_16x16x32_bf16 v[98:101], v[180:183], v[196:199], v[98:101]
	v_mfma_f32_16x16x32_bf16 v[86:89], v[166:169], v[204:207], v[86:89]
	v_mfma_f32_16x16x32_bf16 v[82:85], v[180:183], v[204:207], v[82:85]
	v_mfma_f32_16x16x32_bf16 v[70:73], v[166:169], v[212:215], v[70:73]
	v_mfma_f32_16x16x32_bf16 v[66:69], v[180:183], v[212:215], v[66:69]
	v_mfma_f32_16x16x32_bf16 v[118:121], v[176:179], v[192:195], v[118:121]
	v_mfma_f32_16x16x32_bf16 v[114:117], v[184:187], v[192:195], v[114:117]
	v_mfma_f32_16x16x32_bf16 v[102:105], v[176:179], v[200:203], v[102:105]
	v_mfma_f32_16x16x32_bf16 v[98:101], v[184:187], v[200:203], v[98:101]
	v_mfma_f32_16x16x32_bf16 v[86:89], v[176:179], v[208:211], v[86:89]
	v_mfma_f32_16x16x32_bf16 v[82:85], v[184:187], v[208:211], v[82:85]
	v_mfma_f32_16x16x32_bf16 v[70:73], v[176:179], v[216:219], v[70:73]
	v_mfma_f32_16x16x32_bf16 v[66:69], v[184:187], v[216:219], v[66:69]
	s_setprio 0
	s_barrier
	s_add_i32 s20, s77, s64
	v_lshl_add_u64 v[220:221], s[54:55], 0, v[146:147]
	s_mov_b32 m0, s20
	ds_read_b128 v[188:191], v174 offset:16384
	ds_read_b128 v[192:195], v174 offset:17408
	ds_read_b128 v[196:199], v174 offset:18432
	ds_read_b128 v[200:203], v174 offset:19456
	ds_read_b128 v[204:207], v174 offset:20480
	ds_read_b128 v[208:211], v174 offset:21504
	ds_read_b128 v[212:215], v174 offset:22528
	ds_read_b128 v[216:219], v174 offset:23552
	global_load_lds_dwordx4 v[220:221], off
	s_add_i32 m0, s20, 0x2000
	s_add_u32 s20, s54, 0x80000
	v_lshl_add_u64 v[222:223], s[54:55], 0, v[148:149]
	s_addc_u32 s21, s55, 0
	s_add_i32 s43, s78, s64
	global_load_lds_dwordx4 v[222:223], off
	v_lshl_add_u64 v[224:225], s[20:21], 0, v[146:147]
	s_mov_b32 m0, s43
	v_lshl_add_u64 v[226:227], s[56:57], 0, v[148:149]
	global_load_lds_dwordx4 v[224:225], off
	v_lshl_add_u64 v[224:225], s[20:21], 0, v[148:149]
	s_add_i32 m0, s43, 0x2000
	s_nop 0
	global_load_lds_dwordx4 v[224:225], off
	v_lshl_add_u64 v[224:225], s[56:57], 0, v[146:147]
	s_mov_b32 m0, s65
	s_nop 0
	global_load_lds_dwordx4 v[224:225], off
	s_mov_b32 m0, s66
	s_nop 0
	global_load_lds_dwordx4 v[226:227], off
	s_waitcnt vmcnt(8)
	s_waitcnt lgkmcnt(0)
	v_mfma_f32_16x16x32_bf16 v[62:65], v[130:133], v[188:191], v[62:65]
	v_mfma_f32_16x16x32_bf16 v[58:61], v[138:141], v[188:191], v[58:61]
	v_mfma_f32_16x16x32_bf16 v[46:49], v[130:133], v[196:199], v[46:49]
	v_mfma_f32_16x16x32_bf16 v[42:45], v[138:141], v[196:199], v[42:45]
	s_barrier
	s_setprio 1
	v_mfma_f32_16x16x32_bf16 v[30:33], v[130:133], v[204:207], v[30:33]
	v_mfma_f32_16x16x32_bf16 v[26:29], v[138:141], v[204:207], v[26:29]
	v_mfma_f32_16x16x32_bf16 v[14:17], v[130:133], v[212:215], v[14:17]
	v_mfma_f32_16x16x32_bf16 v[10:13], v[138:141], v[212:215], v[10:13]
	v_mfma_f32_16x16x32_bf16 v[62:65], v[134:137], v[192:195], v[62:65]
	v_mfma_f32_16x16x32_bf16 v[58:61], v[142:145], v[192:195], v[58:61]
	v_mfma_f32_16x16x32_bf16 v[46:49], v[134:137], v[200:203], v[46:49]
	v_mfma_f32_16x16x32_bf16 v[42:45], v[142:145], v[200:203], v[42:45]
	v_mfma_f32_16x16x32_bf16 v[30:33], v[134:137], v[208:211], v[30:33]
	v_mfma_f32_16x16x32_bf16 v[26:29], v[142:145], v[208:211], v[26:29]
	v_mfma_f32_16x16x32_bf16 v[14:17], v[134:137], v[216:219], v[14:17]
	v_mfma_f32_16x16x32_bf16 v[10:13], v[142:145], v[216:219], v[10:13]
	v_mfma_f32_16x16x32_bf16 v[54:57], v[166:169], v[188:191], v[54:57]
	v_mfma_f32_16x16x32_bf16 v[50:53], v[180:183], v[188:191], v[50:53]
	v_mfma_f32_16x16x32_bf16 v[38:41], v[166:169], v[196:199], v[38:41]
	v_mfma_f32_16x16x32_bf16 v[34:37], v[180:183], v[196:199], v[34:37]
	v_mfma_f32_16x16x32_bf16 v[22:25], v[166:169], v[204:207], v[22:25]
	v_mfma_f32_16x16x32_bf16 v[18:21], v[180:183], v[204:207], v[18:21]
	v_mfma_f32_16x16x32_bf16 v[6:9], v[166:169], v[212:215], v[6:9]
	v_mfma_f32_16x16x32_bf16 v[2:5], v[180:183], v[212:215], v[2:5]
	v_mfma_f32_16x16x32_bf16 v[54:57], v[176:179], v[192:195], v[54:57]
	v_mfma_f32_16x16x32_bf16 v[50:53], v[184:187], v[192:195], v[50:53]
	v_mfma_f32_16x16x32_bf16 v[38:41], v[176:179], v[200:203], v[38:41]
	v_mfma_f32_16x16x32_bf16 v[34:37], v[184:187], v[200:203], v[34:37]
	v_mfma_f32_16x16x32_bf16 v[22:25], v[176:179], v[208:211], v[22:25]
	v_mfma_f32_16x16x32_bf16 v[18:21], v[184:187], v[208:211], v[18:21]
	v_mfma_f32_16x16x32_bf16 v[6:9], v[176:179], v[216:219], v[6:9]
	v_mfma_f32_16x16x32_bf16 v[2:5], v[184:187], v[216:219], v[2:5]
	s_setprio 0
	s_barrier
	s_add_i32 s43, 0, 0x18000
	s_add_i32 s45, 0, 0x1c000
	v_add_u32_e32 v142, s43, v170
	v_add_u32_e32 v184, s45, v170
	ds_read_b128 v[130:133], v142
	ds_read_b128 v[134:137], v142 offset:1024
	ds_read_b128 v[138:141], v142 offset:2048
	ds_read_b128 v[142:145], v142 offset:3072
	ds_read_b128 v[166:169], v184
	ds_read_b128 v[176:179], v184 offset:1024
	ds_read_b128 v[180:183], v184 offset:2048
	ds_read_b128 v[184:187], v184 offset:3072
	s_add_u32 s20, s56, 0x80000
	s_addc_u32 s21, s57, 0
	s_mov_b32 m0, s67
	v_lshl_add_u64 v[228:229], s[20:21], 0, v[146:147]
	ds_read_b128 v[188:191], v174 offset:32768
	ds_read_b128 v[192:195], v174 offset:33792
	ds_read_b128 v[196:199], v174 offset:34816
	ds_read_b128 v[200:203], v174 offset:35840
	ds_read_b128 v[204:207], v174 offset:36864
	ds_read_b128 v[208:211], v174 offset:37888
	ds_read_b128 v[212:215], v174 offset:38912
	ds_read_b128 v[216:219], v174 offset:39936
	global_load_lds_dwordx4 v[228:229], off
	v_lshl_add_u64 v[228:229], s[20:21], 0, v[148:149]
	s_mov_b32 m0, s68
	s_nop 0
	global_load_lds_dwordx4 v[228:229], off
	s_waitcnt vmcnt(8)
	s_waitcnt lgkmcnt(0)
	v_mfma_f32_16x16x32_bf16 v[126:129], v[130:133], v[188:191], v[126:129]
	v_mfma_f32_16x16x32_bf16 v[122:125], v[138:141], v[188:191], v[122:125]
	v_mfma_f32_16x16x32_bf16 v[110:113], v[130:133], v[196:199], v[110:113]
	v_mfma_f32_16x16x32_bf16 v[106:109], v[138:141], v[196:199], v[106:109]
	s_barrier
	s_setprio 1
	v_mfma_f32_16x16x32_bf16 v[94:97], v[130:133], v[204:207], v[94:97]
	v_mfma_f32_16x16x32_bf16 v[90:93], v[138:141], v[204:207], v[90:93]
	v_mfma_f32_16x16x32_bf16 v[78:81], v[130:133], v[212:215], v[78:81]
	v_mfma_f32_16x16x32_bf16 v[74:77], v[138:141], v[212:215], v[74:77]
	v_mfma_f32_16x16x32_bf16 v[126:129], v[134:137], v[192:195], v[126:129]
	v_mfma_f32_16x16x32_bf16 v[122:125], v[142:145], v[192:195], v[122:125]
	v_mfma_f32_16x16x32_bf16 v[110:113], v[134:137], v[200:203], v[110:113]
	v_mfma_f32_16x16x32_bf16 v[106:109], v[142:145], v[200:203], v[106:109]
	v_mfma_f32_16x16x32_bf16 v[94:97], v[134:137], v[208:211], v[94:97]
	v_mfma_f32_16x16x32_bf16 v[90:93], v[142:145], v[208:211], v[90:93]
	v_mfma_f32_16x16x32_bf16 v[78:81], v[134:137], v[216:219], v[78:81]
	v_mfma_f32_16x16x32_bf16 v[74:77], v[142:145], v[216:219], v[74:77]
	v_mfma_f32_16x16x32_bf16 v[118:121], v[166:169], v[188:191], v[118:121]
	v_mfma_f32_16x16x32_bf16 v[114:117], v[180:183], v[188:191], v[114:117]
	v_mfma_f32_16x16x32_bf16 v[102:105], v[166:169], v[196:199], v[102:105]
	v_mfma_f32_16x16x32_bf16 v[98:101], v[180:183], v[196:199], v[98:101]
	v_mfma_f32_16x16x32_bf16 v[86:89], v[166:169], v[204:207], v[86:89]
	v_mfma_f32_16x16x32_bf16 v[82:85], v[180:183], v[204:207], v[82:85]
	v_mfma_f32_16x16x32_bf16 v[70:73], v[166:169], v[212:215], v[70:73]
	v_mfma_f32_16x16x32_bf16 v[66:69], v[180:183], v[212:215], v[66:69]
	v_mfma_f32_16x16x32_bf16 v[118:121], v[176:179], v[192:195], v[118:121]
	v_mfma_f32_16x16x32_bf16 v[114:117], v[184:187], v[192:195], v[114:117]
	v_mfma_f32_16x16x32_bf16 v[102:105], v[176:179], v[200:203], v[102:105]
	v_mfma_f32_16x16x32_bf16 v[98:101], v[184:187], v[200:203], v[98:101]
	v_mfma_f32_16x16x32_bf16 v[86:89], v[176:179], v[208:211], v[86:89]
	v_mfma_f32_16x16x32_bf16 v[82:85], v[184:187], v[208:211], v[82:85]
	v_mfma_f32_16x16x32_bf16 v[70:73], v[176:179], v[216:219], v[70:73]
	v_mfma_f32_16x16x32_bf16 v[66:69], v[184:187], v[216:219], v[66:69]
	s_setprio 0
	s_barrier
	s_add_i32 s20, s43, s64
	v_lshl_add_u64 v[220:221], v[220:221], 0, s[26:27]
	s_mov_b32 m0, s20
	ds_read_b128 v[188:191], v174 offset:49152
	ds_read_b128 v[192:195], v174 offset:50176
	ds_read_b128 v[196:199], v174 offset:51200
	ds_read_b128 v[200:203], v174 offset:52224
	ds_read_b128 v[204:207], v174 offset:53248
	ds_read_b128 v[208:211], v174 offset:54272
	ds_read_b128 v[212:215], v174 offset:55296
	ds_read_b128 v[216:219], v174 offset:56320
	global_load_lds_dwordx4 v[220:221], off
	s_add_i32 m0, s20, 0x2000
	s_add_u32 s20, s54, 0x80080
	v_lshl_add_u64 v[220:221], v[222:223], 0, s[26:27]
	s_addc_u32 s21, s55, 0
	s_add_i32 s43, s45, s64
	global_load_lds_dwordx4 v[220:221], off
	v_lshl_add_u64 v[220:221], s[20:21], 0, v[146:147]
	s_mov_b32 m0, s43
	s_nop 0
	global_load_lds_dwordx4 v[220:221], off
	v_lshl_add_u64 v[220:221], s[20:21], 0, v[148:149]
	s_add_i32 m0, s43, 0x2000
	s_nop 0
	global_load_lds_dwordx4 v[220:221], off
	v_lshl_add_u64 v[220:221], v[224:225], 0, s[26:27]
	s_mov_b32 m0, s73
	s_nop 0
	global_load_lds_dwordx4 v[220:221], off
	v_lshl_add_u64 v[220:221], v[226:227], 0, s[26:27]
	s_mov_b32 m0, s74
	s_nop 0
	global_load_lds_dwordx4 v[220:221], off
	s_waitcnt vmcnt(8)
	s_waitcnt lgkmcnt(0)
	v_mfma_f32_16x16x32_bf16 v[62:65], v[130:133], v[188:191], v[62:65]
	v_mfma_f32_16x16x32_bf16 v[58:61], v[138:141], v[188:191], v[58:61]
	v_mfma_f32_16x16x32_bf16 v[46:49], v[130:133], v[196:199], v[46:49]
	v_mfma_f32_16x16x32_bf16 v[42:45], v[138:141], v[196:199], v[42:45]
	s_barrier
	s_setprio 1
	v_mfma_f32_16x16x32_bf16 v[30:33], v[130:133], v[204:207], v[30:33]
	v_mfma_f32_16x16x32_bf16 v[26:29], v[138:141], v[204:207], v[26:29]
	v_mfma_f32_16x16x32_bf16 v[14:17], v[130:133], v[212:215], v[14:17]
	v_mfma_f32_16x16x32_bf16 v[10:13], v[138:141], v[212:215], v[10:13]
	v_mfma_f32_16x16x32_bf16 v[62:65], v[134:137], v[192:195], v[62:65]
	v_mfma_f32_16x16x32_bf16 v[58:61], v[142:145], v[192:195], v[58:61]
	v_mfma_f32_16x16x32_bf16 v[46:49], v[134:137], v[200:203], v[46:49]
	v_mfma_f32_16x16x32_bf16 v[42:45], v[142:145], v[200:203], v[42:45]
	v_mfma_f32_16x16x32_bf16 v[30:33], v[134:137], v[208:211], v[30:33]
	v_mfma_f32_16x16x32_bf16 v[26:29], v[142:145], v[208:211], v[26:29]
	v_mfma_f32_16x16x32_bf16 v[14:17], v[134:137], v[216:219], v[14:17]
	v_mfma_f32_16x16x32_bf16 v[10:13], v[142:145], v[216:219], v[10:13]
	v_mfma_f32_16x16x32_bf16 v[54:57], v[166:169], v[188:191], v[54:57]
	v_mfma_f32_16x16x32_bf16 v[50:53], v[180:183], v[188:191], v[50:53]
	v_mfma_f32_16x16x32_bf16 v[38:41], v[166:169], v[196:199], v[38:41]
	v_mfma_f32_16x16x32_bf16 v[34:37], v[180:183], v[196:199], v[34:37]
	v_mfma_f32_16x16x32_bf16 v[22:25], v[166:169], v[204:207], v[22:25]
	v_mfma_f32_16x16x32_bf16 v[18:21], v[180:183], v[204:207], v[18:21]
	v_mfma_f32_16x16x32_bf16 v[6:9], v[166:169], v[212:215], v[6:9]
	v_mfma_f32_16x16x32_bf16 v[2:5], v[180:183], v[212:215], v[2:5]
	v_mfma_f32_16x16x32_bf16 v[54:57], v[176:179], v[192:195], v[54:57]
	v_mfma_f32_16x16x32_bf16 v[50:53], v[184:187], v[192:195], v[50:53]
	v_mfma_f32_16x16x32_bf16 v[38:41], v[176:179], v[200:203], v[38:41]
	v_mfma_f32_16x16x32_bf16 v[34:37], v[184:187], v[200:203], v[34:37]
	v_mfma_f32_16x16x32_bf16 v[22:25], v[176:179], v[208:211], v[22:25]
	v_mfma_f32_16x16x32_bf16 v[18:21], v[184:187], v[208:211], v[18:21]
	v_mfma_f32_16x16x32_bf16 v[6:9], v[176:179], v[216:219], v[6:9]
	v_mfma_f32_16x16x32_bf16 v[2:5], v[184:187], v[216:219], v[2:5]
	s_setprio 0
	s_barrier
	s_add_i32 s19, s19, 2
	s_add_u32 s52, s52, 0x100
	s_addc_u32 s53, s53, 0
	s_add_u32 s17, s17, 0x100
	s_addc_u32 s18, s18, 0
	s_cmp_gt_u32 s19, 29
	s_cbranch_scc0 .LBB0_986
	s_and_b64 vcc, exec, s[28:29]
	s_cbranch_vccnz .LBB0_991
	v_lshl_add_u32 v166, s50, 8, v163
	s_cmp_gt_i32 s10, 1
	s_mov_b64 s[50:51], -1
	s_cbranch_scc1 .LBB0_992

.LBB0_1213:
	ds_read_b128 v[130:133], v189
	ds_read_b128 v[134:137], v189 offset:1024
	ds_read_b128 v[138:141], v189 offset:2048
	ds_read_b128 v[142:145], v189 offset:3072
	ds_read_b128 v[164:167], v190
	ds_read_b128 v[168:171], v190 offset:1024
	ds_read_b128 v[172:175], v190 offset:2048
	ds_read_b128 v[194:197], v190 offset:3072
	s_add_u32 s20, s52, 0xfff80080
	s_addc_u32 s21, s53, -1
	s_cmp_eq_u32 s19, 28
	s_cselect_b32 s57, s3, s21
	s_cselect_b32 s56, s14, s20
	s_cselect_b32 s55, s15, s18
	s_cselect_b32 s54, s16, s17
	v_lshl_add_u64 v[230:231], s[52:53], 0, v[154:155]
	s_add_i32 m0, s65, 0xc000
	ds_read_b128 v[198:201], v191
	ds_read_b128 v[202:205], v191 offset:1024
	ds_read_b128 v[206:209], v191 offset:2048
	ds_read_b128 v[210:213], v191 offset:3072
	ds_read_b128 v[214:217], v191 offset:4096
	ds_read_b128 v[218:221], v191 offset:5120
	ds_read_b128 v[222:225], v191 offset:6144
	ds_read_b128 v[226:229], v191 offset:7168
	global_load_lds_dwordx4 v[230:231], off
	v_lshl_add_u64 v[230:231], s[52:53], 0, v[156:157]
	s_add_i32 m0, s65, 0xe000
	s_nop 0
	global_load_lds_dwordx4 v[230:231], off
	s_waitcnt vmcnt(8)
	s_waitcnt lgkmcnt(0)
	v_mfma_f32_16x16x32_bf16 v[126:129], v[130:133], v[198:201], v[126:129]
	v_mfma_f32_16x16x32_bf16 v[122:125], v[138:141], v[198:201], v[122:125]
	v_mfma_f32_16x16x32_bf16 v[110:113], v[130:133], v[206:209], v[110:113]
	v_mfma_f32_16x16x32_bf16 v[106:109], v[138:141], v[206:209], v[106:109]
	s_barrier
	s_setprio 1
	v_mfma_f32_16x16x32_bf16 v[94:97], v[130:133], v[214:217], v[94:97]
	v_mfma_f32_16x16x32_bf16 v[90:93], v[138:141], v[214:217], v[90:93]
	v_mfma_f32_16x16x32_bf16 v[78:81], v[130:133], v[222:225], v[78:81]
	v_mfma_f32_16x16x32_bf16 v[74:77], v[138:141], v[222:225], v[74:77]
	v_mfma_f32_16x16x32_bf16 v[126:129], v[134:137], v[202:205], v[126:129]
	v_mfma_f32_16x16x32_bf16 v[122:125], v[142:145], v[202:205], v[122:125]
	v_mfma_f32_16x16x32_bf16 v[110:113], v[134:137], v[210:213], v[110:113]
	v_mfma_f32_16x16x32_bf16 v[106:109], v[142:145], v[210:213], v[106:109]
	v_mfma_f32_16x16x32_bf16 v[94:97], v[134:137], v[218:221], v[94:97]
	v_mfma_f32_16x16x32_bf16 v[90:93], v[142:145], v[218:221], v[90:93]
	v_mfma_f32_16x16x32_bf16 v[78:81], v[134:137], v[226:229], v[78:81]
	v_mfma_f32_16x16x32_bf16 v[74:77], v[142:145], v[226:229], v[74:77]
	v_mfma_f32_16x16x32_bf16 v[118:121], v[164:167], v[198:201], v[118:121]
	v_mfma_f32_16x16x32_bf16 v[114:117], v[172:175], v[198:201], v[114:117]
	v_mfma_f32_16x16x32_bf16 v[102:105], v[164:167], v[206:209], v[102:105]
	v_mfma_f32_16x16x32_bf16 v[98:101], v[172:175], v[206:209], v[98:101]
	v_mfma_f32_16x16x32_bf16 v[86:89], v[164:167], v[214:217], v[86:89]
	v_mfma_f32_16x16x32_bf16 v[82:85], v[172:175], v[214:217], v[82:85]
	v_mfma_f32_16x16x32_bf16 v[70:73], v[164:167], v[222:225], v[70:73]
	v_mfma_f32_16x16x32_bf16 v[66:69], v[172:175], v[222:225], v[66:69]
	v_mfma_f32_16x16x32_bf16 v[118:121], v[168:171], v[202:205], v[118:121]
	v_mfma_f32_16x16x32_bf16 v[114:117], v[194:197], v[202:205], v[114:117]
	v_mfma_f32_16x16x32_bf16 v[102:105], v[168:171], v[210:213], v[102:105]
	v_mfma_f32_16x16x32_bf16 v[98:101], v[194:197], v[210:213], v[98:101]
	v_mfma_f32_16x16x32_bf16 v[86:89], v[168:171], v[218:221], v[86:89]
	v_mfma_f32_16x16x32_bf16 v[82:85], v[194:197], v[218:221], v[82:85]
	v_mfma_f32_16x16x32_bf16 v[70:73], v[168:171], v[226:229], v[70:73]
	v_mfma_f32_16x16x32_bf16 v[66:69], v[194:197], v[226:229], v[66:69]
	s_setprio 0
	s_barrier
	s_add_i32 s20, s77, s64
	v_lshl_add_u64 v[230:231], s[54:55], 0, v[146:147]
	s_mov_b32 m0, s20
	ds_read_b128 v[198:201], v191 offset:16384
	ds_read_b128 v[202:205], v191 offset:17408
	ds_read_b128 v[206:209], v191 offset:18432
	ds_read_b128 v[210:213], v191 offset:19456
	ds_read_b128 v[214:217], v191 offset:20480
	ds_read_b128 v[218:221], v191 offset:21504
	ds_read_b128 v[222:225], v191 offset:22528
	ds_read_b128 v[226:229], v191 offset:23552
	global_load_lds_dwordx4 v[230:231], off
	s_add_i32 m0, s20, 0x2000
	s_add_u32 s20, s54, 0x80000
	v_lshl_add_u64 v[232:233], s[54:55], 0, v[148:149]
	s_addc_u32 s21, s55, 0
	s_add_i32 s43, s78, s64
	global_load_lds_dwordx4 v[232:233], off
	v_lshl_add_u64 v[234:235], s[20:21], 0, v[146:147]
	s_mov_b32 m0, s43
	v_lshl_add_u64 v[236:237], s[56:57], 0, v[148:149]
	global_load_lds_dwordx4 v[234:235], off
	v_lshl_add_u64 v[234:235], s[20:21], 0, v[148:149]
	s_add_i32 m0, s43, 0x2000
	s_nop 0
	global_load_lds_dwordx4 v[234:235], off
	v_lshl_add_u64 v[234:235], s[56:57], 0, v[146:147]
	s_mov_b32 m0, s65
	s_nop 0
	global_load_lds_dwordx4 v[234:235], off
	s_mov_b32 m0, s66
	s_nop 0
	global_load_lds_dwordx4 v[236:237], off
	s_waitcnt vmcnt(8)
	s_waitcnt lgkmcnt(0)
	v_mfma_f32_16x16x32_bf16 v[62:65], v[130:133], v[198:201], v[62:65]
	v_mfma_f32_16x16x32_bf16 v[58:61], v[138:141], v[198:201], v[58:61]
	v_mfma_f32_16x16x32_bf16 v[46:49], v[130:133], v[206:209], v[46:49]
	v_mfma_f32_16x16x32_bf16 v[42:45], v[138:141], v[206:209], v[42:45]
	s_barrier
	s_setprio 1
	v_mfma_f32_16x16x32_bf16 v[30:33], v[130:133], v[214:217], v[30:33]
	v_mfma_f32_16x16x32_bf16 v[26:29], v[138:141], v[214:217], v[26:29]
	v_mfma_f32_16x16x32_bf16 v[14:17], v[130:133], v[222:225], v[14:17]
	v_mfma_f32_16x16x32_bf16 v[10:13], v[138:141], v[222:225], v[10:13]
	v_mfma_f32_16x16x32_bf16 v[62:65], v[134:137], v[202:205], v[62:65]
	v_mfma_f32_16x16x32_bf16 v[58:61], v[142:145], v[202:205], v[58:61]
	v_mfma_f32_16x16x32_bf16 v[46:49], v[134:137], v[210:213], v[46:49]
	v_mfma_f32_16x16x32_bf16 v[42:45], v[142:145], v[210:213], v[42:45]
	v_mfma_f32_16x16x32_bf16 v[30:33], v[134:137], v[218:221], v[30:33]
	v_mfma_f32_16x16x32_bf16 v[26:29], v[142:145], v[218:221], v[26:29]
	v_mfma_f32_16x16x32_bf16 v[14:17], v[134:137], v[226:229], v[14:17]
	v_mfma_f32_16x16x32_bf16 v[10:13], v[142:145], v[226:229], v[10:13]
	v_mfma_f32_16x16x32_bf16 v[54:57], v[164:167], v[198:201], v[54:57]
	v_mfma_f32_16x16x32_bf16 v[50:53], v[172:175], v[198:201], v[50:53]
	v_mfma_f32_16x16x32_bf16 v[38:41], v[164:167], v[206:209], v[38:41]
	v_mfma_f32_16x16x32_bf16 v[34:37], v[172:175], v[206:209], v[34:37]
	v_mfma_f32_16x16x32_bf16 v[22:25], v[164:167], v[214:217], v[22:25]
	v_mfma_f32_16x16x32_bf16 v[18:21], v[172:175], v[214:217], v[18:21]
	v_mfma_f32_16x16x32_bf16 v[6:9], v[164:167], v[222:225], v[6:9]
	v_mfma_f32_16x16x32_bf16 v[2:5], v[172:175], v[222:225], v[2:5]
	v_mfma_f32_16x16x32_bf16 v[54:57], v[168:171], v[202:205], v[54:57]
	v_mfma_f32_16x16x32_bf16 v[50:53], v[194:197], v[202:205], v[50:53]
	v_mfma_f32_16x16x32_bf16 v[38:41], v[168:171], v[210:213], v[38:41]
	v_mfma_f32_16x16x32_bf16 v[34:37], v[194:197], v[210:213], v[34:37]
	v_mfma_f32_16x16x32_bf16 v[22:25], v[168:171], v[218:221], v[22:25]
	v_mfma_f32_16x16x32_bf16 v[18:21], v[194:197], v[218:221], v[18:21]
	v_mfma_f32_16x16x32_bf16 v[6:9], v[168:171], v[226:229], v[6:9]
	v_mfma_f32_16x16x32_bf16 v[2:5], v[194:197], v[226:229], v[2:5]
	s_setprio 0
	s_barrier
	s_add_i32 s43, 0, 0x18000
	s_add_i32 s45, 0, 0x1c000
	v_add_u32_e32 v142, s43, v187
	v_add_u32_e32 v193, s45, v187
	ds_read_b128 v[130:133], v142
	ds_read_b128 v[134:137], v142 offset:1024
	ds_read_b128 v[138:141], v142 offset:2048
	ds_read_b128 v[142:145], v142 offset:3072
	ds_read_b128 v[164:167], v193
	ds_read_b128 v[168:171], v193 offset:1024
	ds_read_b128 v[172:175], v193 offset:2048
	ds_read_b128 v[194:197], v193 offset:3072
	s_add_u32 s20, s56, 0x80000
	s_addc_u32 s21, s57, 0
	s_mov_b32 m0, s67
	v_lshl_add_u64 v[238:239], s[20:21], 0, v[146:147]
	ds_read_b128 v[198:201], v191 offset:32768
	ds_read_b128 v[202:205], v191 offset:33792
	ds_read_b128 v[206:209], v191 offset:34816
	ds_read_b128 v[210:213], v191 offset:35840
	ds_read_b128 v[214:217], v191 offset:36864
	ds_read_b128 v[218:221], v191 offset:37888
	ds_read_b128 v[222:225], v191 offset:38912
	ds_read_b128 v[226:229], v191 offset:39936
	global_load_lds_dwordx4 v[238:239], off
	v_lshl_add_u64 v[238:239], s[20:21], 0, v[148:149]
	s_mov_b32 m0, s68
	s_nop 0
	global_load_lds_dwordx4 v[238:239], off
	s_waitcnt vmcnt(8)
	s_waitcnt lgkmcnt(0)
	v_mfma_f32_16x16x32_bf16 v[126:129], v[130:133], v[198:201], v[126:129]
	v_mfma_f32_16x16x32_bf16 v[122:125], v[138:141], v[198:201], v[122:125]
	v_mfma_f32_16x16x32_bf16 v[110:113], v[130:133], v[206:209], v[110:113]
	v_mfma_f32_16x16x32_bf16 v[106:109], v[138:141], v[206:209], v[106:109]
	s_barrier
	s_setprio 1
	v_mfma_f32_16x16x32_bf16 v[94:97], v[130:133], v[214:217], v[94:97]
	v_mfma_f32_16x16x32_bf16 v[90:93], v[138:141], v[214:217], v[90:93]
	v_mfma_f32_16x16x32_bf16 v[78:81], v[130:133], v[222:225], v[78:81]
	v_mfma_f32_16x16x32_bf16 v[74:77], v[138:141], v[222:225], v[74:77]
	v_mfma_f32_16x16x32_bf16 v[126:129], v[134:137], v[202:205], v[126:129]
	v_mfma_f32_16x16x32_bf16 v[122:125], v[142:145], v[202:205], v[122:125]
	v_mfma_f32_16x16x32_bf16 v[110:113], v[134:137], v[210:213], v[110:113]
	v_mfma_f32_16x16x32_bf16 v[106:109], v[142:145], v[210:213], v[106:109]
	v_mfma_f32_16x16x32_bf16 v[94:97], v[134:137], v[218:221], v[94:97]
	v_mfma_f32_16x16x32_bf16 v[90:93], v[142:145], v[218:221], v[90:93]
	v_mfma_f32_16x16x32_bf16 v[78:81], v[134:137], v[226:229], v[78:81]
	v_mfma_f32_16x16x32_bf16 v[74:77], v[142:145], v[226:229], v[74:77]
	v_mfma_f32_16x16x32_bf16 v[118:121], v[164:167], v[198:201], v[118:121]
	v_mfma_f32_16x16x32_bf16 v[114:117], v[172:175], v[198:201], v[114:117]
	v_mfma_f32_16x16x32_bf16 v[102:105], v[164:167], v[206:209], v[102:105]
	v_mfma_f32_16x16x32_bf16 v[98:101], v[172:175], v[206:209], v[98:101]
	v_mfma_f32_16x16x32_bf16 v[86:89], v[164:167], v[214:217], v[86:89]
	v_mfma_f32_16x16x32_bf16 v[82:85], v[172:175], v[214:217], v[82:85]
	v_mfma_f32_16x16x32_bf16 v[70:73], v[164:167], v[222:225], v[70:73]
	v_mfma_f32_16x16x32_bf16 v[66:69], v[172:175], v[222:225], v[66:69]
	v_mfma_f32_16x16x32_bf16 v[118:121], v[168:171], v[202:205], v[118:121]
	v_mfma_f32_16x16x32_bf16 v[114:117], v[194:197], v[202:205], v[114:117]
	v_mfma_f32_16x16x32_bf16 v[102:105], v[168:171], v[210:213], v[102:105]
	v_mfma_f32_16x16x32_bf16 v[98:101], v[194:197], v[210:213], v[98:101]
	v_mfma_f32_16x16x32_bf16 v[86:89], v[168:171], v[218:221], v[86:89]
	v_mfma_f32_16x16x32_bf16 v[82:85], v[194:197], v[218:221], v[82:85]
	v_mfma_f32_16x16x32_bf16 v[70:73], v[168:171], v[226:229], v[70:73]
	v_mfma_f32_16x16x32_bf16 v[66:69], v[194:197], v[226:229], v[66:69]
	s_setprio 0
	s_barrier
	s_add_i32 s20, s43, s64
	v_lshl_add_u64 v[230:231], v[230:231], 0, s[26:27]
	s_mov_b32 m0, s20
	ds_read_b128 v[198:201], v191 offset:49152
	ds_read_b128 v[202:205], v191 offset:50176
	ds_read_b128 v[206:209], v191 offset:51200
	ds_read_b128 v[210:213], v191 offset:52224
	ds_read_b128 v[214:217], v191 offset:53248
	ds_read_b128 v[218:221], v191 offset:54272
	ds_read_b128 v[222:225], v191 offset:55296
	ds_read_b128 v[226:229], v191 offset:56320
	global_load_lds_dwordx4 v[230:231], off
	s_add_i32 m0, s20, 0x2000
	s_add_u32 s20, s54, 0x80080
	v_lshl_add_u64 v[230:231], v[232:233], 0, s[26:27]
	s_addc_u32 s21, s55, 0
	s_add_i32 s43, s45, s64
	global_load_lds_dwordx4 v[230:231], off
	v_lshl_add_u64 v[230:231], s[20:21], 0, v[146:147]
	s_mov_b32 m0, s43
	s_nop 0
	global_load_lds_dwordx4 v[230:231], off
	v_lshl_add_u64 v[230:231], s[20:21], 0, v[148:149]
	s_add_i32 m0, s43, 0x2000
	s_nop 0
	global_load_lds_dwordx4 v[230:231], off
	v_lshl_add_u64 v[230:231], v[234:235], 0, s[26:27]
	s_mov_b32 m0, s73
	s_nop 0
	global_load_lds_dwordx4 v[230:231], off
	v_lshl_add_u64 v[230:231], v[236:237], 0, s[26:27]
	s_mov_b32 m0, s74
	s_nop 0
	global_load_lds_dwordx4 v[230:231], off
	s_waitcnt vmcnt(8)
	s_waitcnt lgkmcnt(0)
	v_mfma_f32_16x16x32_bf16 v[62:65], v[130:133], v[198:201], v[62:65]
	v_mfma_f32_16x16x32_bf16 v[58:61], v[138:141], v[198:201], v[58:61]
	v_mfma_f32_16x16x32_bf16 v[46:49], v[130:133], v[206:209], v[46:49]
	v_mfma_f32_16x16x32_bf16 v[42:45], v[138:141], v[206:209], v[42:45]
	s_barrier
	s_setprio 1
	v_mfma_f32_16x16x32_bf16 v[30:33], v[130:133], v[214:217], v[30:33]
	v_mfma_f32_16x16x32_bf16 v[26:29], v[138:141], v[214:217], v[26:29]
	v_mfma_f32_16x16x32_bf16 v[14:17], v[130:133], v[222:225], v[14:17]
	v_mfma_f32_16x16x32_bf16 v[10:13], v[138:141], v[222:225], v[10:13]
	v_mfma_f32_16x16x32_bf16 v[62:65], v[134:137], v[202:205], v[62:65]
	v_mfma_f32_16x16x32_bf16 v[58:61], v[142:145], v[202:205], v[58:61]
	v_mfma_f32_16x16x32_bf16 v[46:49], v[134:137], v[210:213], v[46:49]
	v_mfma_f32_16x16x32_bf16 v[42:45], v[142:145], v[210:213], v[42:45]
	v_mfma_f32_16x16x32_bf16 v[30:33], v[134:137], v[218:221], v[30:33]
	v_mfma_f32_16x16x32_bf16 v[26:29], v[142:145], v[218:221], v[26:29]
	v_mfma_f32_16x16x32_bf16 v[14:17], v[134:137], v[226:229], v[14:17]
	v_mfma_f32_16x16x32_bf16 v[10:13], v[142:145], v[226:229], v[10:13]
	v_mfma_f32_16x16x32_bf16 v[54:57], v[164:167], v[198:201], v[54:57]
	v_mfma_f32_16x16x32_bf16 v[50:53], v[172:175], v[198:201], v[50:53]
	v_mfma_f32_16x16x32_bf16 v[38:41], v[164:167], v[206:209], v[38:41]
	v_mfma_f32_16x16x32_bf16 v[34:37], v[172:175], v[206:209], v[34:37]
	v_mfma_f32_16x16x32_bf16 v[22:25], v[164:167], v[214:217], v[22:25]
	v_mfma_f32_16x16x32_bf16 v[18:21], v[172:175], v[214:217], v[18:21]
	v_mfma_f32_16x16x32_bf16 v[6:9], v[164:167], v[222:225], v[6:9]
	v_mfma_f32_16x16x32_bf16 v[2:5], v[172:175], v[222:225], v[2:5]
	v_mfma_f32_16x16x32_bf16 v[54:57], v[168:171], v[202:205], v[54:57]
	v_mfma_f32_16x16x32_bf16 v[50:53], v[194:197], v[202:205], v[50:53]
	v_mfma_f32_16x16x32_bf16 v[38:41], v[168:171], v[210:213], v[38:41]
	v_mfma_f32_16x16x32_bf16 v[34:37], v[194:197], v[210:213], v[34:37]
	v_mfma_f32_16x16x32_bf16 v[22:25], v[168:171], v[218:221], v[22:25]
	v_mfma_f32_16x16x32_bf16 v[18:21], v[194:197], v[218:221], v[18:21]
	v_mfma_f32_16x16x32_bf16 v[6:9], v[168:171], v[226:229], v[6:9]
	v_mfma_f32_16x16x32_bf16 v[2:5], v[194:197], v[226:229], v[2:5]
	s_setprio 0
	s_barrier
	s_add_i32 s19, s19, 2
	s_add_u32 s52, s52, 0x100
	s_addc_u32 s53, s53, 0
	s_add_u32 s17, s17, 0x100
	s_addc_u32 s18, s18, 0
	s_cmp_gt_u32 s19, 29
	s_cbranch_scc0 .LBB0_1213
	s_and_b64 vcc, exec, s[28:29]
	s_cbranch_vccnz .LBB0_1218
	v_lshl_add_u32 v164, s50, 8, v186
	s_cmp_gt_i32 s10, 1
	s_mov_b64 s[50:51], -1
	s_cbranch_scc1 .LBB0_1219

.LBB0_1264:
	ds_read_b128 v[142:145], v163
	ds_read_b128 v[146:149], v163 offset:1024
	ds_read_b128 v[150:153], v163 offset:2048
	ds_read_b128 v[154:157], v163 offset:3072
	ds_read_b128 v[170:173], v166
	ds_read_b128 v[174:177], v166 offset:1024
	ds_read_b128 v[178:181], v166 offset:2048
	ds_read_b128 v[182:185], v166 offset:3072
	s_add_u32 s44, s42, 0xfffe0080
	s_addc_u32 s45, s43, -1
	s_cmp_eq_u32 s29, 4
	s_cselect_b32 s47, s3, s45
	s_cselect_b32 s46, s16, s44
	s_cselect_b32 s45, s17, s27
	s_cselect_b32 s44, s18, s19
	v_lshl_add_u64 v[218:219], s[42:43], 0, v[138:139]
	s_add_i32 m0, s39, 0xc000
	ds_read_b128 v[186:189], v167
	ds_read_b128 v[190:193], v167 offset:1024
	ds_read_b128 v[194:197], v167 offset:2048
	ds_read_b128 v[198:201], v167 offset:3072
	ds_read_b128 v[202:205], v167 offset:4096
	ds_read_b128 v[206:209], v167 offset:5120
	ds_read_b128 v[210:213], v167 offset:6144
	ds_read_b128 v[214:217], v167 offset:7168
	global_load_lds_dwordx4 v[218:219], off
	v_lshl_add_u64 v[218:219], s[42:43], 0, v[140:141]
	s_add_i32 m0, s39, 0xe000
	s_nop 0
	global_load_lds_dwordx4 v[218:219], off
	s_waitcnt vmcnt(8)
	s_waitcnt lgkmcnt(0)
	v_mfma_f32_16x16x32_bf16 v[126:129], v[142:145], v[186:189], v[126:129]
	v_mfma_f32_16x16x32_bf16 v[122:125], v[150:153], v[186:189], v[122:125]
	v_mfma_f32_16x16x32_bf16 v[118:121], v[142:145], v[194:197], v[118:121]
	v_mfma_f32_16x16x32_bf16 v[110:113], v[150:153], v[194:197], v[110:113]
	s_barrier
	s_setprio 1
	v_mfma_f32_16x16x32_bf16 v[102:105], v[142:145], v[202:205], v[102:105]
	v_mfma_f32_16x16x32_bf16 v[94:97], v[150:153], v[202:205], v[94:97]
	v_mfma_f32_16x16x32_bf16 v[86:89], v[142:145], v[210:213], v[86:89]
	v_mfma_f32_16x16x32_bf16 v[78:81], v[150:153], v[210:213], v[78:81]
	v_mfma_f32_16x16x32_bf16 v[126:129], v[146:149], v[190:193], v[126:129]
	v_mfma_f32_16x16x32_bf16 v[122:125], v[154:157], v[190:193], v[122:125]
	v_mfma_f32_16x16x32_bf16 v[118:121], v[146:149], v[198:201], v[118:121]
	v_mfma_f32_16x16x32_bf16 v[110:113], v[154:157], v[198:201], v[110:113]
	v_mfma_f32_16x16x32_bf16 v[102:105], v[146:149], v[206:209], v[102:105]
	v_mfma_f32_16x16x32_bf16 v[94:97], v[154:157], v[206:209], v[94:97]
	v_mfma_f32_16x16x32_bf16 v[86:89], v[146:149], v[214:217], v[86:89]
	v_mfma_f32_16x16x32_bf16 v[78:81], v[154:157], v[214:217], v[78:81]
	v_mfma_f32_16x16x32_bf16 v[114:117], v[170:173], v[186:189], v[114:117]
	v_mfma_f32_16x16x32_bf16 v[106:109], v[178:181], v[186:189], v[106:109]
	v_mfma_f32_16x16x32_bf16 v[98:101], v[170:173], v[194:197], v[98:101]
	v_mfma_f32_16x16x32_bf16 v[90:93], v[178:181], v[194:197], v[90:93]
	v_mfma_f32_16x16x32_bf16 v[82:85], v[170:173], v[202:205], v[82:85]
	v_mfma_f32_16x16x32_bf16 v[74:77], v[178:181], v[202:205], v[74:77]
	v_mfma_f32_16x16x32_bf16 v[70:73], v[170:173], v[210:213], v[70:73]
	v_mfma_f32_16x16x32_bf16 v[66:69], v[178:181], v[210:213], v[66:69]
	v_mfma_f32_16x16x32_bf16 v[114:117], v[174:177], v[190:193], v[114:117]
	v_mfma_f32_16x16x32_bf16 v[106:109], v[182:185], v[190:193], v[106:109]
	v_mfma_f32_16x16x32_bf16 v[98:101], v[174:177], v[198:201], v[98:101]
	v_mfma_f32_16x16x32_bf16 v[90:93], v[182:185], v[198:201], v[90:93]
	v_mfma_f32_16x16x32_bf16 v[82:85], v[174:177], v[206:209], v[82:85]
	v_mfma_f32_16x16x32_bf16 v[74:77], v[182:185], v[206:209], v[74:77]
	v_mfma_f32_16x16x32_bf16 v[70:73], v[174:177], v[214:217], v[70:73]
	v_mfma_f32_16x16x32_bf16 v[66:69], v[182:185], v[214:217], v[66:69]
	s_setprio 0
	s_barrier
	s_add_i32 s62, s60, s54
	v_lshl_add_u64 v[218:219], s[44:45], 0, v[132:133]
	s_mov_b32 m0, s62
	ds_read_b128 v[186:189], v167 offset:16384
	ds_read_b128 v[190:193], v167 offset:17408
	ds_read_b128 v[194:197], v167 offset:18432
	ds_read_b128 v[198:201], v167 offset:19456
	ds_read_b128 v[202:205], v167 offset:20480
	ds_read_b128 v[206:209], v167 offset:21504
	ds_read_b128 v[210:213], v167 offset:22528
	ds_read_b128 v[214:217], v167 offset:23552
	global_load_lds_dwordx4 v[218:219], off
	s_add_i32 m0, s62, 0x2000
	s_add_u32 s62, s44, 0x20000
	v_lshl_add_u64 v[220:221], s[44:45], 0, v[136:137]
	s_addc_u32 s63, s45, 0
	s_add_i32 s64, s61, s54
	global_load_lds_dwordx4 v[220:221], off
	v_lshl_add_u64 v[222:223], s[62:63], 0, v[132:133]
	s_mov_b32 m0, s64
	v_lshl_add_u64 v[224:225], s[46:47], 0, v[134:135]
	global_load_lds_dwordx4 v[222:223], off
	v_lshl_add_u64 v[222:223], s[62:63], 0, v[136:137]
	s_add_i32 m0, s64, 0x2000
	s_nop 0
	global_load_lds_dwordx4 v[222:223], off
	v_lshl_add_u64 v[222:223], s[46:47], 0, v[130:131]
	s_mov_b32 m0, s39
	s_nop 0
	global_load_lds_dwordx4 v[222:223], off
	s_mov_b32 m0, s41
	s_nop 0
	global_load_lds_dwordx4 v[224:225], off
	s_waitcnt vmcnt(8)
	s_waitcnt lgkmcnt(0)
	v_mfma_f32_16x16x32_bf16 v[62:65], v[142:145], v[186:189], v[62:65]
	v_mfma_f32_16x16x32_bf16 v[58:61], v[150:153], v[186:189], v[58:61]
	v_mfma_f32_16x16x32_bf16 v[54:57], v[142:145], v[194:197], v[54:57]
	v_mfma_f32_16x16x32_bf16 v[46:49], v[150:153], v[194:197], v[46:49]
	s_barrier
	s_setprio 1
	v_mfma_f32_16x16x32_bf16 v[38:41], v[142:145], v[202:205], v[38:41]
	v_mfma_f32_16x16x32_bf16 v[30:33], v[150:153], v[202:205], v[30:33]
	v_mfma_f32_16x16x32_bf16 v[22:25], v[142:145], v[210:213], v[22:25]
	v_mfma_f32_16x16x32_bf16 v[14:17], v[150:153], v[210:213], v[14:17]
	v_mfma_f32_16x16x32_bf16 v[62:65], v[146:149], v[190:193], v[62:65]
	v_mfma_f32_16x16x32_bf16 v[58:61], v[154:157], v[190:193], v[58:61]
	v_mfma_f32_16x16x32_bf16 v[54:57], v[146:149], v[198:201], v[54:57]
	v_mfma_f32_16x16x32_bf16 v[46:49], v[154:157], v[198:201], v[46:49]
	v_mfma_f32_16x16x32_bf16 v[38:41], v[146:149], v[206:209], v[38:41]
	v_mfma_f32_16x16x32_bf16 v[30:33], v[154:157], v[206:209], v[30:33]
	v_mfma_f32_16x16x32_bf16 v[22:25], v[146:149], v[214:217], v[22:25]
	v_mfma_f32_16x16x32_bf16 v[14:17], v[154:157], v[214:217], v[14:17]
	v_mfma_f32_16x16x32_bf16 v[50:53], v[170:173], v[186:189], v[50:53]
	v_mfma_f32_16x16x32_bf16 v[42:45], v[178:181], v[186:189], v[42:45]
	v_mfma_f32_16x16x32_bf16 v[34:37], v[170:173], v[194:197], v[34:37]
	v_mfma_f32_16x16x32_bf16 v[26:29], v[178:181], v[194:197], v[26:29]
	v_mfma_f32_16x16x32_bf16 v[18:21], v[170:173], v[202:205], v[18:21]
	v_mfma_f32_16x16x32_bf16 v[10:13], v[178:181], v[202:205], v[10:13]
	v_mfma_f32_16x16x32_bf16 v[6:9], v[170:173], v[210:213], v[6:9]
	v_mfma_f32_16x16x32_bf16 v[2:5], v[178:181], v[210:213], v[2:5]
	v_mfma_f32_16x16x32_bf16 v[50:53], v[174:177], v[190:193], v[50:53]
	v_mfma_f32_16x16x32_bf16 v[42:45], v[182:185], v[190:193], v[42:45]
	v_mfma_f32_16x16x32_bf16 v[34:37], v[174:177], v[198:201], v[34:37]
	v_mfma_f32_16x16x32_bf16 v[26:29], v[182:185], v[198:201], v[26:29]
	v_mfma_f32_16x16x32_bf16 v[18:21], v[174:177], v[206:209], v[18:21]
	v_mfma_f32_16x16x32_bf16 v[10:13], v[182:185], v[206:209], v[10:13]
	v_mfma_f32_16x16x32_bf16 v[6:9], v[174:177], v[214:217], v[6:9]
	v_mfma_f32_16x16x32_bf16 v[2:5], v[182:185], v[214:217], v[2:5]
	s_setprio 0
	s_barrier
	s_add_i32 s62, 0, 0x18000
	s_add_i32 s63, 0, 0x1c000
	v_add_u32_e32 v154, s62, v161
	v_add_u32_e32 v158, s63, v161
	ds_read_b128 v[142:145], v154
	ds_read_b128 v[146:149], v154 offset:1024
	ds_read_b128 v[150:153], v154 offset:2048
	ds_read_b128 v[154:157], v154 offset:3072
	ds_read_b128 v[170:173], v158
	ds_read_b128 v[174:177], v158 offset:1024
	ds_read_b128 v[178:181], v158 offset:2048
	ds_read_b128 v[182:185], v158 offset:3072
	s_add_u32 s46, s46, 0x20000
	s_addc_u32 s47, s47, 0
	s_mov_b32 m0, s55
	v_lshl_add_u64 v[226:227], s[46:47], 0, v[130:131]
	ds_read_b128 v[186:189], v167 offset:32768
	ds_read_b128 v[190:193], v167 offset:33792
	ds_read_b128 v[194:197], v167 offset:34816
	ds_read_b128 v[198:201], v167 offset:35840
	ds_read_b128 v[202:205], v167 offset:36864
	ds_read_b128 v[206:209], v167 offset:37888
	ds_read_b128 v[210:213], v167 offset:38912
	ds_read_b128 v[214:217], v167 offset:39936
	global_load_lds_dwordx4 v[226:227], off
	v_lshl_add_u64 v[226:227], s[46:47], 0, v[134:135]
	s_mov_b32 m0, s56
	s_nop 0
	global_load_lds_dwordx4 v[226:227], off
	s_waitcnt vmcnt(8)
	s_waitcnt lgkmcnt(0)
	v_mfma_f32_16x16x32_bf16 v[126:129], v[142:145], v[186:189], v[126:129]
	v_mfma_f32_16x16x32_bf16 v[122:125], v[150:153], v[186:189], v[122:125]
	v_mfma_f32_16x16x32_bf16 v[118:121], v[142:145], v[194:197], v[118:121]
	v_mfma_f32_16x16x32_bf16 v[110:113], v[150:153], v[194:197], v[110:113]
	s_barrier
	s_setprio 1
	v_mfma_f32_16x16x32_bf16 v[102:105], v[142:145], v[202:205], v[102:105]
	v_mfma_f32_16x16x32_bf16 v[94:97], v[150:153], v[202:205], v[94:97]
	v_mfma_f32_16x16x32_bf16 v[86:89], v[142:145], v[210:213], v[86:89]
	v_mfma_f32_16x16x32_bf16 v[78:81], v[150:153], v[210:213], v[78:81]
	v_mfma_f32_16x16x32_bf16 v[126:129], v[146:149], v[190:193], v[126:129]
	v_mfma_f32_16x16x32_bf16 v[122:125], v[154:157], v[190:193], v[122:125]
	v_mfma_f32_16x16x32_bf16 v[118:121], v[146:149], v[198:201], v[118:121]
	v_mfma_f32_16x16x32_bf16 v[110:113], v[154:157], v[198:201], v[110:113]
	v_mfma_f32_16x16x32_bf16 v[102:105], v[146:149], v[206:209], v[102:105]
	v_mfma_f32_16x16x32_bf16 v[94:97], v[154:157], v[206:209], v[94:97]
	v_mfma_f32_16x16x32_bf16 v[86:89], v[146:149], v[214:217], v[86:89]
	v_mfma_f32_16x16x32_bf16 v[78:81], v[154:157], v[214:217], v[78:81]
	v_mfma_f32_16x16x32_bf16 v[114:117], v[170:173], v[186:189], v[114:117]
	v_mfma_f32_16x16x32_bf16 v[106:109], v[178:181], v[186:189], v[106:109]
	v_mfma_f32_16x16x32_bf16 v[98:101], v[170:173], v[194:197], v[98:101]
	v_mfma_f32_16x16x32_bf16 v[90:93], v[178:181], v[194:197], v[90:93]
	v_mfma_f32_16x16x32_bf16 v[82:85], v[170:173], v[202:205], v[82:85]
	v_mfma_f32_16x16x32_bf16 v[74:77], v[178:181], v[202:205], v[74:77]
	v_mfma_f32_16x16x32_bf16 v[70:73], v[170:173], v[210:213], v[70:73]
	v_mfma_f32_16x16x32_bf16 v[66:69], v[178:181], v[210:213], v[66:69]
	v_mfma_f32_16x16x32_bf16 v[114:117], v[174:177], v[190:193], v[114:117]
	v_mfma_f32_16x16x32_bf16 v[106:109], v[182:185], v[190:193], v[106:109]
	v_mfma_f32_16x16x32_bf16 v[98:101], v[174:177], v[198:201], v[98:101]
	v_mfma_f32_16x16x32_bf16 v[90:93], v[182:185], v[198:201], v[90:93]
	v_mfma_f32_16x16x32_bf16 v[82:85], v[174:177], v[206:209], v[82:85]
	v_mfma_f32_16x16x32_bf16 v[74:77], v[182:185], v[206:209], v[74:77]
	v_mfma_f32_16x16x32_bf16 v[70:73], v[174:177], v[214:217], v[70:73]
	v_mfma_f32_16x16x32_bf16 v[66:69], v[182:185], v[214:217], v[66:69]
	s_setprio 0
	s_barrier
	s_add_i32 s46, s62, s54
	v_lshl_add_u64 v[218:219], v[218:219], 0, s[22:23]
	s_mov_b32 m0, s46
	ds_read_b128 v[186:189], v167 offset:49152
	ds_read_b128 v[190:193], v167 offset:50176
	ds_read_b128 v[194:197], v167 offset:51200
	ds_read_b128 v[198:201], v167 offset:52224
	ds_read_b128 v[202:205], v167 offset:53248
	ds_read_b128 v[206:209], v167 offset:54272
	ds_read_b128 v[210:213], v167 offset:55296
	ds_read_b128 v[214:217], v167 offset:56320
	global_load_lds_dwordx4 v[218:219], off
	s_add_i32 m0, s46, 0x2000
	s_add_u32 s44, s44, 0x20080
	v_lshl_add_u64 v[218:219], v[220:221], 0, s[22:23]
	s_addc_u32 s45, s45, 0
	s_add_i32 s46, s63, s54
	global_load_lds_dwordx4 v[218:219], off
	v_lshl_add_u64 v[218:219], s[44:45], 0, v[132:133]
	s_mov_b32 m0, s46
	s_nop 0
	global_load_lds_dwordx4 v[218:219], off
	v_lshl_add_u64 v[218:219], s[44:45], 0, v[136:137]
	s_add_i32 m0, s46, 0x2000
	s_nop 0
	global_load_lds_dwordx4 v[218:219], off
	v_lshl_add_u64 v[218:219], v[222:223], 0, s[22:23]
	s_mov_b32 m0, s14
	s_nop 0
	global_load_lds_dwordx4 v[218:219], off
	v_lshl_add_u64 v[218:219], v[224:225], 0, s[22:23]
	s_mov_b32 m0, s15
	s_nop 0
	global_load_lds_dwordx4 v[218:219], off
	s_waitcnt vmcnt(8)
	s_waitcnt lgkmcnt(0)
	v_mfma_f32_16x16x32_bf16 v[62:65], v[142:145], v[186:189], v[62:65]
	v_mfma_f32_16x16x32_bf16 v[58:61], v[150:153], v[186:189], v[58:61]
	v_mfma_f32_16x16x32_bf16 v[54:57], v[142:145], v[194:197], v[54:57]
	v_mfma_f32_16x16x32_bf16 v[46:49], v[150:153], v[194:197], v[46:49]
	s_barrier
	s_setprio 1
	v_mfma_f32_16x16x32_bf16 v[38:41], v[142:145], v[202:205], v[38:41]
	v_mfma_f32_16x16x32_bf16 v[30:33], v[150:153], v[202:205], v[30:33]
	v_mfma_f32_16x16x32_bf16 v[22:25], v[142:145], v[210:213], v[22:25]
	v_mfma_f32_16x16x32_bf16 v[14:17], v[150:153], v[210:213], v[14:17]
	v_mfma_f32_16x16x32_bf16 v[62:65], v[146:149], v[190:193], v[62:65]
	v_mfma_f32_16x16x32_bf16 v[58:61], v[154:157], v[190:193], v[58:61]
	v_mfma_f32_16x16x32_bf16 v[54:57], v[146:149], v[198:201], v[54:57]
	v_mfma_f32_16x16x32_bf16 v[46:49], v[154:157], v[198:201], v[46:49]
	v_mfma_f32_16x16x32_bf16 v[38:41], v[146:149], v[206:209], v[38:41]
	v_mfma_f32_16x16x32_bf16 v[30:33], v[154:157], v[206:209], v[30:33]
	v_mfma_f32_16x16x32_bf16 v[22:25], v[146:149], v[214:217], v[22:25]
	v_mfma_f32_16x16x32_bf16 v[14:17], v[154:157], v[214:217], v[14:17]
	v_mfma_f32_16x16x32_bf16 v[50:53], v[170:173], v[186:189], v[50:53]
	v_mfma_f32_16x16x32_bf16 v[42:45], v[178:181], v[186:189], v[42:45]
	v_mfma_f32_16x16x32_bf16 v[34:37], v[170:173], v[194:197], v[34:37]
	v_mfma_f32_16x16x32_bf16 v[26:29], v[178:181], v[194:197], v[26:29]
	v_mfma_f32_16x16x32_bf16 v[18:21], v[170:173], v[202:205], v[18:21]
	v_mfma_f32_16x16x32_bf16 v[10:13], v[178:181], v[202:205], v[10:13]
	v_mfma_f32_16x16x32_bf16 v[6:9], v[170:173], v[210:213], v[6:9]
	v_mfma_f32_16x16x32_bf16 v[2:5], v[178:181], v[210:213], v[2:5]
	v_mfma_f32_16x16x32_bf16 v[50:53], v[174:177], v[190:193], v[50:53]
	v_mfma_f32_16x16x32_bf16 v[42:45], v[182:185], v[190:193], v[42:45]
	v_mfma_f32_16x16x32_bf16 v[34:37], v[174:177], v[198:201], v[34:37]
	v_mfma_f32_16x16x32_bf16 v[26:29], v[182:185], v[198:201], v[26:29]
	v_mfma_f32_16x16x32_bf16 v[18:21], v[174:177], v[206:209], v[18:21]
	v_mfma_f32_16x16x32_bf16 v[10:13], v[182:185], v[206:209], v[10:13]
	v_mfma_f32_16x16x32_bf16 v[6:9], v[174:177], v[214:217], v[6:9]
	v_mfma_f32_16x16x32_bf16 v[2:5], v[182:185], v[214:217], v[2:5]
	s_setprio 0
	s_barrier
	s_add_i32 s29, s29, 2
	s_add_u32 s42, s42, 0x100
	s_addc_u32 s43, s43, 0
	s_add_u32 s19, s19, 0x100
	s_addc_u32 s27, s27, 0
	s_cmp_gt_u32 s29, 5
	s_cbranch_scc0 .LBB0_1264
	s_and_b64 vcc, exec, s[24:25]
	s_cbranch_vccz .LBB0_1267
	s_barrier

.LBB0_1336:
	ds_read_b128 v[154:157], v175
	ds_read_b128 v[158:161], v175 offset:1024
	ds_read_b128 v[164:167], v175 offset:2048
	ds_read_b128 v[168:171], v175 offset:3072
	ds_read_b128 v[180:183], v176
	ds_read_b128 v[184:187], v176 offset:1024
	ds_read_b128 v[188:191], v176 offset:2048
	ds_read_b128 v[192:195], v176 offset:3072
	s_add_u32 s20, s36, 0xfffe0080
	s_addc_u32 s21, s37, -1
	s_cmp_eq_u32 s19, 4
	s_cselect_b32 s41, s3, s21
	s_cselect_b32 s40, s14, s20
	s_cselect_b32 s39, s15, s18
	s_cselect_b32 s38, s16, s17
	v_lshl_add_u64 v[228:229], s[36:37], 0, v[144:145]
	s_add_i32 m0, s49, 0xc000
	ds_read_b128 v[196:199], v177
	ds_read_b128 v[200:203], v177 offset:1024
	ds_read_b128 v[204:207], v177 offset:2048
	ds_read_b128 v[208:211], v177 offset:3072
	ds_read_b128 v[212:215], v177 offset:4096
	ds_read_b128 v[216:219], v177 offset:5120
	ds_read_b128 v[220:223], v177 offset:6144
	ds_read_b128 v[224:227], v177 offset:7168
	global_load_lds_dwordx4 v[228:229], off
	v_lshl_add_u64 v[228:229], s[36:37], 0, v[146:147]
	s_add_i32 m0, s49, 0xe000
	s_nop 0
	global_load_lds_dwordx4 v[228:229], off
	s_waitcnt vmcnt(8)
	s_waitcnt lgkmcnt(0)
	v_mfma_f32_16x16x32_bf16 v[126:129], v[154:157], v[196:199], v[126:129]
	v_mfma_f32_16x16x32_bf16 v[122:125], v[164:167], v[196:199], v[122:125]
	v_mfma_f32_16x16x32_bf16 v[118:121], v[154:157], v[204:207], v[118:121]
	v_mfma_f32_16x16x32_bf16 v[110:113], v[164:167], v[204:207], v[110:113]
	s_barrier
	s_setprio 1
	v_mfma_f32_16x16x32_bf16 v[102:105], v[154:157], v[212:215], v[102:105]
	v_mfma_f32_16x16x32_bf16 v[94:97], v[164:167], v[212:215], v[94:97]
	v_mfma_f32_16x16x32_bf16 v[86:89], v[154:157], v[220:223], v[86:89]
	v_mfma_f32_16x16x32_bf16 v[78:81], v[164:167], v[220:223], v[78:81]
	v_mfma_f32_16x16x32_bf16 v[126:129], v[158:161], v[200:203], v[126:129]
	v_mfma_f32_16x16x32_bf16 v[122:125], v[168:171], v[200:203], v[122:125]
	v_mfma_f32_16x16x32_bf16 v[118:121], v[158:161], v[208:211], v[118:121]
	v_mfma_f32_16x16x32_bf16 v[110:113], v[168:171], v[208:211], v[110:113]
	v_mfma_f32_16x16x32_bf16 v[102:105], v[158:161], v[216:219], v[102:105]
	v_mfma_f32_16x16x32_bf16 v[94:97], v[168:171], v[216:219], v[94:97]
	v_mfma_f32_16x16x32_bf16 v[86:89], v[158:161], v[224:227], v[86:89]
	v_mfma_f32_16x16x32_bf16 v[78:81], v[168:171], v[224:227], v[78:81]
	v_mfma_f32_16x16x32_bf16 v[114:117], v[180:183], v[196:199], v[114:117]
	v_mfma_f32_16x16x32_bf16 v[106:109], v[188:191], v[196:199], v[106:109]
	v_mfma_f32_16x16x32_bf16 v[98:101], v[180:183], v[204:207], v[98:101]
	v_mfma_f32_16x16x32_bf16 v[90:93], v[188:191], v[204:207], v[90:93]
	v_mfma_f32_16x16x32_bf16 v[82:85], v[180:183], v[212:215], v[82:85]
	v_mfma_f32_16x16x32_bf16 v[74:77], v[188:191], v[212:215], v[74:77]
	v_mfma_f32_16x16x32_bf16 v[70:73], v[180:183], v[220:223], v[70:73]
	v_mfma_f32_16x16x32_bf16 v[66:69], v[188:191], v[220:223], v[66:69]
	v_mfma_f32_16x16x32_bf16 v[114:117], v[184:187], v[200:203], v[114:117]
	v_mfma_f32_16x16x32_bf16 v[106:109], v[192:195], v[200:203], v[106:109]
	v_mfma_f32_16x16x32_bf16 v[98:101], v[184:187], v[208:211], v[98:101]
	v_mfma_f32_16x16x32_bf16 v[90:93], v[192:195], v[208:211], v[90:93]
	v_mfma_f32_16x16x32_bf16 v[82:85], v[184:187], v[216:219], v[82:85]
	v_mfma_f32_16x16x32_bf16 v[74:77], v[192:195], v[216:219], v[74:77]
	v_mfma_f32_16x16x32_bf16 v[70:73], v[184:187], v[224:227], v[70:73]
	v_mfma_f32_16x16x32_bf16 v[66:69], v[192:195], v[224:227], v[66:69]
	s_setprio 0
	s_barrier
	s_add_i32 s20, s57, s46
	v_lshl_add_u64 v[228:229], s[38:39], 0, v[134:135]
	s_mov_b32 m0, s20
	ds_read_b128 v[196:199], v177 offset:16384
	ds_read_b128 v[200:203], v177 offset:17408
	ds_read_b128 v[204:207], v177 offset:18432
	ds_read_b128 v[208:211], v177 offset:19456
	ds_read_b128 v[212:215], v177 offset:20480
	ds_read_b128 v[216:219], v177 offset:21504
	ds_read_b128 v[220:223], v177 offset:22528
	ds_read_b128 v[224:227], v177 offset:23552
	global_load_lds_dwordx4 v[228:229], off
	s_add_i32 m0, s20, 0x2000
	s_add_u32 s20, s38, 0x20000
	v_lshl_add_u64 v[230:231], s[38:39], 0, v[130:131]
	s_addc_u32 s21, s39, 0
	s_add_i32 s27, s60, s46
	global_load_lds_dwordx4 v[230:231], off
	v_lshl_add_u64 v[232:233], s[20:21], 0, v[134:135]
	s_mov_b32 m0, s27
	v_lshl_add_u64 v[234:235], s[40:41], 0, v[132:133]
	global_load_lds_dwordx4 v[232:233], off
	v_lshl_add_u64 v[232:233], s[20:21], 0, v[130:131]
	s_add_i32 m0, s27, 0x2000
	s_nop 0
	global_load_lds_dwordx4 v[232:233], off
	v_lshl_add_u64 v[232:233], s[40:41], 0, v[136:137]
	s_mov_b32 m0, s49
	s_nop 0
	global_load_lds_dwordx4 v[232:233], off
	s_mov_b32 m0, s50
	s_nop 0
	global_load_lds_dwordx4 v[234:235], off
	s_waitcnt vmcnt(8)
	s_waitcnt lgkmcnt(0)
	v_mfma_f32_16x16x32_bf16 v[62:65], v[154:157], v[196:199], v[62:65]
	v_mfma_f32_16x16x32_bf16 v[58:61], v[164:167], v[196:199], v[58:61]
	v_mfma_f32_16x16x32_bf16 v[54:57], v[154:157], v[204:207], v[54:57]
	v_mfma_f32_16x16x32_bf16 v[46:49], v[164:167], v[204:207], v[46:49]
	s_barrier
	s_setprio 1
	v_mfma_f32_16x16x32_bf16 v[38:41], v[154:157], v[212:215], v[38:41]
	v_mfma_f32_16x16x32_bf16 v[30:33], v[164:167], v[212:215], v[30:33]
	v_mfma_f32_16x16x32_bf16 v[22:25], v[154:157], v[220:223], v[22:25]
	v_mfma_f32_16x16x32_bf16 v[14:17], v[164:167], v[220:223], v[14:17]
	v_mfma_f32_16x16x32_bf16 v[62:65], v[158:161], v[200:203], v[62:65]
	v_mfma_f32_16x16x32_bf16 v[58:61], v[168:171], v[200:203], v[58:61]
	v_mfma_f32_16x16x32_bf16 v[54:57], v[158:161], v[208:211], v[54:57]
	v_mfma_f32_16x16x32_bf16 v[46:49], v[168:171], v[208:211], v[46:49]
	v_mfma_f32_16x16x32_bf16 v[38:41], v[158:161], v[216:219], v[38:41]
	v_mfma_f32_16x16x32_bf16 v[30:33], v[168:171], v[216:219], v[30:33]
	v_mfma_f32_16x16x32_bf16 v[22:25], v[158:161], v[224:227], v[22:25]
	v_mfma_f32_16x16x32_bf16 v[14:17], v[168:171], v[224:227], v[14:17]
	v_mfma_f32_16x16x32_bf16 v[50:53], v[180:183], v[196:199], v[50:53]
	v_mfma_f32_16x16x32_bf16 v[42:45], v[188:191], v[196:199], v[42:45]
	v_mfma_f32_16x16x32_bf16 v[34:37], v[180:183], v[204:207], v[34:37]
	v_mfma_f32_16x16x32_bf16 v[26:29], v[188:191], v[204:207], v[26:29]
	v_mfma_f32_16x16x32_bf16 v[18:21], v[180:183], v[212:215], v[18:21]
	v_mfma_f32_16x16x32_bf16 v[10:13], v[188:191], v[212:215], v[10:13]
	v_mfma_f32_16x16x32_bf16 v[6:9], v[180:183], v[220:223], v[6:9]
	v_mfma_f32_16x16x32_bf16 v[2:5], v[188:191], v[220:223], v[2:5]
	v_mfma_f32_16x16x32_bf16 v[50:53], v[184:187], v[200:203], v[50:53]
	v_mfma_f32_16x16x32_bf16 v[42:45], v[192:195], v[200:203], v[42:45]
	v_mfma_f32_16x16x32_bf16 v[34:37], v[184:187], v[208:211], v[34:37]
	v_mfma_f32_16x16x32_bf16 v[26:29], v[192:195], v[208:211], v[26:29]
	v_mfma_f32_16x16x32_bf16 v[18:21], v[184:187], v[216:219], v[18:21]
	v_mfma_f32_16x16x32_bf16 v[10:13], v[192:195], v[216:219], v[10:13]
	v_mfma_f32_16x16x32_bf16 v[6:9], v[184:187], v[224:227], v[6:9]
	v_mfma_f32_16x16x32_bf16 v[2:5], v[192:195], v[224:227], v[2:5]
	s_setprio 0
	s_barrier
	s_add_i32 s27, 0, 0x18000
	v_add_u32_e32 v153, s27, v173
	s_add_i32 s29, 0, 0x1c000
	ds_read_b128 v[154:157], v153
	ds_read_b128 v[158:161], v153 offset:1024
	ds_read_b128 v[164:167], v153 offset:2048
	ds_read_b128 v[168:171], v153 offset:3072
	v_add_u32_e32 v153, s29, v173
	ds_read_b128 v[180:183], v153
	ds_read_b128 v[184:187], v153 offset:1024
	ds_read_b128 v[188:191], v153 offset:2048
	ds_read_b128 v[192:195], v153 offset:3072
	s_add_u32 s20, s40, 0x20000
	s_addc_u32 s21, s41, 0
	s_mov_b32 m0, s51
	v_lshl_add_u64 v[236:237], s[20:21], 0, v[136:137]
	ds_read_b128 v[196:199], v177 offset:32768
	ds_read_b128 v[200:203], v177 offset:33792
	ds_read_b128 v[204:207], v177 offset:34816
	ds_read_b128 v[208:211], v177 offset:35840
	ds_read_b128 v[212:215], v177 offset:36864
	ds_read_b128 v[216:219], v177 offset:37888
	ds_read_b128 v[220:223], v177 offset:38912
	ds_read_b128 v[224:227], v177 offset:39936
	global_load_lds_dwordx4 v[236:237], off
	v_lshl_add_u64 v[236:237], s[20:21], 0, v[132:133]
	s_mov_b32 m0, s52
	s_nop 0
	global_load_lds_dwordx4 v[236:237], off
	s_waitcnt vmcnt(8)
	s_waitcnt lgkmcnt(0)
	v_mfma_f32_16x16x32_bf16 v[126:129], v[154:157], v[196:199], v[126:129]
	v_mfma_f32_16x16x32_bf16 v[122:125], v[164:167], v[196:199], v[122:125]
	v_mfma_f32_16x16x32_bf16 v[118:121], v[154:157], v[204:207], v[118:121]
	v_mfma_f32_16x16x32_bf16 v[110:113], v[164:167], v[204:207], v[110:113]
	s_barrier
	s_setprio 1
	v_mfma_f32_16x16x32_bf16 v[102:105], v[154:157], v[212:215], v[102:105]
	v_mfma_f32_16x16x32_bf16 v[94:97], v[164:167], v[212:215], v[94:97]
	v_mfma_f32_16x16x32_bf16 v[86:89], v[154:157], v[220:223], v[86:89]
	v_mfma_f32_16x16x32_bf16 v[78:81], v[164:167], v[220:223], v[78:81]
	v_mfma_f32_16x16x32_bf16 v[126:129], v[158:161], v[200:203], v[126:129]
	v_mfma_f32_16x16x32_bf16 v[122:125], v[168:171], v[200:203], v[122:125]
	v_mfma_f32_16x16x32_bf16 v[118:121], v[158:161], v[208:211], v[118:121]
	v_mfma_f32_16x16x32_bf16 v[110:113], v[168:171], v[208:211], v[110:113]
	v_mfma_f32_16x16x32_bf16 v[102:105], v[158:161], v[216:219], v[102:105]
	v_mfma_f32_16x16x32_bf16 v[94:97], v[168:171], v[216:219], v[94:97]
	v_mfma_f32_16x16x32_bf16 v[86:89], v[158:161], v[224:227], v[86:89]
	v_mfma_f32_16x16x32_bf16 v[78:81], v[168:171], v[224:227], v[78:81]
	v_mfma_f32_16x16x32_bf16 v[114:117], v[180:183], v[196:199], v[114:117]
	v_mfma_f32_16x16x32_bf16 v[106:109], v[188:191], v[196:199], v[106:109]
	v_mfma_f32_16x16x32_bf16 v[98:101], v[180:183], v[204:207], v[98:101]
	v_mfma_f32_16x16x32_bf16 v[90:93], v[188:191], v[204:207], v[90:93]
	v_mfma_f32_16x16x32_bf16 v[82:85], v[180:183], v[212:215], v[82:85]
	v_mfma_f32_16x16x32_bf16 v[74:77], v[188:191], v[212:215], v[74:77]
	v_mfma_f32_16x16x32_bf16 v[70:73], v[180:183], v[220:223], v[70:73]
	v_mfma_f32_16x16x32_bf16 v[66:69], v[188:191], v[220:223], v[66:69]
	v_mfma_f32_16x16x32_bf16 v[114:117], v[184:187], v[200:203], v[114:117]
	v_mfma_f32_16x16x32_bf16 v[106:109], v[192:195], v[200:203], v[106:109]
	v_mfma_f32_16x16x32_bf16 v[98:101], v[184:187], v[208:211], v[98:101]
	v_mfma_f32_16x16x32_bf16 v[90:93], v[192:195], v[208:211], v[90:93]
	v_mfma_f32_16x16x32_bf16 v[82:85], v[184:187], v[216:219], v[82:85]
	v_mfma_f32_16x16x32_bf16 v[74:77], v[192:195], v[216:219], v[74:77]
	v_mfma_f32_16x16x32_bf16 v[70:73], v[184:187], v[224:227], v[70:73]
	v_mfma_f32_16x16x32_bf16 v[66:69], v[192:195], v[224:227], v[66:69]
	s_setprio 0
	s_barrier
	s_add_i32 s20, s27, s46
	v_lshl_add_u64 v[228:229], v[228:229], 0, s[22:23]
	s_mov_b32 m0, s20
	ds_read_b128 v[196:199], v177 offset:49152
	ds_read_b128 v[200:203], v177 offset:50176
	ds_read_b128 v[204:207], v177 offset:51200
	ds_read_b128 v[208:211], v177 offset:52224
	ds_read_b128 v[212:215], v177 offset:53248
	ds_read_b128 v[216:219], v177 offset:54272
	ds_read_b128 v[220:223], v177 offset:55296
	ds_read_b128 v[224:227], v177 offset:56320
	global_load_lds_dwordx4 v[228:229], off
	s_add_i32 m0, s20, 0x2000
	s_add_u32 s20, s38, 0x20080
	v_lshl_add_u64 v[228:229], v[230:231], 0, s[22:23]
	s_addc_u32 s21, s39, 0
	s_add_i32 s27, s29, s46
	global_load_lds_dwordx4 v[228:229], off
	v_lshl_add_u64 v[228:229], s[20:21], 0, v[134:135]
	s_mov_b32 m0, s27
	s_nop 0
	global_load_lds_dwordx4 v[228:229], off
	v_lshl_add_u64 v[228:229], s[20:21], 0, v[130:131]
	s_add_i32 m0, s27, 0x2000
	s_nop 0
	global_load_lds_dwordx4 v[228:229], off
	v_lshl_add_u64 v[228:229], v[232:233], 0, s[22:23]
	s_mov_b32 m0, s53
	s_nop 0
	global_load_lds_dwordx4 v[228:229], off
	v_lshl_add_u64 v[228:229], v[234:235], 0, s[22:23]
	s_mov_b32 m0, s54
	s_nop 0
	global_load_lds_dwordx4 v[228:229], off
	s_waitcnt vmcnt(8)
	s_waitcnt lgkmcnt(0)
	v_mfma_f32_16x16x32_bf16 v[62:65], v[154:157], v[196:199], v[62:65]
	v_mfma_f32_16x16x32_bf16 v[58:61], v[164:167], v[196:199], v[58:61]
	v_mfma_f32_16x16x32_bf16 v[54:57], v[154:157], v[204:207], v[54:57]
	v_mfma_f32_16x16x32_bf16 v[46:49], v[164:167], v[204:207], v[46:49]
	s_barrier
	s_setprio 1
	v_mfma_f32_16x16x32_bf16 v[38:41], v[154:157], v[212:215], v[38:41]
	v_mfma_f32_16x16x32_bf16 v[30:33], v[164:167], v[212:215], v[30:33]
	v_mfma_f32_16x16x32_bf16 v[22:25], v[154:157], v[220:223], v[22:25]
	v_mfma_f32_16x16x32_bf16 v[14:17], v[164:167], v[220:223], v[14:17]
	v_mfma_f32_16x16x32_bf16 v[62:65], v[158:161], v[200:203], v[62:65]
	v_mfma_f32_16x16x32_bf16 v[58:61], v[168:171], v[200:203], v[58:61]
	v_mfma_f32_16x16x32_bf16 v[54:57], v[158:161], v[208:211], v[54:57]
	v_mfma_f32_16x16x32_bf16 v[46:49], v[168:171], v[208:211], v[46:49]
	v_mfma_f32_16x16x32_bf16 v[38:41], v[158:161], v[216:219], v[38:41]
	v_mfma_f32_16x16x32_bf16 v[30:33], v[168:171], v[216:219], v[30:33]
	v_mfma_f32_16x16x32_bf16 v[22:25], v[158:161], v[224:227], v[22:25]
	v_mfma_f32_16x16x32_bf16 v[14:17], v[168:171], v[224:227], v[14:17]
	v_mfma_f32_16x16x32_bf16 v[50:53], v[180:183], v[196:199], v[50:53]
	v_mfma_f32_16x16x32_bf16 v[42:45], v[188:191], v[196:199], v[42:45]
	v_mfma_f32_16x16x32_bf16 v[34:37], v[180:183], v[204:207], v[34:37]
	v_mfma_f32_16x16x32_bf16 v[26:29], v[188:191], v[204:207], v[26:29]
	v_mfma_f32_16x16x32_bf16 v[18:21], v[180:183], v[212:215], v[18:21]
	v_mfma_f32_16x16x32_bf16 v[10:13], v[188:191], v[212:215], v[10:13]
	v_mfma_f32_16x16x32_bf16 v[6:9], v[180:183], v[220:223], v[6:9]
	v_mfma_f32_16x16x32_bf16 v[2:5], v[188:191], v[220:223], v[2:5]
	v_mfma_f32_16x16x32_bf16 v[50:53], v[184:187], v[200:203], v[50:53]
	v_mfma_f32_16x16x32_bf16 v[42:45], v[192:195], v[200:203], v[42:45]
	v_mfma_f32_16x16x32_bf16 v[34:37], v[184:187], v[208:211], v[34:37]
	v_mfma_f32_16x16x32_bf16 v[26:29], v[192:195], v[208:211], v[26:29]
	v_mfma_f32_16x16x32_bf16 v[18:21], v[184:187], v[216:219], v[18:21]
	v_mfma_f32_16x16x32_bf16 v[10:13], v[192:195], v[216:219], v[10:13]
	v_mfma_f32_16x16x32_bf16 v[6:9], v[184:187], v[224:227], v[6:9]
	v_mfma_f32_16x16x32_bf16 v[2:5], v[192:195], v[224:227], v[2:5]
	s_setprio 0
	s_barrier
	s_add_i32 s19, s19, 2
	s_add_u32 s36, s36, 0x100
	s_addc_u32 s37, s37, 0
	s_add_u32 s17, s17, 0x100
	s_addc_u32 s18, s18, 0
	s_cmp_gt_u32 s19, 5
	s_cbranch_scc0 .LBB0_1336
	s_and_b64 vcc, exec, s[24:25]
	s_cbranch_vccz .LBB0_1339
	s_barrier

.LBB0_1497:
	ds_read_b128 v[134:137], v214
	ds_read_b128 v[138:141], v214 offset:1024
	ds_read_b128 v[142:145], v214 offset:2048
	ds_read_b128 v[178:181], v214 offset:3072
	ds_read_b128 v[182:185], v215
	ds_read_b128 v[186:189], v215 offset:1024
	ds_read_b128 v[190:193], v215 offset:2048
	ds_read_b128 v[194:197], v215 offset:3072
	s_add_u32 s40, s38, 0x100
	s_addc_u32 s41, s39, 0
	s_add_u32 s0, s15, s38
	s_addc_u32 s1, s16, s39
	s_cmp_eq_u32 s17, 28
	s_cselect_b32 s45, s3, s1
	s_cselect_b32 s1, 0, s40
	s_cselect_b32 s44, s14, s0
	s_cselect_b32 s0, 0, s41
	s_add_u32 s42, s10, s1
	s_addc_u32 s43, s11, s0
	s_mov_b32 m0, s64
	v_lshl_add_u64 v[244:245], v[130:131], 0, s[38:39]
	ds_read_b128 v[198:201], v216
	ds_read_b128 v[202:205], v216 offset:1024
	ds_read_b128 v[206:209], v216 offset:2048
	ds_read_b128 v[224:227], v216 offset:3072
	ds_read_b128 v[228:231], v216 offset:4096
	ds_read_b128 v[232:235], v216 offset:5120
	ds_read_b128 v[236:239], v216 offset:6144
	ds_read_b128 v[240:243], v216 offset:7168
	global_load_lds_dwordx4 v[244:245], off
	v_lshl_add_u64 v[244:245], v[132:133], 0, s[38:39]
	s_mov_b32 m0, s65
	s_nop 0
	global_load_lds_dwordx4 v[244:245], off
	s_waitcnt vmcnt(8)
	s_waitcnt lgkmcnt(0)
	v_mfma_f32_16x16x32_bf16 v[82:85], v[134:137], v[198:201], v[82:85]
	v_mfma_f32_16x16x32_bf16 v[78:81], v[142:145], v[198:201], v[78:81]
	v_mfma_f32_16x16x32_bf16 v[110:113], v[134:137], v[206:209], v[110:113]
	v_mfma_f32_16x16x32_bf16 v[106:109], v[142:145], v[206:209], v[106:109]
	s_barrier
	s_setprio 1
	v_mfma_f32_16x16x32_bf16 v[118:121], v[134:137], v[228:231], v[118:121]
	v_mfma_f32_16x16x32_bf16 v[114:117], v[142:145], v[228:231], v[114:117]
	v_mfma_f32_16x16x32_bf16 v[126:129], v[134:137], v[236:239], v[126:129]
	v_mfma_f32_16x16x32_bf16 v[122:125], v[142:145], v[236:239], v[122:125]
	v_mfma_f32_16x16x32_bf16 v[82:85], v[138:141], v[202:205], v[82:85]
	v_mfma_f32_16x16x32_bf16 v[78:81], v[178:181], v[202:205], v[78:81]
	v_mfma_f32_16x16x32_bf16 v[110:113], v[138:141], v[224:227], v[110:113]
	v_mfma_f32_16x16x32_bf16 v[106:109], v[178:181], v[224:227], v[106:109]
	v_mfma_f32_16x16x32_bf16 v[118:121], v[138:141], v[232:235], v[118:121]
	v_mfma_f32_16x16x32_bf16 v[114:117], v[178:181], v[232:235], v[114:117]
	v_mfma_f32_16x16x32_bf16 v[126:129], v[138:141], v[240:243], v[126:129]
	v_mfma_f32_16x16x32_bf16 v[122:125], v[178:181], v[240:243], v[122:125]
	v_mfma_f32_16x16x32_bf16 v[22:25], v[182:185], v[198:201], v[22:25]
	v_mfma_f32_16x16x32_bf16 v[26:29], v[190:193], v[198:201], v[26:29]
	v_mfma_f32_16x16x32_bf16 v[42:45], v[182:185], v[206:209], v[42:45]
	v_mfma_f32_16x16x32_bf16 v[46:49], v[190:193], v[206:209], v[46:49]
	v_mfma_f32_16x16x32_bf16 v[62:65], v[182:185], v[228:231], v[62:65]
	v_mfma_f32_16x16x32_bf16 v[70:73], v[190:193], v[228:231], v[70:73]
	v_mfma_f32_16x16x32_bf16 v[90:93], v[182:185], v[236:239], v[90:93]
	v_mfma_f32_16x16x32_bf16 v[94:97], v[190:193], v[236:239], v[94:97]
	v_mfma_f32_16x16x32_bf16 v[22:25], v[186:189], v[202:205], v[22:25]
	v_mfma_f32_16x16x32_bf16 v[26:29], v[194:197], v[202:205], v[26:29]
	v_mfma_f32_16x16x32_bf16 v[42:45], v[186:189], v[224:227], v[42:45]
	v_mfma_f32_16x16x32_bf16 v[46:49], v[194:197], v[224:227], v[46:49]
	v_mfma_f32_16x16x32_bf16 v[62:65], v[186:189], v[232:235], v[62:65]
	v_mfma_f32_16x16x32_bf16 v[70:73], v[194:197], v[232:235], v[70:73]
	v_mfma_f32_16x16x32_bf16 v[90:93], v[186:189], v[240:243], v[90:93]
	v_mfma_f32_16x16x32_bf16 v[94:97], v[194:197], v[240:243], v[94:97]
	s_setprio 0
	s_barrier
	s_mov_b32 m0, s66
	v_lshl_add_u64 v[244:245], s[42:43], 0, v[150:151]
	s_add_u32 s18, s42, 0x80000
	ds_read_b128 v[198:201], v216 offset:16384
	ds_read_b128 v[202:205], v216 offset:17408
	ds_read_b128 v[206:209], v216 offset:18432
	ds_read_b128 v[224:227], v216 offset:19456
	ds_read_b128 v[228:231], v216 offset:20480
	ds_read_b128 v[232:235], v216 offset:21504
	ds_read_b128 v[236:239], v216 offset:22528
	ds_read_b128 v[240:243], v216 offset:23552
	global_load_lds_dwordx4 v[244:245], off
	v_lshl_add_u64 v[246:247], s[42:43], 0, v[146:147]
	s_mov_b32 m0, s67
	s_addc_u32 s19, s43, 0
	global_load_lds_dwordx4 v[246:247], off
	v_lshl_add_u64 v[248:249], s[18:19], 0, v[150:151]
	s_mov_b32 m0, s68
	v_lshl_add_u64 v[250:251], s[44:45], 0, v[148:149]
	global_load_lds_dwordx4 v[248:249], off
	v_lshl_add_u64 v[248:249], s[18:19], 0, v[146:147]
	s_mov_b32 m0, s69
	s_nop 0
	global_load_lds_dwordx4 v[248:249], off
	v_lshl_add_u64 v[248:249], s[44:45], 0, v[152:153]
	s_mov_b32 m0, s9
	s_nop 0
	global_load_lds_dwordx4 v[248:249], off
	s_mov_b32 m0, s55
	s_nop 0
	global_load_lds_dwordx4 v[250:251], off
	s_waitcnt vmcnt(8)
	s_waitcnt lgkmcnt(0)
	v_mfma_f32_16x16x32_bf16 v[102:105], v[134:137], v[198:201], v[102:105]
	v_mfma_f32_16x16x32_bf16 v[98:101], v[142:145], v[198:201], v[98:101]
	v_mfma_f32_16x16x32_bf16 v[66:69], v[134:137], v[206:209], v[66:69]
	v_mfma_f32_16x16x32_bf16 v[58:61], v[142:145], v[206:209], v[58:61]
	s_barrier
	s_setprio 1
	v_mfma_f32_16x16x32_bf16 v[38:41], v[134:137], v[228:231], v[38:41]
	v_mfma_f32_16x16x32_bf16 v[34:37], v[142:145], v[228:231], v[34:37]
	v_mfma_f32_16x16x32_bf16 v[14:17], v[134:137], v[236:239], v[14:17]
	v_mfma_f32_16x16x32_bf16 v[10:13], v[142:145], v[236:239], v[10:13]
	v_mfma_f32_16x16x32_bf16 v[102:105], v[138:141], v[202:205], v[102:105]
	v_mfma_f32_16x16x32_bf16 v[98:101], v[178:181], v[202:205], v[98:101]
	v_mfma_f32_16x16x32_bf16 v[66:69], v[138:141], v[224:227], v[66:69]
	v_mfma_f32_16x16x32_bf16 v[58:61], v[178:181], v[224:227], v[58:61]
	v_mfma_f32_16x16x32_bf16 v[38:41], v[138:141], v[232:235], v[38:41]
	v_mfma_f32_16x16x32_bf16 v[34:37], v[178:181], v[232:235], v[34:37]
	v_mfma_f32_16x16x32_bf16 v[14:17], v[138:141], v[240:243], v[14:17]
	v_mfma_f32_16x16x32_bf16 v[10:13], v[178:181], v[240:243], v[10:13]
	v_mfma_f32_16x16x32_bf16 v[86:89], v[182:185], v[198:201], v[86:89]
	v_mfma_f32_16x16x32_bf16 v[74:77], v[190:193], v[198:201], v[74:77]
	v_mfma_f32_16x16x32_bf16 v[54:57], v[182:185], v[206:209], v[54:57]
	v_mfma_f32_16x16x32_bf16 v[50:53], v[190:193], v[206:209], v[50:53]
	v_mfma_f32_16x16x32_bf16 v[30:33], v[182:185], v[228:231], v[30:33]
	v_mfma_f32_16x16x32_bf16 v[18:21], v[190:193], v[228:231], v[18:21]
	v_mfma_f32_16x16x32_bf16 v[6:9], v[182:185], v[236:239], v[6:9]
	v_mfma_f32_16x16x32_bf16 v[2:5], v[190:193], v[236:239], v[2:5]
	v_mfma_f32_16x16x32_bf16 v[86:89], v[186:189], v[202:205], v[86:89]
	v_mfma_f32_16x16x32_bf16 v[74:77], v[194:197], v[202:205], v[74:77]
	v_mfma_f32_16x16x32_bf16 v[54:57], v[186:189], v[224:227], v[54:57]
	v_mfma_f32_16x16x32_bf16 v[50:53], v[194:197], v[224:227], v[50:53]
	v_mfma_f32_16x16x32_bf16 v[30:33], v[186:189], v[232:235], v[30:33]
	v_mfma_f32_16x16x32_bf16 v[18:21], v[194:197], v[232:235], v[18:21]
	v_mfma_f32_16x16x32_bf16 v[6:9], v[186:189], v[240:243], v[6:9]
	v_mfma_f32_16x16x32_bf16 v[2:5], v[194:197], v[240:243], v[2:5]
	s_setprio 0
	s_barrier
	s_add_i32 s0, 0, 0x1c000
	v_add_u32_e32 v194, s0, v212
	ds_read_b128 v[134:137], v220
	ds_read_b128 v[138:141], v220 offset:1024
	ds_read_b128 v[142:145], v220 offset:2048
	ds_read_b128 v[178:181], v220 offset:3072
	ds_read_b128 v[182:185], v194
	ds_read_b128 v[186:189], v194 offset:1024
	ds_read_b128 v[190:193], v194 offset:2048
	ds_read_b128 v[194:197], v194 offset:3072
	s_add_u32 s18, s44, 0x80000
	s_addc_u32 s19, s45, 0
	s_mov_b32 m0, s56
	v_lshl_add_u64 v[252:253], s[18:19], 0, v[152:153]
	ds_read_b128 v[198:201], v216 offset:32768
	ds_read_b128 v[202:205], v216 offset:33792
	ds_read_b128 v[206:209], v216 offset:34816
	ds_read_b128 v[224:227], v216 offset:35840
	ds_read_b128 v[228:231], v216 offset:36864
	ds_read_b128 v[232:235], v216 offset:37888
	ds_read_b128 v[236:239], v216 offset:38912
	ds_read_b128 v[240:243], v216 offset:39936
	global_load_lds_dwordx4 v[252:253], off
	v_lshl_add_u64 v[252:253], s[18:19], 0, v[148:149]
	s_mov_b32 m0, s57
	s_nop 0
	global_load_lds_dwordx4 v[252:253], off
	s_waitcnt vmcnt(8)
	s_waitcnt lgkmcnt(0)
	v_mfma_f32_16x16x32_bf16 v[82:85], v[134:137], v[198:201], v[82:85]
	v_mfma_f32_16x16x32_bf16 v[78:81], v[142:145], v[198:201], v[78:81]
	v_mfma_f32_16x16x32_bf16 v[110:113], v[134:137], v[206:209], v[110:113]
	v_mfma_f32_16x16x32_bf16 v[106:109], v[142:145], v[206:209], v[106:109]
	s_barrier
	s_setprio 1
	v_mfma_f32_16x16x32_bf16 v[118:121], v[134:137], v[228:231], v[118:121]
	v_mfma_f32_16x16x32_bf16 v[114:117], v[142:145], v[228:231], v[114:117]
	v_mfma_f32_16x16x32_bf16 v[126:129], v[134:137], v[236:239], v[126:129]
	v_mfma_f32_16x16x32_bf16 v[122:125], v[142:145], v[236:239], v[122:125]
	v_mfma_f32_16x16x32_bf16 v[82:85], v[138:141], v[202:205], v[82:85]
	v_mfma_f32_16x16x32_bf16 v[78:81], v[178:181], v[202:205], v[78:81]
	v_mfma_f32_16x16x32_bf16 v[110:113], v[138:141], v[224:227], v[110:113]
	v_mfma_f32_16x16x32_bf16 v[106:109], v[178:181], v[224:227], v[106:109]
	v_mfma_f32_16x16x32_bf16 v[118:121], v[138:141], v[232:235], v[118:121]
	v_mfma_f32_16x16x32_bf16 v[114:117], v[178:181], v[232:235], v[114:117]
	v_mfma_f32_16x16x32_bf16 v[126:129], v[138:141], v[240:243], v[126:129]
	v_mfma_f32_16x16x32_bf16 v[122:125], v[178:181], v[240:243], v[122:125]
	v_mfma_f32_16x16x32_bf16 v[22:25], v[182:185], v[198:201], v[22:25]
	v_mfma_f32_16x16x32_bf16 v[26:29], v[190:193], v[198:201], v[26:29]
	v_mfma_f32_16x16x32_bf16 v[42:45], v[182:185], v[206:209], v[42:45]
	v_mfma_f32_16x16x32_bf16 v[46:49], v[190:193], v[206:209], v[46:49]
	v_mfma_f32_16x16x32_bf16 v[62:65], v[182:185], v[228:231], v[62:65]
	v_mfma_f32_16x16x32_bf16 v[70:73], v[190:193], v[228:231], v[70:73]
	v_mfma_f32_16x16x32_bf16 v[90:93], v[182:185], v[236:239], v[90:93]
	v_mfma_f32_16x16x32_bf16 v[94:97], v[190:193], v[236:239], v[94:97]
	v_mfma_f32_16x16x32_bf16 v[22:25], v[186:189], v[202:205], v[22:25]
	v_mfma_f32_16x16x32_bf16 v[26:29], v[194:197], v[202:205], v[26:29]
	v_mfma_f32_16x16x32_bf16 v[42:45], v[186:189], v[224:227], v[42:45]
	v_mfma_f32_16x16x32_bf16 v[46:49], v[194:197], v[224:227], v[46:49]
	v_mfma_f32_16x16x32_bf16 v[62:65], v[186:189], v[232:235], v[62:65]
	v_mfma_f32_16x16x32_bf16 v[70:73], v[194:197], v[232:235], v[70:73]
	v_mfma_f32_16x16x32_bf16 v[90:93], v[186:189], v[240:243], v[90:93]
	v_mfma_f32_16x16x32_bf16 v[94:97], v[194:197], v[240:243], v[94:97]
	s_setprio 0
	s_barrier
	s_add_i32 s1, s72, s54
	v_lshl_add_u64 v[244:245], v[244:245], 0, s[26:27]
	s_mov_b32 m0, s1
	ds_read_b128 v[198:201], v216 offset:49152
	ds_read_b128 v[202:205], v216 offset:50176
	ds_read_b128 v[206:209], v216 offset:51200
	ds_read_b128 v[224:227], v216 offset:52224
	ds_read_b128 v[228:231], v216 offset:53248
	ds_read_b128 v[232:235], v216 offset:54272
	ds_read_b128 v[236:239], v216 offset:55296
	ds_read_b128 v[240:243], v216 offset:56320
	global_load_lds_dwordx4 v[244:245], off
	s_add_i32 m0, s1, 0x2000
	s_add_u32 s18, s42, 0x80080
	v_lshl_add_u64 v[244:245], v[246:247], 0, s[26:27]
	s_addc_u32 s19, s43, 0
	s_add_i32 s0, s0, s54
	global_load_lds_dwordx4 v[244:245], off
	v_lshl_add_u64 v[244:245], s[18:19], 0, v[150:151]
	s_mov_b32 m0, s0
	s_nop 0
	global_load_lds_dwordx4 v[244:245], off
	v_lshl_add_u64 v[244:245], s[18:19], 0, v[146:147]
	s_add_i32 m0, s0, 0x2000
	s_nop 0
	global_load_lds_dwordx4 v[244:245], off
	v_lshl_add_u64 v[244:245], v[248:249], 0, s[26:27]
	s_mov_b32 m0, s61
	s_nop 0
	global_load_lds_dwordx4 v[244:245], off
	v_lshl_add_u64 v[244:245], v[250:251], 0, s[26:27]
	s_mov_b32 m0, s62
	s_nop 0
	global_load_lds_dwordx4 v[244:245], off
	s_waitcnt vmcnt(8)
	s_waitcnt lgkmcnt(0)
	v_mfma_f32_16x16x32_bf16 v[102:105], v[134:137], v[198:201], v[102:105]
	v_mfma_f32_16x16x32_bf16 v[98:101], v[142:145], v[198:201], v[98:101]
	v_mfma_f32_16x16x32_bf16 v[66:69], v[134:137], v[206:209], v[66:69]
	v_mfma_f32_16x16x32_bf16 v[58:61], v[142:145], v[206:209], v[58:61]
	s_barrier
	s_setprio 1
	v_mfma_f32_16x16x32_bf16 v[38:41], v[134:137], v[228:231], v[38:41]
	v_mfma_f32_16x16x32_bf16 v[34:37], v[142:145], v[228:231], v[34:37]
	v_mfma_f32_16x16x32_bf16 v[14:17], v[134:137], v[236:239], v[14:17]
	v_mfma_f32_16x16x32_bf16 v[10:13], v[142:145], v[236:239], v[10:13]
	v_mfma_f32_16x16x32_bf16 v[102:105], v[138:141], v[202:205], v[102:105]
	v_mfma_f32_16x16x32_bf16 v[98:101], v[178:181], v[202:205], v[98:101]
	v_mfma_f32_16x16x32_bf16 v[66:69], v[138:141], v[224:227], v[66:69]
	v_mfma_f32_16x16x32_bf16 v[58:61], v[178:181], v[224:227], v[58:61]
	v_mfma_f32_16x16x32_bf16 v[38:41], v[138:141], v[232:235], v[38:41]
	v_mfma_f32_16x16x32_bf16 v[34:37], v[178:181], v[232:235], v[34:37]
	v_mfma_f32_16x16x32_bf16 v[14:17], v[138:141], v[240:243], v[14:17]
	v_mfma_f32_16x16x32_bf16 v[10:13], v[178:181], v[240:243], v[10:13]
	v_mfma_f32_16x16x32_bf16 v[86:89], v[182:185], v[198:201], v[86:89]
	v_mfma_f32_16x16x32_bf16 v[74:77], v[190:193], v[198:201], v[74:77]
	v_mfma_f32_16x16x32_bf16 v[54:57], v[182:185], v[206:209], v[54:57]
	v_mfma_f32_16x16x32_bf16 v[50:53], v[190:193], v[206:209], v[50:53]
	v_mfma_f32_16x16x32_bf16 v[30:33], v[182:185], v[228:231], v[30:33]
	v_mfma_f32_16x16x32_bf16 v[18:21], v[190:193], v[228:231], v[18:21]
	v_mfma_f32_16x16x32_bf16 v[6:9], v[182:185], v[236:239], v[6:9]
	v_mfma_f32_16x16x32_bf16 v[2:5], v[190:193], v[236:239], v[2:5]
	v_mfma_f32_16x16x32_bf16 v[86:89], v[186:189], v[202:205], v[86:89]
	v_mfma_f32_16x16x32_bf16 v[74:77], v[194:197], v[202:205], v[74:77]
	v_mfma_f32_16x16x32_bf16 v[54:57], v[186:189], v[224:227], v[54:57]
	v_mfma_f32_16x16x32_bf16 v[50:53], v[194:197], v[224:227], v[50:53]
	v_mfma_f32_16x16x32_bf16 v[30:33], v[186:189], v[232:235], v[30:33]
	v_mfma_f32_16x16x32_bf16 v[18:21], v[194:197], v[232:235], v[18:21]
	v_mfma_f32_16x16x32_bf16 v[6:9], v[186:189], v[240:243], v[6:9]
	v_mfma_f32_16x16x32_bf16 v[2:5], v[194:197], v[240:243], v[2:5]
	s_setprio 0
	s_barrier
	s_add_i32 s17, s17, 2
	s_cmp_gt_u32 s17, 29
	s_mov_b64 s[38:39], s[40:41]
	s_cbranch_scc0 .LBB0_1497
	s_and_b64 vcc, exec, s[28:29]
	s_cbranch_vccz .LBB0_1500
	s_barrier

.LBB0_1604:
	ds_read_b128 v[154:157], v151
	ds_read_b128 v[158:161], v151 offset:1024
	ds_read_b128 v[164:167], v151 offset:2048
	ds_read_b128 v[168:171], v151 offset:3072
	ds_read_b128 v[172:175], v152
	ds_read_b128 v[176:179], v152 offset:1024
	ds_read_b128 v[180:183], v152 offset:2048
	ds_read_b128 v[184:187], v152 offset:3072
	s_add_u32 s0, s34, 0xfff80080
	s_addc_u32 s1, s35, -1
	s_cmp_eq_u32 s53, 28
	s_cselect_b32 s39, s16, s1
	s_cselect_b32 s38, s17, s0
	s_cselect_b32 s37, s18, s25
	s_cselect_b32 s36, s19, s23
	v_lshl_add_u64 v[146:147], s[34:35], 0, v[138:139]
	s_add_i32 m0, s31, 0xc000
	ds_read_b128 v[188:191], v153
	ds_read_b128 v[192:195], v153 offset:1024
	ds_read_b128 v[196:199], v153 offset:2048
	ds_read_b128 v[200:203], v153 offset:3072
	ds_read_b128 v[204:207], v153 offset:4096
	ds_read_b128 v[208:211], v153 offset:5120
	ds_read_b128 v[212:215], v153 offset:6144
	ds_read_b128 v[216:219], v153 offset:7168
	global_load_lds_dwordx4 v[146:147], off
	v_lshl_add_u64 v[146:147], s[34:35], 0, v[140:141]
	s_add_i32 m0, s31, 0xe000
	s_nop 0
	global_load_lds_dwordx4 v[146:147], off
	s_waitcnt vmcnt(8)
	s_waitcnt lgkmcnt(0)
	v_mfma_f32_16x16x32_bf16 v[126:129], v[154:157], v[188:191], v[126:129]
	v_mfma_f32_16x16x32_bf16 v[122:125], v[164:167], v[188:191], v[122:125]
	v_mfma_f32_16x16x32_bf16 v[110:113], v[154:157], v[196:199], v[110:113]
	v_mfma_f32_16x16x32_bf16 v[106:109], v[164:167], v[196:199], v[106:109]
	s_barrier
	s_setprio 1
	v_mfma_f32_16x16x32_bf16 v[94:97], v[154:157], v[204:207], v[94:97]
	v_mfma_f32_16x16x32_bf16 v[90:93], v[164:167], v[204:207], v[90:93]
	v_mfma_f32_16x16x32_bf16 v[78:81], v[154:157], v[212:215], v[78:81]
	v_mfma_f32_16x16x32_bf16 v[74:77], v[164:167], v[212:215], v[74:77]
	v_mfma_f32_16x16x32_bf16 v[126:129], v[158:161], v[192:195], v[126:129]
	v_mfma_f32_16x16x32_bf16 v[122:125], v[168:171], v[192:195], v[122:125]
	v_mfma_f32_16x16x32_bf16 v[110:113], v[158:161], v[200:203], v[110:113]
	v_mfma_f32_16x16x32_bf16 v[106:109], v[168:171], v[200:203], v[106:109]
	v_mfma_f32_16x16x32_bf16 v[94:97], v[158:161], v[208:211], v[94:97]
	v_mfma_f32_16x16x32_bf16 v[90:93], v[168:171], v[208:211], v[90:93]
	v_mfma_f32_16x16x32_bf16 v[78:81], v[158:161], v[216:219], v[78:81]
	v_mfma_f32_16x16x32_bf16 v[74:77], v[168:171], v[216:219], v[74:77]
	v_mfma_f32_16x16x32_bf16 v[118:121], v[172:175], v[188:191], v[118:121]
	v_mfma_f32_16x16x32_bf16 v[114:117], v[180:183], v[188:191], v[114:117]
	v_mfma_f32_16x16x32_bf16 v[102:105], v[172:175], v[196:199], v[102:105]
	v_mfma_f32_16x16x32_bf16 v[98:101], v[180:183], v[196:199], v[98:101]
	v_mfma_f32_16x16x32_bf16 v[86:89], v[172:175], v[204:207], v[86:89]
	v_mfma_f32_16x16x32_bf16 v[82:85], v[180:183], v[204:207], v[82:85]
	v_mfma_f32_16x16x32_bf16 v[70:73], v[172:175], v[212:215], v[70:73]
	v_mfma_f32_16x16x32_bf16 v[66:69], v[180:183], v[212:215], v[66:69]
	v_mfma_f32_16x16x32_bf16 v[118:121], v[176:179], v[192:195], v[118:121]
	v_mfma_f32_16x16x32_bf16 v[114:117], v[184:187], v[192:195], v[114:117]
	v_mfma_f32_16x16x32_bf16 v[102:105], v[176:179], v[200:203], v[102:105]
	v_mfma_f32_16x16x32_bf16 v[98:101], v[184:187], v[200:203], v[98:101]
	v_mfma_f32_16x16x32_bf16 v[86:89], v[176:179], v[208:211], v[86:89]
	v_mfma_f32_16x16x32_bf16 v[82:85], v[184:187], v[208:211], v[82:85]
	v_mfma_f32_16x16x32_bf16 v[70:73], v[176:179], v[216:219], v[70:73]
	v_mfma_f32_16x16x32_bf16 v[66:69], v[184:187], v[216:219], v[66:69]
	s_setprio 0
	s_barrier
	s_add_i32 s0, s15, s44
	v_lshl_add_u64 v[146:147], s[36:37], 0, v[134:135]
	s_mov_b32 m0, s0
	ds_read_b128 v[188:191], v153 offset:16384
	ds_read_b128 v[192:195], v153 offset:17408
	ds_read_b128 v[196:199], v153 offset:18432
	ds_read_b128 v[200:203], v153 offset:19456
	ds_read_b128 v[204:207], v153 offset:20480
	ds_read_b128 v[208:211], v153 offset:21504
	ds_read_b128 v[212:215], v153 offset:22528
	ds_read_b128 v[216:219], v153 offset:23552
	global_load_lds_dwordx4 v[146:147], off
	s_add_i32 m0, s0, 0x2000
	s_add_u32 s54, s36, 0x80000
	v_lshl_add_u64 v[220:221], s[36:37], 0, v[130:131]
	s_addc_u32 s55, s37, 0
	s_add_i32 s0, s51, s44
	global_load_lds_dwordx4 v[220:221], off
	v_lshl_add_u64 v[222:223], s[54:55], 0, v[134:135]
	s_mov_b32 m0, s0
	v_lshl_add_u64 v[224:225], s[38:39], 0, v[132:133]
	global_load_lds_dwordx4 v[222:223], off
	v_lshl_add_u64 v[222:223], s[54:55], 0, v[130:131]
	s_add_i32 m0, s0, 0x2000
	s_nop 0
	global_load_lds_dwordx4 v[222:223], off
	v_lshl_add_u64 v[222:223], s[38:39], 0, v[136:137]
	s_mov_b32 m0, s31
	s_nop 0
	global_load_lds_dwordx4 v[222:223], off
	s_mov_b32 m0, s47
	s_nop 0
	global_load_lds_dwordx4 v[224:225], off
	s_waitcnt vmcnt(8)
	s_waitcnt lgkmcnt(0)
	v_mfma_f32_16x16x32_bf16 v[62:65], v[154:157], v[188:191], v[62:65]
	v_mfma_f32_16x16x32_bf16 v[58:61], v[164:167], v[188:191], v[58:61]
	v_mfma_f32_16x16x32_bf16 v[46:49], v[154:157], v[196:199], v[46:49]
	v_mfma_f32_16x16x32_bf16 v[42:45], v[164:167], v[196:199], v[42:45]
	s_barrier
	s_setprio 1
	v_mfma_f32_16x16x32_bf16 v[30:33], v[154:157], v[204:207], v[30:33]
	v_mfma_f32_16x16x32_bf16 v[26:29], v[164:167], v[204:207], v[26:29]
	v_mfma_f32_16x16x32_bf16 v[14:17], v[154:157], v[212:215], v[14:17]
	v_mfma_f32_16x16x32_bf16 v[10:13], v[164:167], v[212:215], v[10:13]
	v_mfma_f32_16x16x32_bf16 v[62:65], v[158:161], v[192:195], v[62:65]
	v_mfma_f32_16x16x32_bf16 v[58:61], v[168:171], v[192:195], v[58:61]
	v_mfma_f32_16x16x32_bf16 v[46:49], v[158:161], v[200:203], v[46:49]
	v_mfma_f32_16x16x32_bf16 v[42:45], v[168:171], v[200:203], v[42:45]
	v_mfma_f32_16x16x32_bf16 v[30:33], v[158:161], v[208:211], v[30:33]
	v_mfma_f32_16x16x32_bf16 v[26:29], v[168:171], v[208:211], v[26:29]
	v_mfma_f32_16x16x32_bf16 v[14:17], v[158:161], v[216:219], v[14:17]
	v_mfma_f32_16x16x32_bf16 v[10:13], v[168:171], v[216:219], v[10:13]
	v_mfma_f32_16x16x32_bf16 v[54:57], v[172:175], v[188:191], v[54:57]
	v_mfma_f32_16x16x32_bf16 v[50:53], v[180:183], v[188:191], v[50:53]
	v_mfma_f32_16x16x32_bf16 v[38:41], v[172:175], v[196:199], v[38:41]
	v_mfma_f32_16x16x32_bf16 v[34:37], v[180:183], v[196:199], v[34:37]
	v_mfma_f32_16x16x32_bf16 v[22:25], v[172:175], v[204:207], v[22:25]
	v_mfma_f32_16x16x32_bf16 v[18:21], v[180:183], v[204:207], v[18:21]
	v_mfma_f32_16x16x32_bf16 v[6:9], v[172:175], v[212:215], v[6:9]
	v_mfma_f32_16x16x32_bf16 v[2:5], v[180:183], v[212:215], v[2:5]
	v_mfma_f32_16x16x32_bf16 v[54:57], v[176:179], v[192:195], v[54:57]
	v_mfma_f32_16x16x32_bf16 v[50:53], v[184:187], v[192:195], v[50:53]
	v_mfma_f32_16x16x32_bf16 v[38:41], v[176:179], v[200:203], v[38:41]
	v_mfma_f32_16x16x32_bf16 v[34:37], v[184:187], v[200:203], v[34:37]
	v_mfma_f32_16x16x32_bf16 v[22:25], v[176:179], v[208:211], v[22:25]
	v_mfma_f32_16x16x32_bf16 v[18:21], v[184:187], v[208:211], v[18:21]
	v_mfma_f32_16x16x32_bf16 v[6:9], v[176:179], v[216:219], v[6:9]
	v_mfma_f32_16x16x32_bf16 v[2:5], v[184:187], v[216:219], v[2:5]
	s_setprio 0
	s_barrier
	s_add_i32 s0, 0, 0x18000
	v_add_u32_e32 v163, s0, v149
	s_add_i32 s1, 0, 0x1c000
	ds_read_b128 v[154:157], v163
	ds_read_b128 v[158:161], v163 offset:1024
	ds_read_b128 v[164:167], v163 offset:2048
	ds_read_b128 v[168:171], v163 offset:3072
	v_add_u32_e32 v163, s1, v149
	ds_read_b128 v[172:175], v163
	ds_read_b128 v[176:179], v163 offset:1024
	ds_read_b128 v[180:183], v163 offset:2048
	ds_read_b128 v[184:187], v163 offset:3072
	s_add_u32 s38, s38, 0x80000
	s_addc_u32 s39, s39, 0
	s_mov_b32 m0, s48
	v_lshl_add_u64 v[226:227], s[38:39], 0, v[136:137]
	ds_read_b128 v[188:191], v153 offset:32768
	ds_read_b128 v[192:195], v153 offset:33792
	ds_read_b128 v[196:199], v153 offset:34816
	ds_read_b128 v[200:203], v153 offset:35840
	ds_read_b128 v[204:207], v153 offset:36864
	ds_read_b128 v[208:211], v153 offset:37888
	ds_read_b128 v[212:215], v153 offset:38912
	ds_read_b128 v[216:219], v153 offset:39936
	global_load_lds_dwordx4 v[226:227], off
	v_lshl_add_u64 v[226:227], s[38:39], 0, v[132:133]
	s_mov_b32 m0, s49
	s_nop 0
	global_load_lds_dwordx4 v[226:227], off
	s_waitcnt vmcnt(8)
	s_waitcnt lgkmcnt(0)
	v_mfma_f32_16x16x32_bf16 v[126:129], v[154:157], v[188:191], v[126:129]
	v_mfma_f32_16x16x32_bf16 v[122:125], v[164:167], v[188:191], v[122:125]
	v_mfma_f32_16x16x32_bf16 v[110:113], v[154:157], v[196:199], v[110:113]
	v_mfma_f32_16x16x32_bf16 v[106:109], v[164:167], v[196:199], v[106:109]
	s_barrier
	s_setprio 1
	v_mfma_f32_16x16x32_bf16 v[94:97], v[154:157], v[204:207], v[94:97]
	v_mfma_f32_16x16x32_bf16 v[90:93], v[164:167], v[204:207], v[90:93]
	v_mfma_f32_16x16x32_bf16 v[78:81], v[154:157], v[212:215], v[78:81]
	v_mfma_f32_16x16x32_bf16 v[74:77], v[164:167], v[212:215], v[74:77]
	v_mfma_f32_16x16x32_bf16 v[126:129], v[158:161], v[192:195], v[126:129]
	v_mfma_f32_16x16x32_bf16 v[122:125], v[168:171], v[192:195], v[122:125]
	v_mfma_f32_16x16x32_bf16 v[110:113], v[158:161], v[200:203], v[110:113]
	v_mfma_f32_16x16x32_bf16 v[106:109], v[168:171], v[200:203], v[106:109]
	v_mfma_f32_16x16x32_bf16 v[94:97], v[158:161], v[208:211], v[94:97]
	v_mfma_f32_16x16x32_bf16 v[90:93], v[168:171], v[208:211], v[90:93]
	v_mfma_f32_16x16x32_bf16 v[78:81], v[158:161], v[216:219], v[78:81]
	v_mfma_f32_16x16x32_bf16 v[74:77], v[168:171], v[216:219], v[74:77]
	v_mfma_f32_16x16x32_bf16 v[118:121], v[172:175], v[188:191], v[118:121]
	v_mfma_f32_16x16x32_bf16 v[114:117], v[180:183], v[188:191], v[114:117]
	v_mfma_f32_16x16x32_bf16 v[102:105], v[172:175], v[196:199], v[102:105]
	v_mfma_f32_16x16x32_bf16 v[98:101], v[180:183], v[196:199], v[98:101]
	v_mfma_f32_16x16x32_bf16 v[86:89], v[172:175], v[204:207], v[86:89]
	v_mfma_f32_16x16x32_bf16 v[82:85], v[180:183], v[204:207], v[82:85]
	v_mfma_f32_16x16x32_bf16 v[70:73], v[172:175], v[212:215], v[70:73]
	v_mfma_f32_16x16x32_bf16 v[66:69], v[180:183], v[212:215], v[66:69]
	v_mfma_f32_16x16x32_bf16 v[118:121], v[176:179], v[192:195], v[118:121]
	v_mfma_f32_16x16x32_bf16 v[114:117], v[184:187], v[192:195], v[114:117]
	v_mfma_f32_16x16x32_bf16 v[102:105], v[176:179], v[200:203], v[102:105]
	v_mfma_f32_16x16x32_bf16 v[98:101], v[184:187], v[200:203], v[98:101]
	v_mfma_f32_16x16x32_bf16 v[86:89], v[176:179], v[208:211], v[86:89]
	v_mfma_f32_16x16x32_bf16 v[82:85], v[184:187], v[208:211], v[82:85]
	v_mfma_f32_16x16x32_bf16 v[70:73], v[176:179], v[216:219], v[70:73]
	v_mfma_f32_16x16x32_bf16 v[66:69], v[184:187], v[216:219], v[66:69]
	s_setprio 0
	s_barrier
	s_add_i32 s0, s0, s44
	v_lshl_add_u64 v[146:147], v[146:147], 0, s[10:11]
	s_mov_b32 m0, s0
	ds_read_b128 v[188:191], v153 offset:49152
	ds_read_b128 v[192:195], v153 offset:50176
	ds_read_b128 v[196:199], v153 offset:51200
	ds_read_b128 v[200:203], v153 offset:52224
	ds_read_b128 v[204:207], v153 offset:53248
	ds_read_b128 v[208:211], v153 offset:54272
	ds_read_b128 v[212:215], v153 offset:55296
	ds_read_b128 v[216:219], v153 offset:56320
	global_load_lds_dwordx4 v[146:147], off
	s_add_i32 m0, s0, 0x2000
	s_add_u32 s36, s36, 0x80080
	v_lshl_add_u64 v[146:147], v[220:221], 0, s[10:11]
	s_addc_u32 s37, s37, 0
	s_add_i32 s0, s1, s44
	global_load_lds_dwordx4 v[146:147], off
	v_lshl_add_u64 v[146:147], s[36:37], 0, v[134:135]
	s_mov_b32 m0, s0
	s_nop 0
	global_load_lds_dwordx4 v[146:147], off
	v_lshl_add_u64 v[146:147], s[36:37], 0, v[130:131]
	s_add_i32 m0, s0, 0x2000
	s_nop 0
	global_load_lds_dwordx4 v[146:147], off
	v_lshl_add_u64 v[146:147], v[222:223], 0, s[10:11]
	s_mov_b32 m0, s20
	s_nop 0
	global_load_lds_dwordx4 v[146:147], off
	v_lshl_add_u64 v[146:147], v[224:225], 0, s[10:11]
	s_mov_b32 m0, s21
	s_nop 0
	global_load_lds_dwordx4 v[146:147], off
	s_waitcnt vmcnt(8)
	s_waitcnt lgkmcnt(0)
	v_mfma_f32_16x16x32_bf16 v[62:65], v[154:157], v[188:191], v[62:65]
	v_mfma_f32_16x16x32_bf16 v[58:61], v[164:167], v[188:191], v[58:61]
	v_mfma_f32_16x16x32_bf16 v[46:49], v[154:157], v[196:199], v[46:49]
	v_mfma_f32_16x16x32_bf16 v[42:45], v[164:167], v[196:199], v[42:45]
	s_barrier
	s_setprio 1
	v_mfma_f32_16x16x32_bf16 v[30:33], v[154:157], v[204:207], v[30:33]
	v_mfma_f32_16x16x32_bf16 v[26:29], v[164:167], v[204:207], v[26:29]
	v_mfma_f32_16x16x32_bf16 v[14:17], v[154:157], v[212:215], v[14:17]
	v_mfma_f32_16x16x32_bf16 v[10:13], v[164:167], v[212:215], v[10:13]
	v_mfma_f32_16x16x32_bf16 v[62:65], v[158:161], v[192:195], v[62:65]
	v_mfma_f32_16x16x32_bf16 v[58:61], v[168:171], v[192:195], v[58:61]
	v_mfma_f32_16x16x32_bf16 v[46:49], v[158:161], v[200:203], v[46:49]
	v_mfma_f32_16x16x32_bf16 v[42:45], v[168:171], v[200:203], v[42:45]
	v_mfma_f32_16x16x32_bf16 v[30:33], v[158:161], v[208:211], v[30:33]
	v_mfma_f32_16x16x32_bf16 v[26:29], v[168:171], v[208:211], v[26:29]
	v_mfma_f32_16x16x32_bf16 v[14:17], v[158:161], v[216:219], v[14:17]
	v_mfma_f32_16x16x32_bf16 v[10:13], v[168:171], v[216:219], v[10:13]
	v_mfma_f32_16x16x32_bf16 v[54:57], v[172:175], v[188:191], v[54:57]
	v_mfma_f32_16x16x32_bf16 v[50:53], v[180:183], v[188:191], v[50:53]
	v_mfma_f32_16x16x32_bf16 v[38:41], v[172:175], v[196:199], v[38:41]
	v_mfma_f32_16x16x32_bf16 v[34:37], v[180:183], v[196:199], v[34:37]
	v_mfma_f32_16x16x32_bf16 v[22:25], v[172:175], v[204:207], v[22:25]
	v_mfma_f32_16x16x32_bf16 v[18:21], v[180:183], v[204:207], v[18:21]
	v_mfma_f32_16x16x32_bf16 v[6:9], v[172:175], v[212:215], v[6:9]
	v_mfma_f32_16x16x32_bf16 v[2:5], v[180:183], v[212:215], v[2:5]
	v_mfma_f32_16x16x32_bf16 v[54:57], v[176:179], v[192:195], v[54:57]
	v_mfma_f32_16x16x32_bf16 v[50:53], v[184:187], v[192:195], v[50:53]
	v_mfma_f32_16x16x32_bf16 v[38:41], v[176:179], v[200:203], v[38:41]
	v_mfma_f32_16x16x32_bf16 v[34:37], v[184:187], v[200:203], v[34:37]
	v_mfma_f32_16x16x32_bf16 v[22:25], v[176:179], v[208:211], v[22:25]
	v_mfma_f32_16x16x32_bf16 v[18:21], v[184:187], v[208:211], v[18:21]
	v_mfma_f32_16x16x32_bf16 v[6:9], v[176:179], v[216:219], v[6:9]
	v_mfma_f32_16x16x32_bf16 v[2:5], v[184:187], v[216:219], v[2:5]
	s_setprio 0
	s_barrier
	s_add_i32 s53, s53, 2
	s_add_u32 s34, s34, 0x100
	s_addc_u32 s35, s35, 0
	s_add_u32 s23, s23, 0x100
	s_addc_u32 s25, s25, 0
	s_cmp_gt_u32 s53, 29
	s_cbranch_scc0 .LBB0_1604
	s_and_b64 vcc, exec, s[12:13]
	s_cbranch_vccz .LBB0_1607
	s_barrier

.LBB0_1675:
	ds_read_b128 v[156:159], v191
	ds_read_b128 v[160:163], v191 offset:1024
	ds_read_b128 v[164:167], v191 offset:2048
	ds_read_b128 v[168:171], v191 offset:3072
	ds_read_b128 v[172:175], v192
	ds_read_b128 v[176:179], v192 offset:1024
	ds_read_b128 v[180:183], v192 offset:2048
	ds_read_b128 v[184:187], v192 offset:3072
	s_add_u32 s36, s30, 0xffea0080
	s_addc_u32 s37, s31, -1
	s_cmpk_eq_i32 s29, 0x54
	s_cselect_b32 s39, s25, s37
	s_cselect_b32 s38, s24, s36
	s_cselect_b32 s37, s5, s35
	s_cselect_b32 s36, s4, s34
	s_mov_b32 m0, s57
	v_lshl_add_u64 v[234:235], s[30:31], 0, v[150:151]
	ds_read_b128 v[202:205], v193
	ds_read_b128 v[206:209], v193 offset:1024
	ds_read_b128 v[210:213], v193 offset:2048
	ds_read_b128 v[214:217], v193 offset:3072
	ds_read_b128 v[218:221], v193 offset:4096
	ds_read_b128 v[222:225], v193 offset:5120
	ds_read_b128 v[226:229], v193 offset:6144
	ds_read_b128 v[230:233], v193 offset:7168
	global_load_lds_dwordx4 v[234:235], off
	v_lshl_add_u64 v[234:235], s[30:31], 0, v[152:153]
	s_mov_b32 m0, s58
	s_nop 0
	global_load_lds_dwordx4 v[234:235], off
	s_waitcnt vmcnt(8)
	s_waitcnt lgkmcnt(0)
	v_mfma_f32_16x16x32_bf16 v[126:129], v[156:159], v[202:205], v[126:129]
	v_mfma_f32_16x16x32_bf16 v[122:125], v[164:167], v[202:205], v[122:125]
	v_mfma_f32_16x16x32_bf16 v[110:113], v[156:159], v[210:213], v[110:113]
	v_mfma_f32_16x16x32_bf16 v[106:109], v[164:167], v[210:213], v[106:109]
	s_barrier
	s_setprio 1
	v_mfma_f32_16x16x32_bf16 v[94:97], v[156:159], v[218:221], v[94:97]
	v_mfma_f32_16x16x32_bf16 v[90:93], v[164:167], v[218:221], v[90:93]
	v_mfma_f32_16x16x32_bf16 v[78:81], v[156:159], v[226:229], v[78:81]
	v_mfma_f32_16x16x32_bf16 v[74:77], v[164:167], v[226:229], v[74:77]
	v_mfma_f32_16x16x32_bf16 v[126:129], v[160:163], v[206:209], v[126:129]
	v_mfma_f32_16x16x32_bf16 v[122:125], v[168:171], v[206:209], v[122:125]
	v_mfma_f32_16x16x32_bf16 v[110:113], v[160:163], v[214:217], v[110:113]
	v_mfma_f32_16x16x32_bf16 v[106:109], v[168:171], v[214:217], v[106:109]
	v_mfma_f32_16x16x32_bf16 v[94:97], v[160:163], v[222:225], v[94:97]
	v_mfma_f32_16x16x32_bf16 v[90:93], v[168:171], v[222:225], v[90:93]
	v_mfma_f32_16x16x32_bf16 v[78:81], v[160:163], v[230:233], v[78:81]
	v_mfma_f32_16x16x32_bf16 v[74:77], v[168:171], v[230:233], v[74:77]
	v_mfma_f32_16x16x32_bf16 v[118:121], v[172:175], v[202:205], v[118:121]
	v_mfma_f32_16x16x32_bf16 v[114:117], v[180:183], v[202:205], v[114:117]
	v_mfma_f32_16x16x32_bf16 v[102:105], v[172:175], v[210:213], v[102:105]
	v_mfma_f32_16x16x32_bf16 v[98:101], v[180:183], v[210:213], v[98:101]
	v_mfma_f32_16x16x32_bf16 v[86:89], v[172:175], v[218:221], v[86:89]
	v_mfma_f32_16x16x32_bf16 v[82:85], v[180:183], v[218:221], v[82:85]
	v_mfma_f32_16x16x32_bf16 v[70:73], v[172:175], v[226:229], v[70:73]
	v_mfma_f32_16x16x32_bf16 v[66:69], v[180:183], v[226:229], v[66:69]
	v_mfma_f32_16x16x32_bf16 v[118:121], v[176:179], v[206:209], v[118:121]
	v_mfma_f32_16x16x32_bf16 v[114:117], v[184:187], v[206:209], v[114:117]
	v_mfma_f32_16x16x32_bf16 v[102:105], v[176:179], v[214:217], v[102:105]
	v_mfma_f32_16x16x32_bf16 v[98:101], v[184:187], v[214:217], v[98:101]
	v_mfma_f32_16x16x32_bf16 v[86:89], v[176:179], v[222:225], v[86:89]
	v_mfma_f32_16x16x32_bf16 v[82:85], v[184:187], v[222:225], v[82:85]
	v_mfma_f32_16x16x32_bf16 v[70:73], v[176:179], v[230:233], v[70:73]
	v_mfma_f32_16x16x32_bf16 v[66:69], v[184:187], v[230:233], v[66:69]
	s_setprio 0
	s_barrier
	s_mov_b32 m0, s59
	v_lshl_add_u64 v[234:235], s[36:37], 0, v[134:135]
	s_add_u32 s40, s36, 0x160000
	ds_read_b128 v[202:205], v193 offset:16384
	ds_read_b128 v[206:209], v193 offset:17408
	ds_read_b128 v[210:213], v193 offset:18432
	ds_read_b128 v[214:217], v193 offset:19456
	ds_read_b128 v[218:221], v193 offset:20480
	ds_read_b128 v[222:225], v193 offset:21504
	ds_read_b128 v[226:229], v193 offset:22528
	ds_read_b128 v[230:233], v193 offset:23552
	global_load_lds_dwordx4 v[234:235], off
	v_lshl_add_u64 v[236:237], s[36:37], 0, v[130:131]
	s_mov_b32 m0, s60
	s_addc_u32 s41, s37, 0
	global_load_lds_dwordx4 v[236:237], off
	v_lshl_add_u64 v[238:239], s[40:41], 0, v[134:135]
	s_mov_b32 m0, s61
	v_lshl_add_u64 v[240:241], s[38:39], 0, v[132:133]
	global_load_lds_dwordx4 v[238:239], off
	v_lshl_add_u64 v[238:239], s[40:41], 0, v[130:131]
	s_mov_b32 m0, s62
	s_nop 0
	global_load_lds_dwordx4 v[238:239], off
	v_lshl_add_u64 v[238:239], s[38:39], 0, v[136:137]
	s_mov_b32 m0, s48
	s_nop 0
	global_load_lds_dwordx4 v[238:239], off
	s_mov_b32 m0, s49
	s_nop 0
	global_load_lds_dwordx4 v[240:241], off
	s_waitcnt vmcnt(8)
	s_waitcnt lgkmcnt(0)
	v_mfma_f32_16x16x32_bf16 v[62:65], v[156:159], v[202:205], v[62:65]
	v_mfma_f32_16x16x32_bf16 v[58:61], v[164:167], v[202:205], v[58:61]
	v_mfma_f32_16x16x32_bf16 v[46:49], v[156:159], v[210:213], v[46:49]
	v_mfma_f32_16x16x32_bf16 v[42:45], v[164:167], v[210:213], v[42:45]
	s_barrier
	s_setprio 1
	v_mfma_f32_16x16x32_bf16 v[30:33], v[156:159], v[218:221], v[30:33]
	v_mfma_f32_16x16x32_bf16 v[26:29], v[164:167], v[218:221], v[26:29]
	v_mfma_f32_16x16x32_bf16 v[14:17], v[156:159], v[226:229], v[14:17]
	v_mfma_f32_16x16x32_bf16 v[10:13], v[164:167], v[226:229], v[10:13]
	v_mfma_f32_16x16x32_bf16 v[62:65], v[160:163], v[206:209], v[62:65]
	v_mfma_f32_16x16x32_bf16 v[58:61], v[168:171], v[206:209], v[58:61]
	v_mfma_f32_16x16x32_bf16 v[46:49], v[160:163], v[214:217], v[46:49]
	v_mfma_f32_16x16x32_bf16 v[42:45], v[168:171], v[214:217], v[42:45]
	v_mfma_f32_16x16x32_bf16 v[30:33], v[160:163], v[222:225], v[30:33]
	v_mfma_f32_16x16x32_bf16 v[26:29], v[168:171], v[222:225], v[26:29]
	v_mfma_f32_16x16x32_bf16 v[14:17], v[160:163], v[230:233], v[14:17]
	v_mfma_f32_16x16x32_bf16 v[10:13], v[168:171], v[230:233], v[10:13]
	v_mfma_f32_16x16x32_bf16 v[54:57], v[172:175], v[202:205], v[54:57]
	v_mfma_f32_16x16x32_bf16 v[50:53], v[180:183], v[202:205], v[50:53]
	v_mfma_f32_16x16x32_bf16 v[38:41], v[172:175], v[210:213], v[38:41]
	v_mfma_f32_16x16x32_bf16 v[34:37], v[180:183], v[210:213], v[34:37]
	v_mfma_f32_16x16x32_bf16 v[22:25], v[172:175], v[218:221], v[22:25]
	v_mfma_f32_16x16x32_bf16 v[18:21], v[180:183], v[218:221], v[18:21]
	v_mfma_f32_16x16x32_bf16 v[6:9], v[172:175], v[226:229], v[6:9]
	v_mfma_f32_16x16x32_bf16 v[2:5], v[180:183], v[226:229], v[2:5]
	v_mfma_f32_16x16x32_bf16 v[54:57], v[176:179], v[206:209], v[54:57]
	v_mfma_f32_16x16x32_bf16 v[50:53], v[184:187], v[206:209], v[50:53]
	v_mfma_f32_16x16x32_bf16 v[38:41], v[176:179], v[214:217], v[38:41]
	v_mfma_f32_16x16x32_bf16 v[34:37], v[184:187], v[214:217], v[34:37]
	v_mfma_f32_16x16x32_bf16 v[22:25], v[176:179], v[222:225], v[22:25]
	v_mfma_f32_16x16x32_bf16 v[18:21], v[184:187], v[222:225], v[18:21]
	v_mfma_f32_16x16x32_bf16 v[6:9], v[176:179], v[230:233], v[6:9]
	v_mfma_f32_16x16x32_bf16 v[2:5], v[184:187], v[230:233], v[2:5]
	s_setprio 0
	s_barrier
	ds_read_b128 v[156:159], v197
	ds_read_b128 v[160:163], v197 offset:1024
	ds_read_b128 v[164:167], v197 offset:2048
	ds_read_b128 v[168:171], v197 offset:3072
	ds_read_b128 v[172:175], v198
	ds_read_b128 v[176:179], v198 offset:1024
	ds_read_b128 v[180:183], v198 offset:2048
	ds_read_b128 v[184:187], v198 offset:3072
	s_add_u32 s38, s38, 0x160000
	s_addc_u32 s39, s39, 0
	s_mov_b32 m0, s50
	v_lshl_add_u64 v[242:243], s[38:39], 0, v[136:137]
	ds_read_b128 v[202:205], v193 offset:32768
	ds_read_b128 v[206:209], v193 offset:33792
	ds_read_b128 v[210:213], v193 offset:34816
	ds_read_b128 v[214:217], v193 offset:35840
	ds_read_b128 v[218:221], v193 offset:36864
	ds_read_b128 v[222:225], v193 offset:37888
	ds_read_b128 v[226:229], v193 offset:38912
	ds_read_b128 v[230:233], v193 offset:39936
	global_load_lds_dwordx4 v[242:243], off
	v_lshl_add_u64 v[242:243], s[38:39], 0, v[132:133]
	s_mov_b32 m0, s51
	s_nop 0
	global_load_lds_dwordx4 v[242:243], off
	s_waitcnt vmcnt(8)
	s_waitcnt lgkmcnt(0)
	v_mfma_f32_16x16x32_bf16 v[126:129], v[156:159], v[202:205], v[126:129]
	v_mfma_f32_16x16x32_bf16 v[122:125], v[164:167], v[202:205], v[122:125]
	v_mfma_f32_16x16x32_bf16 v[110:113], v[156:159], v[210:213], v[110:113]
	v_mfma_f32_16x16x32_bf16 v[106:109], v[164:167], v[210:213], v[106:109]
	s_barrier
	s_setprio 1
	v_mfma_f32_16x16x32_bf16 v[94:97], v[156:159], v[218:221], v[94:97]
	v_mfma_f32_16x16x32_bf16 v[90:93], v[164:167], v[218:221], v[90:93]
	v_mfma_f32_16x16x32_bf16 v[78:81], v[156:159], v[226:229], v[78:81]
	v_mfma_f32_16x16x32_bf16 v[74:77], v[164:167], v[226:229], v[74:77]
	v_mfma_f32_16x16x32_bf16 v[126:129], v[160:163], v[206:209], v[126:129]
	v_mfma_f32_16x16x32_bf16 v[122:125], v[168:171], v[206:209], v[122:125]
	v_mfma_f32_16x16x32_bf16 v[110:113], v[160:163], v[214:217], v[110:113]
	v_mfma_f32_16x16x32_bf16 v[106:109], v[168:171], v[214:217], v[106:109]
	v_mfma_f32_16x16x32_bf16 v[94:97], v[160:163], v[222:225], v[94:97]
	v_mfma_f32_16x16x32_bf16 v[90:93], v[168:171], v[222:225], v[90:93]
	v_mfma_f32_16x16x32_bf16 v[78:81], v[160:163], v[230:233], v[78:81]
	v_mfma_f32_16x16x32_bf16 v[74:77], v[168:171], v[230:233], v[74:77]
	v_mfma_f32_16x16x32_bf16 v[118:121], v[172:175], v[202:205], v[118:121]
	v_mfma_f32_16x16x32_bf16 v[114:117], v[180:183], v[202:205], v[114:117]
	v_mfma_f32_16x16x32_bf16 v[102:105], v[172:175], v[210:213], v[102:105]
	v_mfma_f32_16x16x32_bf16 v[98:101], v[180:183], v[210:213], v[98:101]
	v_mfma_f32_16x16x32_bf16 v[86:89], v[172:175], v[218:221], v[86:89]
	v_mfma_f32_16x16x32_bf16 v[82:85], v[180:183], v[218:221], v[82:85]
	v_mfma_f32_16x16x32_bf16 v[70:73], v[172:175], v[226:229], v[70:73]
	v_mfma_f32_16x16x32_bf16 v[66:69], v[180:183], v[226:229], v[66:69]
	v_mfma_f32_16x16x32_bf16 v[118:121], v[176:179], v[206:209], v[118:121]
	v_mfma_f32_16x16x32_bf16 v[114:117], v[184:187], v[206:209], v[114:117]
	v_mfma_f32_16x16x32_bf16 v[102:105], v[176:179], v[214:217], v[102:105]
	v_mfma_f32_16x16x32_bf16 v[98:101], v[184:187], v[214:217], v[98:101]
	v_mfma_f32_16x16x32_bf16 v[86:89], v[176:179], v[222:225], v[86:89]
	v_mfma_f32_16x16x32_bf16 v[82:85], v[184:187], v[222:225], v[82:85]
	v_mfma_f32_16x16x32_bf16 v[70:73], v[176:179], v[230:233], v[70:73]
	v_mfma_f32_16x16x32_bf16 v[66:69], v[184:187], v[230:233], v[66:69]
	s_setprio 0
	s_barrier
	s_mov_b32 m0, s64
	v_lshl_add_u64 v[234:235], v[234:235], 0, s[12:13]
	s_add_u32 s36, s36, 0x160080
	ds_read_b128 v[202:205], v193 offset:49152
	ds_read_b128 v[206:209], v193 offset:50176
	ds_read_b128 v[210:213], v193 offset:51200
	ds_read_b128 v[214:217], v193 offset:52224
	ds_read_b128 v[218:221], v193 offset:53248
	ds_read_b128 v[222:225], v193 offset:54272
	ds_read_b128 v[226:229], v193 offset:55296
	ds_read_b128 v[230:233], v193 offset:56320
	global_load_lds_dwordx4 v[234:235], off
	v_lshl_add_u64 v[234:235], v[236:237], 0, s[12:13]
	s_mov_b32 m0, s65
	s_addc_u32 s37, s37, 0
	s_add_i32 s38, s63, s47
	global_load_lds_dwordx4 v[234:235], off
	v_lshl_add_u64 v[234:235], s[36:37], 0, v[134:135]
	s_mov_b32 m0, s38
	s_nop 0
	global_load_lds_dwordx4 v[234:235], off
	v_lshl_add_u64 v[234:235], s[36:37], 0, v[130:131]
	s_add_i32 m0, s38, 0x2000
	s_nop 0
	global_load_lds_dwordx4 v[234:235], off
	v_lshl_add_u64 v[234:235], v[238:239], 0, s[12:13]
	s_mov_b32 m0, s55
	s_nop 0
	global_load_lds_dwordx4 v[234:235], off
	v_lshl_add_u64 v[234:235], v[240:241], 0, s[12:13]
	s_mov_b32 m0, s56
	s_nop 0
	global_load_lds_dwordx4 v[234:235], off
	s_waitcnt vmcnt(8)
	s_waitcnt lgkmcnt(0)
	v_mfma_f32_16x16x32_bf16 v[62:65], v[156:159], v[202:205], v[62:65]
	v_mfma_f32_16x16x32_bf16 v[58:61], v[164:167], v[202:205], v[58:61]
	v_mfma_f32_16x16x32_bf16 v[46:49], v[156:159], v[210:213], v[46:49]
	v_mfma_f32_16x16x32_bf16 v[42:45], v[164:167], v[210:213], v[42:45]
	s_barrier
	s_setprio 1
	v_mfma_f32_16x16x32_bf16 v[30:33], v[156:159], v[218:221], v[30:33]
	v_mfma_f32_16x16x32_bf16 v[26:29], v[164:167], v[218:221], v[26:29]
	v_mfma_f32_16x16x32_bf16 v[14:17], v[156:159], v[226:229], v[14:17]
	v_mfma_f32_16x16x32_bf16 v[10:13], v[164:167], v[226:229], v[10:13]
	v_mfma_f32_16x16x32_bf16 v[62:65], v[160:163], v[206:209], v[62:65]
	v_mfma_f32_16x16x32_bf16 v[58:61], v[168:171], v[206:209], v[58:61]
	v_mfma_f32_16x16x32_bf16 v[46:49], v[160:163], v[214:217], v[46:49]
	v_mfma_f32_16x16x32_bf16 v[42:45], v[168:171], v[214:217], v[42:45]
	v_mfma_f32_16x16x32_bf16 v[30:33], v[160:163], v[222:225], v[30:33]
	v_mfma_f32_16x16x32_bf16 v[26:29], v[168:171], v[222:225], v[26:29]
	v_mfma_f32_16x16x32_bf16 v[14:17], v[160:163], v[230:233], v[14:17]
	v_mfma_f32_16x16x32_bf16 v[10:13], v[168:171], v[230:233], v[10:13]
	v_mfma_f32_16x16x32_bf16 v[54:57], v[172:175], v[202:205], v[54:57]
	v_mfma_f32_16x16x32_bf16 v[50:53], v[180:183], v[202:205], v[50:53]
	v_mfma_f32_16x16x32_bf16 v[38:41], v[172:175], v[210:213], v[38:41]
	v_mfma_f32_16x16x32_bf16 v[34:37], v[180:183], v[210:213], v[34:37]
	v_mfma_f32_16x16x32_bf16 v[22:25], v[172:175], v[218:221], v[22:25]
	v_mfma_f32_16x16x32_bf16 v[18:21], v[180:183], v[218:221], v[18:21]
	v_mfma_f32_16x16x32_bf16 v[6:9], v[172:175], v[226:229], v[6:9]
	v_mfma_f32_16x16x32_bf16 v[2:5], v[180:183], v[226:229], v[2:5]
	v_mfma_f32_16x16x32_bf16 v[54:57], v[176:179], v[206:209], v[54:57]
	v_mfma_f32_16x16x32_bf16 v[50:53], v[184:187], v[206:209], v[50:53]
	v_mfma_f32_16x16x32_bf16 v[38:41], v[176:179], v[214:217], v[38:41]
	v_mfma_f32_16x16x32_bf16 v[34:37], v[184:187], v[214:217], v[34:37]
	v_mfma_f32_16x16x32_bf16 v[22:25], v[176:179], v[222:225], v[22:25]
	v_mfma_f32_16x16x32_bf16 v[18:21], v[184:187], v[222:225], v[18:21]
	v_mfma_f32_16x16x32_bf16 v[6:9], v[176:179], v[230:233], v[6:9]
	v_mfma_f32_16x16x32_bf16 v[2:5], v[184:187], v[230:233], v[2:5]
	s_setprio 0
	s_barrier
	s_add_i32 s29, s29, 2
	s_add_u32 s30, s30, 0x100
	s_addc_u32 s31, s31, 0
	s_add_u32 s34, s34, 0x100
	s_addc_u32 s35, s35, 0
	s_cmpk_gt_u32 s29, 0x55
	s_cbranch_scc0 .LBB0_1675
	s_and_b64 vcc, exec, s[14:15]
	s_cbranch_vccz .LBB0_1678
	s_barrier
